# v30 + radix-16 butterflies with the multiplications folded into the first adds (s100 = 2.0) + attention row-max without the self-max pairs
# speedup vs baseline: 1.0165x; 1.0016x over previous
; __device__ __forceinline__ unsigned cvt_pk_bf16(float lo, float hi) { unsigned r; asm volatile("v_cvt_pk_bf16_f32 %0, %1, %2" : "=v"(r) : "v"(lo), "v"(hi)); return r; }
; __device__ __forceinline__ float lane_read(float v, int src_lane) { return __builtin_bit_cast(float, __builtin_amdgcn_ds_bpermute(src_lane << 2, __builtin_bit_cast(int, v))); }
; #define MFMA16(a, b, c) __builtin_amdgcn_mfma_f32_16x16x32_bf16((a), (b), (c), 0, 0, 0)
; __device__ __forceinline__ void attn_compute(const AttnK& C, const AttnV& V, const bf16x8 (&qf)[4], f32x4 (&o)[8], float& mrun, float& lsum, int lane, int g,
;                                              bool masked, int keycol0, int cs, const LAS float* brow  , int cq) {
;     ...
;     float cm = fmaxf(fmaxf(fmaxf(s[0][0], s[0][1]), fmaxf(s[0][2], s[0][3])), fmaxf(fmaxf(s[1][0], s[1][1]), fmaxf(s[1][2], s[1][3])));
;     cm = fmaxf(cm, lane_read(cm, lane ^ 16)); cm = fmaxf(cm, lane_read(cm, lane ^ 32));
;     const float mnew = fmaxf(mrun, cm), alpha = __builtin_amdgcn_exp2f(mrun - mnew);
;     mrun = mnew;
;     float p[8]; float ps = 0.f;
; #pragma unroll
;     for (int T = 0; T < 2; ++T)
; #pragma unroll
;         for (int i = 0; i < 4; ++i) { p[4 * T + i] = __builtin_amdgcn_exp2f(s[T][i] - mnew); ps += p[4 * T + i]; }
;     lsum = lsum * alpha + ps;
;     v4u pw; pw.x = pg8::cvt_pk_bf16(p[0], p[1]); pw.y = pg8::cvt_pk_bf16(p[2], p[3]); pw.z = pg8::cvt_pk_bf16(p[4], p[5]); pw.w = pg8::cvt_pk_bf16(p[6], p[7]);
;     const bf16x8 pf = __builtin_bit_cast(bf16x8, pw);
; #pragma unroll
;     for (int dt = 0; dt < 8; ++dt) { o[dt] = o[dt] * alpha; o[dt] = MFMA16(V.vf[dt], pf, o[dt]); }
.LBB0_589:
	s_or_b64 exec, exec, s[38:39]
	v_max_f32_e32 v130, v137, v136
	v_max_f32_e32 v131, v138, v132
	v_max_f32_e32 v135, v129, v128
	v_max3_f32 v135, v134, v133, v135
	v_max3_f32 v130, v130, v131, v135
	ds_bpermute_b32 v131, v171, v130
	s_waitcnt lgkmcnt(0)
	v_max_f32_e32 v131, v131, v131
	v_max_f32_e32 v130, v130, v131
	ds_bpermute_b32 v131, v185, v130
	s_waitcnt lgkmcnt(0)
	v_max3_f32 v135, v247, v130, v131
	v_sub_f32_e32 v131, v137, v135
	v_exp_f32_e32 v131, v131
	v_sub_f32_e32 v136, v136, v135
	v_exp_f32_e32 v136, v136
	v_sub_f32_e32 v138, v138, v135
	v_exp_f32_e32 v138, v138
	v_sub_f32_e32 v132, v132, v135
	v_exp_f32_e32 v139, v132
	v_add_f32_e32 v137, 0, v131
	v_sub_f32_e32 v134, v134, v135
	v_add_f32_e32 v137, v136, v137
	v_exp_f32_e32 v134, v134
	v_sub_f32_e32 v133, v133, v135
	v_add_f32_e32 v137, v138, v137
	v_exp_f32_e32 v133, v133
	v_sub_f32_e32 v129, v129, v135
	v_add_f32_e32 v132, v139, v137
	v_exp_f32_e32 v137, v129
	v_add_f32_e32 v132, v134, v132
	v_sub_f32_e32 v130, v247, v135
	v_add_f32_e32 v132, v133, v132
	v_add_f32_e32 v129, v137, v132
	v_sub_f32_e32 v128, v128, v135
	v_exp_f32_e32 v132, v130
	v_exp_f32_e32 v140, v128
	v_cvt_pk_bf16_f32 v128, v131, v136
	v_mov_b32_e32 v247, v135
	v_pk_mul_f32 v[46:47], v[46:47], v[132:133] op_sel_hi:[1,0]
	v_pk_mul_f32 v[44:45], v[44:45], v[132:133] op_sel_hi:[1,0]
	v_pk_mul_f32 v[54:55], v[54:55], v[132:133] op_sel_hi:[1,0]
	v_pk_mul_f32 v[52:53], v[52:53], v[132:133] op_sel_hi:[1,0]
	v_pk_mul_f32 v[42:43], v[42:43], v[132:133] op_sel_hi:[1,0]
	v_pk_mul_f32 v[40:41], v[40:41], v[132:133] op_sel_hi:[1,0]
	v_pk_mul_f32 v[34:35], v[34:35], v[132:133] op_sel_hi:[1,0]
	v_pk_mul_f32 v[32:33], v[32:33], v[132:133] op_sel_hi:[1,0]
	v_pk_mul_f32 v[26:27], v[26:27], v[132:133] op_sel_hi:[1,0]
	v_pk_mul_f32 v[24:25], v[24:25], v[132:133] op_sel_hi:[1,0]
	v_pk_mul_f32 v[18:19], v[18:19], v[132:133] op_sel_hi:[1,0]
	v_pk_mul_f32 v[16:17], v[16:17], v[132:133] op_sel_hi:[1,0]
	v_pk_mul_f32 v[10:11], v[10:11], v[132:133] op_sel_hi:[1,0]
	v_pk_mul_f32 v[8:9], v[8:9], v[132:133] op_sel_hi:[1,0]
	v_pk_mul_f32 v[2:3], v[2:3], v[132:133] op_sel_hi:[1,0]
	v_pk_mul_f32 v[0:1], v[0:1], v[132:133] op_sel_hi:[1,0]
	v_add_f32_e32 v141, v140, v129
	v_cvt_pk_bf16_f32 v129, v138, v139
	v_cvt_pk_bf16_f32 v130, v134, v133
	v_cvt_pk_bf16_f32 v131, v137, v140
	v_fmac_f32_e32 v141, v207, v132
	v_mfma_f32_16x16x32_bf16 v[44:47], v[124:127], v[128:131], v[44:47]
	v_mov_b32_e32 v207, v141
	v_mfma_f32_16x16x32_bf16 v[52:55], v[116:119], v[128:131], v[52:55]
	v_mfma_f32_16x16x32_bf16 v[40:43], v[120:123], v[128:131], v[40:43]
	v_mfma_f32_16x16x32_bf16 v[32:35], v[108:111], v[128:131], v[32:35]
	v_mfma_f32_16x16x32_bf16 v[24:27], v[112:115], v[128:131], v[24:27]
	v_mfma_f32_16x16x32_bf16 v[16:19], v[104:107], v[128:131], v[16:19]
	v_mfma_f32_16x16x32_bf16 v[8:11], v[100:103], v[128:131], v[8:11]
	v_mfma_f32_16x16x32_bf16 v[0:3], v[96:99], v[128:131], v[0:3]

; __device__ __forceinline__ unsigned cvt_pk_bf16(float lo, float hi) { unsigned r; asm volatile("v_cvt_pk_bf16_f32 %0, %1, %2" : "=v"(r) : "v"(lo), "v"(hi)); return r; }
; __device__ __forceinline__ float lane_read(float v, int src_lane) { return __builtin_bit_cast(float, __builtin_amdgcn_ds_bpermute(src_lane << 2, __builtin_bit_cast(int, v))); }
; #define MFMA16(a, b, c) __builtin_amdgcn_mfma_f32_16x16x32_bf16((a), (b), (c), 0, 0, 0)
; __device__ __forceinline__ void attn_compute(const AttnK& C, const AttnV& V, const bf16x8 (&qf)[4], f32x4 (&o)[8], float& mrun, float& lsum, int lane, int g,
;                                              bool masked, int keycol0, int cs, const LAS float* brow  , int cq) {
;     ...
;     float cm = fmaxf(fmaxf(fmaxf(s[0][0], s[0][1]), fmaxf(s[0][2], s[0][3])), fmaxf(fmaxf(s[1][0], s[1][1]), fmaxf(s[1][2], s[1][3])));
;     cm = fmaxf(cm, lane_read(cm, lane ^ 16)); cm = fmaxf(cm, lane_read(cm, lane ^ 32));
;     const float mnew = fmaxf(mrun, cm), alpha = __builtin_amdgcn_exp2f(mrun - mnew);
;     mrun = mnew;
;     float p[8]; float ps = 0.f;
; #pragma unroll
;     for (int T = 0; T < 2; ++T)
; #pragma unroll
;         for (int i = 0; i < 4; ++i) { p[4 * T + i] = __builtin_amdgcn_exp2f(s[T][i] - mnew); ps += p[4 * T + i]; }
;     lsum = lsum * alpha + ps;
;     v4u pw; pw.x = pg8::cvt_pk_bf16(p[0], p[1]); pw.y = pg8::cvt_pk_bf16(p[2], p[3]); pw.z = pg8::cvt_pk_bf16(p[4], p[5]); pw.w = pg8::cvt_pk_bf16(p[6], p[7]);
;     const bf16x8 pf = __builtin_bit_cast(bf16x8, pw);
; #pragma unroll
;     for (int dt = 0; dt < 8; ++dt) { o[dt] = o[dt] * alpha; o[dt] = MFMA16(V.vf[dt], pf, o[dt]); }
.LBB0_608:
	s_or_b64 exec, exec, s[38:39]
	v_max_f32_e32 v162, v179, v178
	v_max_f32_e32 v163, v218, v164
	v_max_f32_e32 v167, v161, v160
	v_max3_f32 v167, v166, v165, v167
	v_max3_f32 v162, v162, v163, v167
	ds_bpermute_b32 v163, v171, v162
	s_waitcnt lgkmcnt(0)
	v_max_f32_e32 v163, v163, v163
	v_max_f32_e32 v162, v162, v163
	ds_bpermute_b32 v163, v185, v162
	s_waitcnt lgkmcnt(0)
	v_max3_f32 v167, v248, v162, v163
	v_sub_f32_e32 v163, v179, v167
	v_exp_f32_e32 v163, v163
	v_sub_f32_e32 v178, v178, v167
	v_exp_f32_e32 v178, v178
	v_sub_f32_e32 v218, v218, v167
	v_exp_f32_e32 v218, v218
	v_sub_f32_e32 v164, v164, v167
	v_exp_f32_e32 v219, v164
	v_add_f32_e32 v179, 0, v163
	v_sub_f32_e32 v166, v166, v167
	v_add_f32_e32 v179, v178, v179
	v_exp_f32_e32 v166, v166
	v_sub_f32_e32 v165, v165, v167
	v_add_f32_e32 v179, v218, v179
	v_exp_f32_e32 v165, v165
	v_sub_f32_e32 v161, v161, v167
	v_add_f32_e32 v164, v219, v179
	v_exp_f32_e32 v179, v161
	v_add_f32_e32 v164, v166, v164
	v_sub_f32_e32 v162, v248, v167
	v_add_f32_e32 v164, v165, v164
	v_add_f32_e32 v161, v179, v164
	v_sub_f32_e32 v160, v160, v167
	v_exp_f32_e32 v164, v162
	v_exp_f32_e32 v222, v160
	v_cvt_pk_bf16_f32 v160, v163, v178
	v_mov_b32_e32 v248, v167
	v_pk_mul_f32 v[66:67], v[66:67], v[164:165] op_sel_hi:[1,0]
	v_pk_mul_f32 v[64:65], v[64:65], v[164:165] op_sel_hi:[1,0]
	v_pk_mul_f32 v[58:59], v[58:59], v[164:165] op_sel_hi:[1,0]
	v_pk_mul_f32 v[56:57], v[56:57], v[164:165] op_sel_hi:[1,0]
	v_pk_mul_f32 v[50:51], v[50:51], v[164:165] op_sel_hi:[1,0]
	v_pk_mul_f32 v[48:49], v[48:49], v[164:165] op_sel_hi:[1,0]
	v_pk_mul_f32 v[38:39], v[38:39], v[164:165] op_sel_hi:[1,0]
	v_pk_mul_f32 v[36:37], v[36:37], v[164:165] op_sel_hi:[1,0]
	v_pk_mul_f32 v[30:31], v[30:31], v[164:165] op_sel_hi:[1,0]
	v_pk_mul_f32 v[28:29], v[28:29], v[164:165] op_sel_hi:[1,0]
	v_pk_mul_f32 v[22:23], v[22:23], v[164:165] op_sel_hi:[1,0]
	v_pk_mul_f32 v[20:21], v[20:21], v[164:165] op_sel_hi:[1,0]
	v_pk_mul_f32 v[14:15], v[14:15], v[164:165] op_sel_hi:[1,0]
	v_pk_mul_f32 v[12:13], v[12:13], v[164:165] op_sel_hi:[1,0]
	v_pk_mul_f32 v[6:7], v[6:7], v[164:165] op_sel_hi:[1,0]
	v_pk_mul_f32 v[4:5], v[4:5], v[164:165] op_sel_hi:[1,0]
	v_add_f32_e32 v223, v222, v161
	v_cvt_pk_bf16_f32 v161, v218, v219
	v_cvt_pk_bf16_f32 v162, v166, v165
	v_cvt_pk_bf16_f32 v163, v179, v222
	v_fmac_f32_e32 v223, v206, v164
	v_mfma_f32_16x16x32_bf16 v[64:67], v[124:127], v[160:163], v[64:67]
	v_mov_b32_e32 v206, v223
	v_mfma_f32_16x16x32_bf16 v[56:59], v[116:119], v[160:163], v[56:59]
	v_mfma_f32_16x16x32_bf16 v[48:51], v[120:123], v[160:163], v[48:51]
	v_mfma_f32_16x16x32_bf16 v[36:39], v[108:111], v[160:163], v[36:39]
	v_mfma_f32_16x16x32_bf16 v[28:31], v[112:115], v[160:163], v[28:31]
	v_mfma_f32_16x16x32_bf16 v[20:23], v[104:107], v[160:163], v[20:23]
	v_mfma_f32_16x16x32_bf16 v[12:15], v[100:103], v[160:163], v[12:15]
	v_mfma_f32_16x16x32_bf16 v[4:7], v[96:99], v[160:163], v[4:7]

; #define LAS __attribute__((address_space(3)))
; __device__ __forceinline__ void attn_compute(const AttnK& C, const AttnV& V, const bf16x8 (&qf)[4], f32x4 (&o)[8], float& mrun, float& lsum, int lane, int g,
;                                              bool masked, int keycol0, int cs, const LAS float* brow  , int cq) {
;     f32x4 s[2];
; #pragma unroll
;     for (int T = 0; T < 2; ++T) { s[T] = (f32x4){0.f, 0.f, 0.f, 0.f};
; #pragma unroll
;         for (int dc = 0; dc < 4; ++dc) s[T] = MFMA16(C.kf[T][dc], qf[dc], s[T]); }
;     if (masked) {
; #pragma unroll
;         for (int T = 0; T < 2; ++T)
; #pragma unroll
;             for (int i = 0; i < 4; ++i) { const int keycol = keycol0 + 8 * g + 4 * T + i; const bool ok = keycol >= cs && keycol < cs + 16;
;                 const int dcol = keycol - cq + 15; const float bv = brow[ok ? dcol : 0];
;                 s[T][i] = ok ? s[T][i] + bv : -1e30f; }
;     }
;     float cm = fmaxf(fmaxf(fmaxf(s[0][0], s[0][1]), fmaxf(s[0][2], s[0][3])), fmaxf(fmaxf(s[1][0], s[1][1]), fmaxf(s[1][2], s[1][3])));
;     cm = fmaxf(cm, lane_read(cm, lane ^ 16)); cm = fmaxf(cm, lane_read(cm, lane ^ 32));
;     const float mnew = fmaxf(mrun, cm), alpha = __builtin_amdgcn_exp2f(mrun - mnew);
;     mrun = mnew;
;     float p[8]; float ps = 0.f;
; #pragma unroll
;     for (int T = 0; T < 2; ++T)
; #pragma unroll
;         for (int i = 0; i < 4; ++i) { p[4 * T + i] = __builtin_amdgcn_exp2f(s[T][i] - mnew); ps += p[4 * T + i]; }
;     lsum = lsum * alpha + ps;
;     v4u pw; pw.x = pg8::cvt_pk_bf16(p[0], p[1]); pw.y = pg8::cvt_pk_bf16(p[2], p[3]); pw.z = pg8::cvt_pk_bf16(p[4], p[5]); pw.w = pg8::cvt_pk_bf16(p[6], p[7]);
;     const bf16x8 pf = __builtin_bit_cast(bf16x8, pw);
; #pragma unroll
;     for (int dt = 0; dt < 8; ++dt) { o[dt] = o[dt] * alpha; o[dt] = MFMA16(V.vf[dt], pf, o[dt]); }
; __device__ __forceinline__ void attn_tile(Frame& F, bool is_lat, int b, int h, int r, int c0, int qrow0, const LAS float* bias_h) {
;     ...
;     for (int c = cbeg; c < 16; c += 2) {
;         ATT_LOADV(VV, c); ATT_LOADK(KB, c + 1); __builtin_amdgcn_sched_barrier(0);
;         ATT_COMP(KA, VV, c); __builtin_amdgcn_sched_barrier(0);
;         ATT_LOADV(VV, c + 1); if (c + 2 < 16) ATT_LOADK(KA, c + 2);
;         __builtin_amdgcn_sched_barrier(0);
;         ATT_COMP(KB, VV, c + 1); __builtin_amdgcn_sched_barrier(0);
.LBB0_633:
	v_add_u32_e32 v164, v147, v170
	v_add_u32_e32 v80, 0x11000, v164
	v_add_u32_e32 v81, 0x13100, v164
	ds_read_b128 v[112:115], v80
	ds_read_b128 v[116:119], v81
	v_add_u32_e32 v80, 0x15200, v164
	v_add_u32_e32 v81, 0x17300, v164
	ds_read_b128 v[120:123], v80
	ds_read_b128 v[124:127], v81
	v_add_u32_e32 v80, 0x19400, v164
	v_add_u32_e32 v81, 0x1b500, v164
	ds_read_b128 v[128:131], v80
	ds_read_b128 v[132:135], v81
	v_add_u32_e32 v80, 0x1d600, v164
	v_add_u32_e32 v81, 0x1f700, v164
	v_add_u32_e32 v151, v148, v170
	ds_read_b128 v[136:139], v80
	ds_read_b128 v[140:143], v81
	ds_read_b128 v[88:91], v151
	ds_read_b128 v[92:95], v151 offset:64
	ds_read_b128 v[96:99], v151 offset:128
	ds_read_b128 v[100:103], v151 offset:192
	ds_read_b128 v[104:107], v151 offset:1088
	ds_read_b128 v[108:111], v151 offset:1152
	ds_read_b128 v[84:87], v151 offset:1216
	ds_read_b128 v[80:83], v151 offset:1280
	s_waitcnt vmcnt(3) lgkmcnt(14)
	v_mfma_f32_16x16x32_bf16 v[152:155], v[16:19], v[0:3], 0
	v_mfma_f32_16x16x32_bf16 v[156:159], v[32:35], v[0:3], 0
	s_waitcnt vmcnt(2)
	v_mfma_f32_16x16x32_bf16 v[152:155], v[20:23], v[4:7], v[152:155]
	v_mfma_f32_16x16x32_bf16 v[156:159], v[36:39], v[4:7], v[156:159]
	s_waitcnt vmcnt(1)
	v_mfma_f32_16x16x32_bf16 v[152:155], v[24:27], v[8:11], v[152:155]
	v_mfma_f32_16x16x32_bf16 v[156:159], v[40:43], v[8:11], v[156:159]
	s_waitcnt vmcnt(0)
	v_mfma_f32_16x16x32_bf16 v[152:155], v[28:31], v[12:15], v[152:155]
	v_mfma_f32_16x16x32_bf16 v[156:159], v[44:47], v[12:15], v[156:159]
	s_nop 6
	v_max_f32_e32 v150, v152, v153
	v_max_f32_e32 v160, v154, v155
	v_max_f32_e32 v161, v158, v159
	v_max3_f32 v161, v156, v157, v161
	v_max3_f32 v150, v150, v160, v161
	ds_bpermute_b32 v160, v171, v150
	s_waitcnt lgkmcnt(0)
	v_max_f32_e32 v160, v160, v160
	v_max_f32_e32 v150, v150, v160
	ds_bpermute_b32 v160, v185, v150
	s_waitcnt lgkmcnt(0)
	v_max3_f32 v150, v146, v150, v160
	v_sub_f32_e32 v146, v146, v150
	v_exp_f32_e32 v146, v146
	v_sub_f32_e32 v152, v152, v150
	v_sub_f32_e32 v153, v153, v150
	v_sub_f32_e32 v154, v154, v150
	v_sub_f32_e32 v155, v155, v150
	v_sub_f32_e32 v156, v156, v150
	v_sub_f32_e32 v157, v157, v150
	v_sub_f32_e32 v158, v158, v150
	v_sub_f32_e32 v159, v159, v150
	v_pk_mul_f32 v[78:79], v[78:79], v[146:147] op_sel_hi:[1,0]
	v_pk_mul_f32 v[76:77], v[76:77], v[146:147] op_sel_hi:[1,0]
	v_pk_mul_f32 v[74:75], v[74:75], v[146:147] op_sel_hi:[1,0]
	v_pk_mul_f32 v[72:73], v[72:73], v[146:147] op_sel_hi:[1,0]
	v_pk_mul_f32 v[70:71], v[70:71], v[146:147] op_sel_hi:[1,0]
	v_pk_mul_f32 v[68:69], v[68:69], v[146:147] op_sel_hi:[1,0]
	v_pk_mul_f32 v[66:67], v[66:67], v[146:147] op_sel_hi:[1,0]
	v_pk_mul_f32 v[64:65], v[64:65], v[146:147] op_sel_hi:[1,0]
	v_pk_mul_f32 v[62:63], v[62:63], v[146:147] op_sel_hi:[1,0]
	v_pk_mul_f32 v[60:61], v[60:61], v[146:147] op_sel_hi:[1,0]
	v_pk_mul_f32 v[58:59], v[58:59], v[146:147] op_sel_hi:[1,0]
	v_pk_mul_f32 v[56:57], v[56:57], v[146:147] op_sel_hi:[1,0]
	v_pk_mul_f32 v[54:55], v[54:55], v[146:147] op_sel_hi:[1,0]
	v_pk_mul_f32 v[52:53], v[52:53], v[146:147] op_sel_hi:[1,0]
	v_pk_mul_f32 v[50:51], v[50:51], v[146:147] op_sel_hi:[1,0]
	v_pk_mul_f32 v[48:49], v[48:49], v[146:147] op_sel_hi:[1,0]
	v_exp_f32_e32 v152, v152
	v_exp_f32_e32 v153, v153
	v_exp_f32_e32 v154, v154
	v_exp_f32_e32 v155, v155
	v_exp_f32_e32 v156, v156
	v_exp_f32_e32 v157, v157
	v_exp_f32_e32 v158, v158
	v_exp_f32_e32 v159, v159
	v_cvt_pk_bf16_f32 v160, v152, v153
	v_cvt_pk_bf16_f32 v161, v154, v155
	v_cvt_pk_bf16_f32 v162, v156, v157
	v_cvt_pk_bf16_f32 v163, v158, v159
	s_nop 0
	v_mfma_f32_16x16x32_bf16 v[76:79], v[112:115], v[160:163], v[76:79]
	v_mfma_f32_16x16x32_bf16 v[72:75], v[116:119], v[160:163], v[72:75]
	v_mfma_f32_16x16x32_bf16 v[68:71], v[120:123], v[160:163], v[68:71]
	v_mfma_f32_16x16x32_bf16 v[64:67], v[124:127], v[160:163], v[64:67]
	v_mfma_f32_16x16x32_bf16 v[60:63], v[128:131], v[160:163], v[60:63]
	v_mfma_f32_16x16x32_bf16 v[56:59], v[132:135], v[160:163], v[56:59]
	v_mfma_f32_16x16x32_bf16 v[52:55], v[136:139], v[160:163], v[52:55]
	v_mfma_f32_16x16x32_bf16 v[48:51], v[140:143], v[160:163], v[48:51]
	v_add_u32_e32 v112, 0x11040, v164
	v_add_u32_e32 v113, 0x13140, v164
	ds_read_b128 v[140:143], v112
	ds_read_b128 v[136:139], v113
	v_add_u32_e32 v112, 0x15240, v164
	v_add_u32_e32 v113, 0x17340, v164
	ds_read_b128 v[132:135], v112
	ds_read_b128 v[128:131], v113
	v_add_u32_e32 v112, 0x19440, v164
	v_add_u32_e32 v113, 0x1b540, v164
	ds_read_b128 v[124:127], v112
	ds_read_b128 v[120:123], v113
	v_add_u32_e32 v112, 0x1d640, v164
	v_add_u32_e32 v113, 0x1f740, v164
	ds_read_b128 v[116:119], v112
	ds_read_b128 v[112:115], v113
	s_cmp_gt_u32 s50, 13
	s_cselect_b64 s[38:39], -1, 0
	s_and_b64 vcc, exec, s[38:39]
	s_cbranch_vccnz .LBB0_632
	ds_read_b128 v[16:19], v151 offset:8704
	ds_read_b128 v[20:23], v151 offset:8768
	ds_read_b128 v[24:27], v151 offset:8832
	ds_read_b128 v[28:31], v151 offset:8896
	ds_read_b128 v[32:35], v151 offset:9792
	ds_read_b128 v[36:39], v151 offset:9856
	ds_read_b128 v[40:43], v151 offset:9920
	ds_read_b128 v[44:47], v151 offset:9984
	s_branch .LBB0_632

; #define LAS __attribute__((address_space(3)))
; __device__ __forceinline__ f32x2 cmul(f32x2 a, f32x2 b) { return (f32x2){a.x * b.x - a.y * b.y, a.x * b.y + a.y * b.x}; }
; template <bool INV> __device__ __forceinline__ void dft16(f32x2 (&x)[16]) {
; #pragma unroll
;     for (int b = 0; b < 4; ++b) r4<INV>(x[b], x[4 + b], x[8 + b], x[12 + b]);
;     const float sg = INV ? -1.f : 1.f;
;     const f32x2 W1 = {0.92387953251f, -0.38268343236f * sg}, W2 = {0.70710678118f, -0.70710678118f * sg}, W3 = {0.38268343236f, -0.92387953251f * sg},
;                 W4 = {0.f, -1.f * sg}, W6 = {-0.70710678118f, -0.70710678118f * sg}, W9 = {-0.92387953251f, 0.38268343236f * sg};
;     x[5] = cmul(x[5], W1); x[9] = cmul(x[9], W2); x[13] = cmul(x[13], W3);
;     x[6] = cmul(x[6], W2); x[10] = cmul(x[10], W4); x[14] = cmul(x[14], W6);
;     x[7] = cmul(x[7], W3); x[11] = cmul(x[11], W6); x[15] = cmul(x[15], W9);
; #pragma unroll
;     for (int c = 0; c < 4; ++c) r4<INV>(x[4 * c], x[4 * c + 1], x[4 * c + 2], x[4 * c + 3]);
; }
; template <bool INV> __device__ __forceinline__ void pass16_s64(LAS f32x2* X, const LAS f32x2* TH, int base, int j) {
;     f32x2 x[16];
; #pragma unroll
;     for (int q = 0; q < 16; ++q) x[q] = X[base + q * 68];
;     bfly16_tab<INV>(x, TH - 2048, 64, j);
; #pragma unroll
;     for (int c = 0; c < 4; ++c)
; #pragma unroll
;         for (int d = 0; d < 4; ++d) X[base + (c + 4 * d) * 68] = x[4 * c + d];
; }
.LBB0_698:
	v_add_u32_e32 v128, s0, v140
	v_lshrrev_b32_e32 v147, 6, v128
	v_mad_u32_u24 v151, v147, s77, v142
	ds_read_b64 v[0:1], v151 offset:0
	ds_read_b64 v[2:3], v151 offset:4352
	ds_read_b64 v[4:5], v151 offset:544
	ds_read_b64 v[6:7], v151 offset:4896
	ds_read_b64 v[8:9], v151 offset:1088
	ds_read_b64 v[10:11], v151 offset:5440
	ds_read_b64 v[12:13], v151 offset:1632
	ds_read_b64 v[14:15], v151 offset:5984
	ds_read_b64 v[16:17], v151 offset:2176
	ds_read_b64 v[18:19], v151 offset:6528
	ds_read_b64 v[20:21], v151 offset:2720
	ds_read_b64 v[22:23], v151 offset:7072
	ds_read_b64 v[24:25], v151 offset:3264
	ds_read_b64 v[26:27], v151 offset:7616
	ds_read_b64 v[28:29], v151 offset:3808
	ds_read_b64 v[30:31], v151 offset:8160
	s_cmp_eq_u32 s0, 0
	s_movk_i32 s0, 0x200
	s_mov_b64 s[36:37], 0
	s_waitcnt lgkmcnt(14)
	v_pk_add_f32 v[32:33], v[0:1], v[2:3]
	s_waitcnt lgkmcnt(12)
	v_pk_add_f32 v[34:35], v[4:5], v[6:7]
	s_waitcnt lgkmcnt(10)
	v_pk_add_f32 v[36:37], v[8:9], v[10:11]
	s_waitcnt lgkmcnt(8)
	v_pk_add_f32 v[38:39], v[12:13], v[14:15]
	v_pk_add_f32 v[2:3], v[0:1], v[2:3] neg_lo:[0,1] neg_hi:[0,1]
	v_pk_add_f32 v[6:7], v[4:5], v[6:7] neg_lo:[0,1] neg_hi:[0,1]
	v_pk_add_f32 v[8:9], v[8:9], v[10:11] neg_lo:[0,1] neg_hi:[0,1]
	v_pk_add_f32 v[12:13], v[12:13], v[14:15] neg_lo:[0,1] neg_hi:[0,1]
	s_waitcnt lgkmcnt(6)
	v_pk_add_f32 v[14:15], v[16:17], v[18:19]
	s_waitcnt lgkmcnt(4)
	v_pk_add_f32 v[10:11], v[20:21], v[22:23]
	s_waitcnt lgkmcnt(2)
	v_pk_add_f32 v[4:5], v[24:25], v[26:27]
	s_waitcnt lgkmcnt(0)
	v_pk_add_f32 v[0:1], v[28:29], v[30:31]
	v_pk_add_f32 v[16:17], v[16:17], v[18:19] neg_lo:[0,1] neg_hi:[0,1]
	v_pk_add_f32 v[20:21], v[20:21], v[22:23] neg_lo:[0,1] neg_hi:[0,1]
	v_pk_add_f32 v[26:27], v[24:25], v[26:27] neg_lo:[0,1] neg_hi:[0,1]
	v_pk_add_f32 v[30:31], v[28:29], v[30:31] neg_lo:[0,1] neg_hi:[0,1]
	v_pk_add_f32 v[28:29], v[32:33], v[14:15]
	v_pk_add_f32 v[24:25], v[34:35], v[10:11]
	v_pk_add_f32 v[22:23], v[36:37], v[4:5]
	v_pk_add_f32 v[18:19], v[38:39], v[0:1]
	v_pk_add_f32 v[14:15], v[32:33], v[14:15] neg_lo:[0,1] neg_hi:[0,1]
	v_pk_add_f32 v[34:35], v[34:35], v[10:11] neg_lo:[0,1] neg_hi:[0,1]
	v_pk_add_f32 v[36:37], v[36:37], v[4:5] neg_lo:[0,1] neg_hi:[0,1]
	v_pk_add_f32 v[38:39], v[38:39], v[0:1] neg_lo:[0,1] neg_hi:[0,1]
	v_pk_add_f32 v[0:1], v[2:3], v[16:17] op_sel:[0,1] op_sel_hi:[1,0] neg_hi:[0,1]
	v_pk_add_f32 v[4:5], v[6:7], v[20:21] op_sel:[0,1] op_sel_hi:[1,0] neg_hi:[0,1]
	v_pk_add_f32 v[10:11], v[8:9], v[26:27] op_sel:[0,1] op_sel_hi:[1,0] neg_hi:[0,1]
	v_pk_add_f32 v[32:33], v[12:13], v[30:31] op_sel:[0,1] op_sel_hi:[1,0] neg_hi:[0,1]
	v_pk_add_f32 v[2:3], v[2:3], v[16:17] op_sel:[0,1] op_sel_hi:[1,0] neg_lo:[0,1]
	v_pk_add_f32 v[20:21], v[6:7], v[20:21] op_sel:[0,1] op_sel_hi:[1,0] neg_lo:[0,1]
	v_pk_add_f32 v[26:27], v[8:9], v[26:27] op_sel:[0,1] op_sel_hi:[1,0] neg_lo:[0,1]
	v_pk_add_f32 v[30:31], v[12:13], v[30:31] op_sel:[0,1] op_sel_hi:[1,0] neg_lo:[0,1]
	v_pk_add_f32 v[12:13], v[28:29], v[22:23]
	v_pk_mul_f32 v[8:9], v[4:5], s[70:71] op_sel_hi:[1,0]
	v_pk_mul_f32 v[6:7], v[34:35], s[72:73] op_sel_hi:[1,0]
	v_pk_mul_f32 v[16:17], v[20:21], s[64:65] op_sel_hi:[1,0]
	v_pk_add_f32 v[22:23], v[28:29], v[22:23] neg_lo:[0,1] neg_hi:[0,1]
	v_pk_fma_f32 v[8:9], v[4:5], s[44:45], v[8:9] op_sel:[0,0,1] op_sel_hi:[1,0,0] neg_lo:[0,0,1]
	v_pk_fma_f32 v[6:7], v[34:35], s[76:77], v[6:7] op_sel:[0,0,1] op_sel_hi:[1,0,0] neg_lo:[0,0,1]
	v_pk_fma_f32 v[20:21], v[20:21], s[82:83], v[16:17] op_sel:[0,0,1] op_sel_hi:[1,0,0] neg_lo:[0,0,1]
	v_pk_add_f32 v[16:17], v[24:25], v[18:19]
	v_pk_fma_f32 v[34:35], v[10:11], s[72:73], v[0:1] op_sel:[0,0,1] op_sel_hi:[1,0,0] neg_hi:[0,0,1]
	v_pk_add_f32 v[4:5], v[14:15], v[36:37] op_sel:[0,1] op_sel_hi:[1,0] neg_hi:[0,1]
	v_pk_fma_f32 v[28:29], v[26:27], s[72:73], v[2:3] op_sel:[0,0,1] op_sel_hi:[1,0,0] neg_hi:[0,0,1]
	v_pk_add_f32 v[24:25], v[24:25], v[18:19] neg_lo:[0,1] neg_hi:[0,1]
	v_pk_fma_f32 v[34:35], v[10:11], s[76:77], v[34:35] op_sel:[0,0,1] op_sel_hi:[1,0,0] neg_lo:[0,0,1]
	v_pk_add_f32 v[14:15], v[14:15], v[36:37] op_sel:[0,1] op_sel_hi:[1,0] neg_lo:[0,1]
	v_pk_fma_f32 v[26:27], v[26:27], s[72:73], v[28:29] op_sel:[0,0,1] op_sel_hi:[1,0,0] neg_lo:[0,0,1]
	v_pk_add_f32 v[28:29], v[12:13], v[16:17]
	v_pk_fma_f32 v[0:1], v[0:1], s[100:101], v[34:35] op_sel_hi:[1,0,1] neg_lo:[0,0,1] neg_hi:[0,0,1]
	v_pk_fma_f32 v[36:37], v[38:39], s[72:73], v[6:7] op_sel:[0,0,1] op_sel_hi:[1,0,0] neg_hi:[0,0,1]
	v_pk_fma_f32 v[2:3], v[2:3], s[100:101], v[26:27] op_sel_hi:[1,0,1] neg_lo:[0,0,1] neg_hi:[0,0,1]
	v_pk_add_f32 v[16:17], v[12:13], v[16:17] neg_lo:[0,1] neg_hi:[0,1]
	v_pk_fma_f32 v[12:13], v[32:33], s[64:65], v[8:9] op_sel:[0,0,1] op_sel_hi:[1,0,0] neg_hi:[0,0,1]
	v_pk_fma_f32 v[36:37], v[38:39], s[72:73], v[36:37] op_sel:[0,0,1] op_sel_hi:[1,0,0] neg_lo:[0,0,1]
	v_pk_fma_f32 v[38:39], v[30:31], s[82:83], v[20:21] op_sel:[0,0,1] op_sel_hi:[1,0,0] neg_hi:[0,0,1]
	v_pk_add_f32 v[10:11], v[22:23], v[24:25] op_sel:[0,1] op_sel_hi:[1,0] neg_hi:[0,1]
	v_pk_fma_f32 v[12:13], v[32:33], s[82:83], v[12:13] op_sel:[0,0,1] op_sel_hi:[1,0,0] neg_lo:[0,0,1]
	v_pk_fma_f32 v[6:7], v[6:7], s[100:101], v[36:37] op_sel_hi:[1,0,1] neg_lo:[0,0,1] neg_hi:[0,0,1]
	v_pk_fma_f32 v[30:31], v[30:31], s[64:65], v[38:39] op_sel:[0,0,1] op_sel_hi:[1,0,0] neg_lo:[0,0,1]
	v_pk_add_f32 v[24:25], v[22:23], v[24:25] op_sel:[0,1] op_sel_hi:[1,0] neg_lo:[0,1]
	v_pk_fma_f32 v[8:9], v[8:9], s[100:101], v[12:13] op_sel_hi:[1,0,1] neg_lo:[0,0,1] neg_hi:[0,0,1]
	v_pk_add_f32 v[22:23], v[4:5], v[36:37]
	v_pk_fma_f32 v[20:21], v[20:21], s[100:101], v[30:31] op_sel_hi:[1,0,1] neg_lo:[0,0,1] neg_hi:[0,0,1]
; #define LAS __attribute__((address_space(3)))
; __device__ __forceinline__ f32x2 cmul(f32x2 a, f32x2 b) { return (f32x2){a.x * b.x - a.y * b.y, a.x * b.y + a.y * b.x}; }
; template <bool INV> __device__ __forceinline__ void bfly16_tab(f32x2 (&x)[16], const LAS f32x2* T, int tstride, int j) {
;     if (INV) {
; #pragma unroll
;         for (int q = 1; q < 16; ++q) { f32x2 p = T[q * tstride + j]; p.y = -p.y; x[q] = cmul(x[q], p); } }
;     dft16<INV>(x);
;     if (!INV) {
; #pragma unroll
;         for (int r = 1; r < 16; ++r) { const f32x2 p = T[r * tstride + j]; x[4 * (r & 3) + (r >> 2)] = cmul(x[4 * (r & 3) + (r >> 2)], p); } }
; }
; template <bool INV> __device__ __forceinline__ void pass16_s64(LAS f32x2* X, const LAS f32x2* TH, int base, int j) {
;     f32x2 x[16];
; #pragma unroll
;     for (int q = 0; q < 16; ++q) x[q] = X[base + q * 68];
;     bfly16_tab<INV>(x, TH - 2048, 64, j);
; #pragma unroll
;     for (int c = 0; c < 4; ++c)
; #pragma unroll
;         for (int d = 0; d < 4; ++d) X[base + (c + 4 * d) * 68] = x[4 * c + d];
; }
	v_pk_add_f32 v[38:39], v[34:35], v[12:13]
	v_pk_add_f32 v[4:5], v[4:5], v[36:37] neg_lo:[0,1] neg_hi:[0,1]
	v_pk_add_f32 v[36:37], v[26:27], v[30:31]
	v_pk_add_f32 v[12:13], v[34:35], v[12:13] neg_lo:[0,1] neg_hi:[0,1]
	v_pk_add_f32 v[34:35], v[14:15], v[6:7] op_sel:[0,1] op_sel_hi:[1,0] neg_hi:[0,1]
	v_pk_add_f32 v[26:27], v[26:27], v[30:31] neg_lo:[0,1] neg_hi:[0,1]
	v_pk_add_f32 v[30:31], v[0:1], v[8:9] op_sel:[0,1] op_sel_hi:[1,0] neg_hi:[0,1]
	v_pk_add_f32 v[6:7], v[14:15], v[6:7] op_sel:[0,1] op_sel_hi:[1,0] neg_lo:[0,1]
	v_pk_add_f32 v[14:15], v[2:3], v[20:21] op_sel:[0,1] op_sel_hi:[1,0] neg_hi:[0,1]
	v_pk_add_f32 v[8:9], v[0:1], v[8:9] op_sel:[0,1] op_sel_hi:[1,0] neg_lo:[0,1]
	v_pk_add_f32 v[20:21], v[2:3], v[20:21] op_sel:[0,1] op_sel_hi:[1,0] neg_lo:[0,1]
	v_pk_mul_f32 v[2:3], v[38:39], v[232:233] op_sel:[0,1] op_sel_hi:[1,1]
	v_pk_mul_f32 v[0:1], v[22:23], v[234:235] op_sel:[0,1] op_sel_hi:[1,1]
	v_pk_fma_f32 v[2:3], v[38:39], v[232:233], v[2:3] op_sel:[0,0,1] op_sel_hi:[1,0,0] neg_lo:[0,0,1]
	v_pk_mul_f32 v[38:39], v[36:37], v[208:209] op_sel:[0,1] op_sel_hi:[1,1]
	v_pk_fma_f32 v[22:23], v[22:23], v[234:235], v[0:1] op_sel:[0,0,1] op_sel_hi:[1,0,0] neg_lo:[0,0,1]
	v_pk_mul_f32 v[0:1], v[10:11], v[210:211] op_sel:[0,1] op_sel_hi:[1,1]
	v_pk_fma_f32 v[36:37], v[36:37], v[208:209], v[38:39] op_sel:[0,0,1] op_sel_hi:[1,0,0] neg_lo:[0,0,1]
	v_pk_mul_f32 v[38:39], v[30:31], v[204:205] op_sel:[0,1] op_sel_hi:[1,1]
	v_pk_fma_f32 v[0:1], v[10:11], v[210:211], v[0:1] op_sel:[0,0,1] op_sel_hi:[1,0,0] neg_lo:[0,0,1]
	v_pk_mul_f32 v[10:11], v[34:35], v[206:207] op_sel:[0,1] op_sel_hi:[1,1]
	v_pk_fma_f32 v[30:31], v[30:31], v[204:205], v[38:39] op_sel:[0,0,1] op_sel_hi:[1,0,0] neg_lo:[0,0,1]
	v_pk_mul_f32 v[38:39], v[14:15], v[200:201] op_sel:[0,1] op_sel_hi:[1,1]
	v_pk_fma_f32 v[10:11], v[34:35], v[206:207], v[10:11] op_sel:[0,0,1] op_sel_hi:[1,0,0] neg_lo:[0,0,1]
	v_pk_mul_f32 v[34:35], v[16:17], v[202:203] op_sel:[0,1] op_sel_hi:[1,1]
	v_pk_fma_f32 v[38:39], v[14:15], v[200:201], v[38:39] op_sel:[0,0,1] op_sel_hi:[1,0,0] neg_lo:[0,0,1]
	v_pk_mul_f32 v[14:15], v[12:13], v[196:197] op_sel:[0,1] op_sel_hi:[1,1]
	v_pk_fma_f32 v[34:35], v[16:17], v[202:203], v[34:35] op_sel:[0,0,1] op_sel_hi:[1,0,0] neg_lo:[0,0,1]
	v_pk_mul_f32 v[16:17], v[4:5], v[198:199] op_sel:[0,1] op_sel_hi:[1,1]
	v_pk_fma_f32 v[14:15], v[12:13], v[196:197], v[14:15] op_sel:[0,0,1] op_sel_hi:[1,0,0] neg_lo:[0,0,1]
	v_pk_mul_f32 v[12:13], v[26:27], v[192:193] op_sel:[0,1] op_sel_hi:[1,1]
	v_pk_fma_f32 v[16:17], v[4:5], v[198:199], v[16:17] op_sel:[0,0,1] op_sel_hi:[1,0,0] neg_lo:[0,0,1]
	v_pk_mul_f32 v[4:5], v[24:25], v[194:195] op_sel:[0,1] op_sel_hi:[1,1]
	v_pk_fma_f32 v[26:27], v[26:27], v[192:193], v[12:13] op_sel:[0,0,1] op_sel_hi:[1,0,0] neg_lo:[0,0,1]
	v_pk_mul_f32 v[12:13], v[8:9], v[188:189] op_sel:[0,1] op_sel_hi:[1,1]
	v_pk_fma_f32 v[4:5], v[24:25], v[194:195], v[4:5] op_sel:[0,0,1] op_sel_hi:[1,0,0] neg_lo:[0,0,1]
	v_pk_mul_f32 v[24:25], v[6:7], v[190:191] op_sel:[0,1] op_sel_hi:[1,1]
	v_pk_fma_f32 v[8:9], v[8:9], v[188:189], v[12:13] op_sel:[0,0,1] op_sel_hi:[1,0,0] neg_lo:[0,0,1]
	v_pk_mul_f32 v[12:13], v[20:21], v[186:187] op_sel:[0,1] op_sel_hi:[1,1]
	v_pk_fma_f32 v[6:7], v[6:7], v[190:191], v[24:25] op_sel:[0,0,1] op_sel_hi:[1,0,0] neg_lo:[0,0,1]
	v_pk_fma_f32 v[20:21], v[20:21], v[186:187], v[12:13] op_sel:[0,0,1] op_sel_hi:[1,0,0] neg_lo:[0,0,1]
	ds_write_b64 v151, v[28:29] offset:0
	ds_write_b64 v151, v[2:3] offset:544
	ds_write_b64 v151, v[22:23] offset:1088
	ds_write_b64 v151, v[36:37] offset:1632
	ds_write_b64 v151, v[0:1] offset:2176
	ds_write_b64 v151, v[30:31] offset:2720
	ds_write_b64 v151, v[10:11] offset:3264
	ds_write_b64 v151, v[38:39] offset:3808
	ds_write_b64 v151, v[34:35] offset:4352
	ds_write_b64 v151, v[14:15] offset:4896
	ds_write_b64 v151, v[16:17] offset:5440
	ds_write_b64 v151, v[26:27] offset:5984
	ds_write_b64 v151, v[4:5] offset:6528
	ds_write_b64 v151, v[8:9] offset:7072
	ds_write_b64 v151, v[6:7] offset:7616
	ds_write_b64 v151, v[20:21] offset:8160
	s_cbranch_scc1 .LBB0_698
	s_waitcnt lgkmcnt(0)
	s_barrier
	s_mov_b32 s0, 0
	s_mov_b64 s[36:37], -1
	ds_read2_b64 v[232:235], v141 offset0:4 offset1:8
	ds_read2_b64 v[208:211], v141 offset0:12 offset1:16
	ds_read2_b64 v[204:207], v141 offset0:20 offset1:24
	ds_read2_b64 v[200:203], v141 offset0:28 offset1:32
	ds_read2_b64 v[196:199], v141 offset0:36 offset1:40
	ds_read2_b64 v[192:195], v141 offset0:44 offset1:48
	ds_read2_b64 v[188:191], v141 offset0:52 offset1:56
	ds_read_b64 v[186:187], v141 offset:480
; #define LAS __attribute__((address_space(3)))
; __device__ __forceinline__ f32x2 cmul(f32x2 a, f32x2 b) { return (f32x2){a.x * b.x - a.y * b.y, a.x * b.y + a.y * b.x}; }
; template <bool INV> __device__ __forceinline__ void dft16(f32x2 (&x)[16]) {
; #pragma unroll
;     for (int b = 0; b < 4; ++b) r4<INV>(x[b], x[4 + b], x[8 + b], x[12 + b]);
;     const float sg = INV ? -1.f : 1.f;
;     const f32x2 W1 = {0.92387953251f, -0.38268343236f * sg}, W2 = {0.70710678118f, -0.70710678118f * sg}, W3 = {0.38268343236f, -0.92387953251f * sg},
;                 W4 = {0.f, -1.f * sg}, W6 = {-0.70710678118f, -0.70710678118f * sg}, W9 = {-0.92387953251f, 0.38268343236f * sg};
;     x[5] = cmul(x[5], W1); x[9] = cmul(x[9], W2); x[13] = cmul(x[13], W3);
;     x[6] = cmul(x[6], W2); x[10] = cmul(x[10], W4); x[14] = cmul(x[14], W6);
;     x[7] = cmul(x[7], W3); x[11] = cmul(x[11], W6); x[15] = cmul(x[15], W9);
; #pragma unroll
;     for (int c = 0; c < 4; ++c) r4<INV>(x[4 * c], x[4 * c + 1], x[4 * c + 2], x[4 * c + 3]);
; }
; template <bool INV> __device__ __forceinline__ void pass16_s4(LAS f32x2* X, const LAS f32x2* TH, const LAS f32x2* TL, int tid) {
; #pragma unroll 1
;     for (int s = 0; s < 2; ++s) {
;         const int b = tid + NTHR * s, blk = b >> 2, jj = b & 3;
;         LAS f32x2* P = X + blk * 68 + jj;
;         f32x2 x[16];
; #pragma unroll
;         for (int q = 0; q < 16; ++q) x[q] = P[4 * q];
;         bfly16_tab<INV>(x, TH - 1024, 4, jj);
; #pragma unroll
;         for (int c = 0; c < 4; ++c)
; #pragma unroll
;             for (int d = 0; d < 4; ++d) P[4 * (c + 4 * d)] = x[4 * c + d];
;     }
; }
.LBB0_700:
	v_add_u32_e32 v128, s0, v140
	v_lshrrev_b32_e32 v147, 2, v128
	v_mad_u32_u24 v151, v147, s43, v144
	ds_read_b64 v[0:1], v151 offset:0
	ds_read_b64 v[2:3], v151 offset:256
	ds_read_b64 v[4:5], v151 offset:32
	ds_read_b64 v[6:7], v151 offset:288
	ds_read_b64 v[8:9], v151 offset:64
	ds_read_b64 v[10:11], v151 offset:320
	ds_read_b64 v[12:13], v151 offset:96
	ds_read_b64 v[14:15], v151 offset:352
	ds_read_b64 v[16:17], v151 offset:128
	ds_read_b64 v[18:19], v151 offset:384
	ds_read_b64 v[20:21], v151 offset:160
	ds_read_b64 v[22:23], v151 offset:416
	ds_read_b64 v[24:25], v151 offset:192
	ds_read_b64 v[26:27], v151 offset:448
	ds_read_b64 v[28:29], v151 offset:224
	ds_read_b64 v[30:31], v151 offset:480
	s_cmp_eq_u32 s0, 0
	s_movk_i32 s0, 0x200
	s_mov_b64 s[36:37], 0
	s_waitcnt lgkmcnt(14)
	v_pk_add_f32 v[32:33], v[0:1], v[2:3]
	s_waitcnt lgkmcnt(12)
	v_pk_add_f32 v[34:35], v[4:5], v[6:7]
	s_waitcnt lgkmcnt(10)
	v_pk_add_f32 v[36:37], v[8:9], v[10:11]
	s_waitcnt lgkmcnt(8)
	v_pk_add_f32 v[38:39], v[12:13], v[14:15]
	v_pk_add_f32 v[0:1], v[0:1], v[2:3] neg_lo:[0,1] neg_hi:[0,1]
	v_pk_add_f32 v[6:7], v[4:5], v[6:7] neg_lo:[0,1] neg_hi:[0,1]
	v_pk_add_f32 v[8:9], v[8:9], v[10:11] neg_lo:[0,1] neg_hi:[0,1]
	v_pk_add_f32 v[12:13], v[12:13], v[14:15] neg_lo:[0,1] neg_hi:[0,1]
	s_waitcnt lgkmcnt(6)
	v_pk_add_f32 v[14:15], v[16:17], v[18:19]
	s_waitcnt lgkmcnt(4)
	v_pk_add_f32 v[10:11], v[20:21], v[22:23]
	s_waitcnt lgkmcnt(2)
	v_pk_add_f32 v[4:5], v[24:25], v[26:27]
	s_waitcnt lgkmcnt(0)
	v_pk_add_f32 v[2:3], v[28:29], v[30:31]
	v_pk_add_f32 v[18:19], v[16:17], v[18:19] neg_lo:[0,1] neg_hi:[0,1]
	v_pk_add_f32 v[22:23], v[20:21], v[22:23] neg_lo:[0,1] neg_hi:[0,1]
	v_pk_add_f32 v[26:27], v[24:25], v[26:27] neg_lo:[0,1] neg_hi:[0,1]
	v_pk_add_f32 v[30:31], v[28:29], v[30:31] neg_lo:[0,1] neg_hi:[0,1]
	v_pk_add_f32 v[28:29], v[32:33], v[14:15]
	v_pk_add_f32 v[24:25], v[34:35], v[10:11]
	v_pk_add_f32 v[20:21], v[36:37], v[4:5]
	v_pk_add_f32 v[16:17], v[38:39], v[2:3]
	v_pk_add_f32 v[14:15], v[32:33], v[14:15] neg_lo:[0,1] neg_hi:[0,1]
	v_pk_add_f32 v[34:35], v[34:35], v[10:11] neg_lo:[0,1] neg_hi:[0,1]
	v_pk_add_f32 v[36:37], v[36:37], v[4:5] neg_lo:[0,1] neg_hi:[0,1]
	v_pk_add_f32 v[2:3], v[38:39], v[2:3] neg_lo:[0,1] neg_hi:[0,1]
	v_pk_add_f32 v[38:39], v[0:1], v[18:19] op_sel:[0,1] op_sel_hi:[1,0] neg_hi:[0,1]
	v_pk_add_f32 v[4:5], v[6:7], v[22:23] op_sel:[0,1] op_sel_hi:[1,0] neg_hi:[0,1]
	v_pk_add_f32 v[10:11], v[8:9], v[26:27] op_sel:[0,1] op_sel_hi:[1,0] neg_hi:[0,1]
	v_pk_add_f32 v[32:33], v[12:13], v[30:31] op_sel:[0,1] op_sel_hi:[1,0] neg_hi:[0,1]
	v_pk_add_f32 v[0:1], v[0:1], v[18:19] op_sel:[0,1] op_sel_hi:[1,0] neg_lo:[0,1]
	v_pk_add_f32 v[6:7], v[6:7], v[22:23] op_sel:[0,1] op_sel_hi:[1,0] neg_lo:[0,1]
	v_pk_add_f32 v[26:27], v[8:9], v[26:27] op_sel:[0,1] op_sel_hi:[1,0] neg_lo:[0,1]
	v_pk_add_f32 v[12:13], v[12:13], v[30:31] op_sel:[0,1] op_sel_hi:[1,0] neg_lo:[0,1]
	v_pk_add_f32 v[30:31], v[28:29], v[20:21]
	v_pk_mul_f32 v[8:9], v[4:5], s[70:71] op_sel_hi:[1,0]
	v_pk_mul_f32 v[22:23], v[34:35], s[72:73] op_sel_hi:[1,0]
	v_pk_mul_f32 v[18:19], v[6:7], s[64:65] op_sel_hi:[1,0]
	v_pk_add_f32 v[28:29], v[28:29], v[20:21] neg_lo:[0,1] neg_hi:[0,1]
	v_pk_fma_f32 v[4:5], v[4:5], s[44:45], v[8:9] op_sel:[0,0,1] op_sel_hi:[1,0,0] neg_lo:[0,0,1]
	v_pk_fma_f32 v[34:35], v[34:35], s[76:77], v[22:23] op_sel:[0,0,1] op_sel_hi:[1,0,0] neg_lo:[0,0,1]
	v_pk_fma_f32 v[18:19], v[6:7], s[82:83], v[18:19] op_sel:[0,0,1] op_sel_hi:[1,0,0] neg_lo:[0,0,1]
	v_pk_add_f32 v[6:7], v[24:25], v[16:17]
	v_pk_fma_f32 v[22:23], v[10:11], s[72:73], v[38:39] op_sel:[0,0,1] op_sel_hi:[1,0,0] neg_hi:[0,0,1]
	v_pk_add_f32 v[8:9], v[14:15], v[36:37] op_sel:[0,1] op_sel_hi:[1,0] neg_hi:[0,1]
	v_pk_fma_f32 v[20:21], v[26:27], s[72:73], v[0:1] op_sel:[0,0,1] op_sel_hi:[1,0,0] neg_hi:[0,0,1]
	v_pk_add_f32 v[16:17], v[24:25], v[16:17] neg_lo:[0,1] neg_hi:[0,1]
	v_pk_fma_f32 v[10:11], v[10:11], s[76:77], v[22:23] op_sel:[0,0,1] op_sel_hi:[1,0,0] neg_lo:[0,0,1]
	v_pk_add_f32 v[14:15], v[14:15], v[36:37] op_sel:[0,1] op_sel_hi:[1,0] neg_lo:[0,1]
	v_pk_fma_f32 v[26:27], v[26:27], s[72:73], v[20:21] op_sel:[0,0,1] op_sel_hi:[1,0,0] neg_lo:[0,0,1]
	v_pk_add_f32 v[20:21], v[30:31], v[6:7]
	v_pk_fma_f32 v[38:39], v[38:39], s[100:101], v[10:11] op_sel_hi:[1,0,1] neg_lo:[0,0,1] neg_hi:[0,0,1]
	v_pk_fma_f32 v[36:37], v[2:3], s[72:73], v[34:35] op_sel:[0,0,1] op_sel_hi:[1,0,0] neg_hi:[0,0,1]
	v_pk_fma_f32 v[0:1], v[0:1], s[100:101], v[26:27] op_sel_hi:[1,0,1] neg_lo:[0,0,1] neg_hi:[0,0,1]
	v_pk_add_f32 v[30:31], v[30:31], v[6:7] neg_lo:[0,1] neg_hi:[0,1]
	v_pk_fma_f32 v[6:7], v[32:33], s[64:65], v[4:5] op_sel:[0,0,1] op_sel_hi:[1,0,0] neg_hi:[0,0,1]
	v_pk_fma_f32 v[2:3], v[2:3], s[72:73], v[36:37] op_sel:[0,0,1] op_sel_hi:[1,0,0] neg_lo:[0,0,1]
	v_pk_fma_f32 v[36:37], v[12:13], s[82:83], v[18:19] op_sel:[0,0,1] op_sel_hi:[1,0,0] neg_hi:[0,0,1]
	v_pk_add_f32 v[22:23], v[28:29], v[16:17] op_sel:[0,1] op_sel_hi:[1,0] neg_hi:[0,1]
	v_pk_fma_f32 v[6:7], v[32:33], s[82:83], v[6:7] op_sel:[0,0,1] op_sel_hi:[1,0,0] neg_lo:[0,0,1]
	v_pk_fma_f32 v[34:35], v[34:35], s[100:101], v[2:3] op_sel_hi:[1,0,1] neg_lo:[0,0,1] neg_hi:[0,0,1]
	v_pk_fma_f32 v[36:37], v[12:13], s[64:65], v[36:37] op_sel:[0,0,1] op_sel_hi:[1,0,0] neg_lo:[0,0,1]
	v_pk_add_f32 v[16:17], v[28:29], v[16:17] op_sel:[0,1] op_sel_hi:[1,0] neg_lo:[0,1]
	v_pk_fma_f32 v[4:5], v[4:5], s[100:101], v[6:7] op_sel_hi:[1,0,1] neg_lo:[0,0,1] neg_hi:[0,0,1]
	v_pk_add_f32 v[28:29], v[8:9], v[2:3]
	v_pk_fma_f32 v[18:19], v[18:19], s[100:101], v[36:37] op_sel_hi:[1,0,1] neg_lo:[0,0,1] neg_hi:[0,0,1]
	v_pk_add_f32 v[12:13], v[10:11], v[6:7]
; #define LAS __attribute__((address_space(3)))
; __device__ __forceinline__ float lane_read(float v, int src_lane) { return __builtin_bit_cast(float, __builtin_amdgcn_ds_bpermute(src_lane << 2, __builtin_bit_cast(int, v))); }
; #define LDS_BARRIER() do { asm volatile("s_waitcnt lgkmcnt(0)" ::: "memory"); __builtin_amdgcn_s_barrier(); asm volatile("" ::: "memory"); } while (0)
; #define LT() ({ int lt_ = tid; asm volatile("" : "+v"(lt_)); lt_; })
; template <bool INV> __device__ __forceinline__ void pass16_s4(LAS f32x2* X, const LAS f32x2* TH, const LAS f32x2* TL, int tid) {
; #pragma unroll 1
;     for (int s = 0; s < 2; ++s) {
;         const int b = tid + NTHR * s, blk = b >> 2, jj = b & 3;
;         LAS f32x2* P = X + blk * 68 + jj;
;         f32x2 x[16];
; #pragma unroll
;         for (int q = 0; q < 16; ++q) x[q] = P[4 * q];
;         bfly16_tab<INV>(x, TH - 1024, 4, jj);
; #pragma unroll
;         for (int c = 0; c < 4; ++c)
; #pragma unroll
;             for (int d = 0; d < 4; ++d) P[4 * (c + 4 * d)] = x[4 * c + d];
;     }
; }
; __device__ __forceinline__ void hyena_latent(Frame& F, int l, int ch, LAS f32x2* X, const LAS f32x2* TH, const LAS f32x2* TL, GAS f32x2* KS, const LAS float* CT  , bool wr = true) {
;     ...
; #pragma unroll
;             for (int i = 0; i < 8; ++i) { const int b = LT() + NTHR * i; const LAS f32x4* P = (const LAS f32x4*)(X + 4 * b + ((b >> 4) << 2)); const f32x4 u = P[0], v = P[1];
;                 f32x2 x0 = {u.x, u.y}, x1 = {u.z, u.w}, x2 = {v.x, v.y}, x3 = {v.z, v.w}; r4<false>(x0, x1, x2, x3);
;                 kreg[2 * i] = (f32x4){x0.x, x0.y, x1.x, x1.y}; kreg[2 * i + 1] = (f32x4){x2.x, x2.y, x3.x, x3.y}; }
;             LDS_BARRIER();
;             HP_END(31) }
;             { HP_BEGIN(32)
; #pragma unroll
;             for (int i = 0; i < 8; ++i) { const int g = LT() + NTHR * i, n0 = 4 * g;
;                 f32x4 z0 = pc0[i], z1 = pc1[i];
;                 if (o == 0) { const f32x4 c = pc0[i], d = pc1[i]; const int ln = F.lane;
;                     float l0 = lane_read(c.w, ln - 1), r0 = lane_read(c.x, ln + 1), l1 = lane_read(d.w, ln - 1), r1 = lane_read(d.x, ln + 1);
;                     if (ln == 0) { l0 = n0 > 0 ? hv[n0 - 1] : 0.f; l1 = n0 > 0 ? hv[SEQ + n0 - 1] : 0.f; }
;                     if (ln == 63) { r0 = n0 + 4 < SEQ ? hv[n0 + 4] : 0.f; r1 = n0 + 4 < SEQ ? hv[SEQ + n0 + 4] : 0.f; }
	v_pk_add_f32 v[8:9], v[8:9], v[2:3] neg_lo:[0,1] neg_hi:[0,1]
	v_pk_add_f32 v[2:3], v[26:27], v[36:37]
	v_pk_add_f32 v[6:7], v[10:11], v[6:7] neg_lo:[0,1] neg_hi:[0,1]
	v_pk_add_f32 v[10:11], v[14:15], v[34:35] op_sel:[0,1] op_sel_hi:[1,0] neg_hi:[0,1]
	v_pk_add_f32 v[26:27], v[26:27], v[36:37] neg_lo:[0,1] neg_hi:[0,1]
	v_pk_add_f32 v[36:37], v[38:39], v[4:5] op_sel:[0,1] op_sel_hi:[1,0] neg_hi:[0,1]
	v_pk_add_f32 v[34:35], v[14:15], v[34:35] op_sel:[0,1] op_sel_hi:[1,0] neg_lo:[0,1]
	v_pk_add_f32 v[14:15], v[0:1], v[18:19] op_sel:[0,1] op_sel_hi:[1,0] neg_hi:[0,1]
	v_pk_add_f32 v[38:39], v[38:39], v[4:5] op_sel:[0,1] op_sel_hi:[1,0] neg_lo:[0,1]
	v_pk_add_f32 v[18:19], v[0:1], v[18:19] op_sel:[0,1] op_sel_hi:[1,0] neg_lo:[0,1]
	v_pk_mul_f32 v[0:1], v[12:13], v[232:233] op_sel:[0,1] op_sel_hi:[1,1]
	v_pk_mul_f32 v[4:5], v[28:29], v[234:235] op_sel:[0,1] op_sel_hi:[1,1]
	v_pk_fma_f32 v[0:1], v[12:13], v[232:233], v[0:1] op_sel:[0,0,1] op_sel_hi:[1,0,0] neg_lo:[0,0,1]
	v_pk_mul_f32 v[12:13], v[2:3], v[208:209] op_sel:[0,1] op_sel_hi:[1,1]
	v_pk_fma_f32 v[28:29], v[28:29], v[234:235], v[4:5] op_sel:[0,0,1] op_sel_hi:[1,0,0] neg_lo:[0,0,1]
	v_pk_mul_f32 v[4:5], v[22:23], v[210:211] op_sel:[0,1] op_sel_hi:[1,1]
	v_pk_fma_f32 v[12:13], v[2:3], v[208:209], v[12:13] op_sel:[0,0,1] op_sel_hi:[1,0,0] neg_lo:[0,0,1]
	v_pk_mul_f32 v[2:3], v[36:37], v[204:205] op_sel:[0,1] op_sel_hi:[1,1]
	v_pk_fma_f32 v[4:5], v[22:23], v[210:211], v[4:5] op_sel:[0,0,1] op_sel_hi:[1,0,0] neg_lo:[0,0,1]
	v_pk_mul_f32 v[22:23], v[10:11], v[206:207] op_sel:[0,1] op_sel_hi:[1,1]
	v_pk_fma_f32 v[2:3], v[36:37], v[204:205], v[2:3] op_sel:[0,0,1] op_sel_hi:[1,0,0] neg_lo:[0,0,1]
	v_pk_mul_f32 v[36:37], v[14:15], v[200:201] op_sel:[0,1] op_sel_hi:[1,1]
	v_pk_fma_f32 v[22:23], v[10:11], v[206:207], v[22:23] op_sel:[0,0,1] op_sel_hi:[1,0,0] neg_lo:[0,0,1]
	v_pk_mul_f32 v[10:11], v[30:31], v[202:203] op_sel:[0,1] op_sel_hi:[1,1]
	v_pk_fma_f32 v[36:37], v[14:15], v[200:201], v[36:37] op_sel:[0,0,1] op_sel_hi:[1,0,0] neg_lo:[0,0,1]
	v_pk_mul_f32 v[14:15], v[6:7], v[196:197] op_sel:[0,1] op_sel_hi:[1,1]
	v_pk_fma_f32 v[30:31], v[30:31], v[202:203], v[10:11] op_sel:[0,0,1] op_sel_hi:[1,0,0] neg_lo:[0,0,1]
	v_pk_mul_f32 v[10:11], v[8:9], v[198:199] op_sel:[0,1] op_sel_hi:[1,1]
	v_pk_fma_f32 v[14:15], v[6:7], v[196:197], v[14:15] op_sel:[0,0,1] op_sel_hi:[1,0,0] neg_lo:[0,0,1]
	v_pk_mul_f32 v[6:7], v[26:27], v[192:193] op_sel:[0,1] op_sel_hi:[1,1]
	v_pk_fma_f32 v[10:11], v[8:9], v[198:199], v[10:11] op_sel:[0,0,1] op_sel_hi:[1,0,0] neg_lo:[0,0,1]
	v_pk_mul_f32 v[8:9], v[16:17], v[194:195] op_sel:[0,1] op_sel_hi:[1,1]
	v_pk_fma_f32 v[26:27], v[26:27], v[192:193], v[6:7] op_sel:[0,0,1] op_sel_hi:[1,0,0] neg_lo:[0,0,1]
	v_pk_mul_f32 v[6:7], v[38:39], v[188:189] op_sel:[0,1] op_sel_hi:[1,1]
	v_pk_fma_f32 v[16:17], v[16:17], v[194:195], v[8:9] op_sel:[0,0,1] op_sel_hi:[1,0,0] neg_lo:[0,0,1]
	v_pk_mul_f32 v[8:9], v[34:35], v[190:191] op_sel:[0,1] op_sel_hi:[1,1]
	v_pk_fma_f32 v[38:39], v[38:39], v[188:189], v[6:7] op_sel:[0,0,1] op_sel_hi:[1,0,0] neg_lo:[0,0,1]
	v_pk_mul_f32 v[6:7], v[18:19], v[186:187] op_sel:[0,1] op_sel_hi:[1,1]
	v_pk_fma_f32 v[8:9], v[34:35], v[190:191], v[8:9] op_sel:[0,0,1] op_sel_hi:[1,0,0] neg_lo:[0,0,1]
	v_pk_fma_f32 v[18:19], v[18:19], v[186:187], v[6:7] op_sel:[0,0,1] op_sel_hi:[1,0,0] neg_lo:[0,0,1]
	ds_write_b64 v151, v[20:21] offset:0
	ds_write_b64 v151, v[0:1] offset:32
	ds_write_b64 v151, v[28:29] offset:64
	ds_write_b64 v151, v[12:13] offset:96
	ds_write_b64 v151, v[4:5] offset:128
	ds_write_b64 v151, v[2:3] offset:160
	ds_write_b64 v151, v[22:23] offset:192
	ds_write_b64 v151, v[36:37] offset:224
	ds_write_b64 v151, v[30:31] offset:256
	ds_write_b64 v151, v[14:15] offset:288
	ds_write_b64 v151, v[10:11] offset:320
	ds_write_b64 v151, v[26:27] offset:352
	ds_write_b64 v151, v[16:17] offset:384
	ds_write_b64 v151, v[38:39] offset:416
	ds_write_b64 v151, v[8:9] offset:448
	ds_write_b64 v151, v[18:19] offset:480
	s_cbranch_scc1 .LBB0_700
	v_mov_b32_e32 v0, v140
	s_waitcnt lgkmcnt(0)
	s_barrier
	v_mov_b32_e32 v128, v140
	v_lshlrev_b32_e32 v1, 5, v0
	v_lshlrev_b32_e32 v0, 1, v0
	v_and_b32_e32 v0, 0xffffffe0, v0
	v_add3_u32 v0, 0, v1, v0
	ds_read_b128 v[56:59], v0
	ds_read_b128 v[60:63], v0 offset:16
	v_mov_b32_e32 v0, v140
	s_and_b64 vcc, s[26:27], exec
	v_add_u32_e32 v0, 0x200, v0
	v_lshlrev_b32_e32 v1, 5, v0
	v_lshlrev_b32_e32 v0, 1, v0
	v_and_b32_e32 v0, 0xffffffe0, v0
	v_add3_u32 v0, 0, v1, v0
	ds_read_b128 v[48:51], v0
	ds_read_b128 v[52:55], v0 offset:16
	v_mov_b32_e32 v0, v140
	s_nop 0
	v_add_u32_e32 v0, 0x400, v0
	v_lshlrev_b32_e32 v1, 5, v0
	v_lshlrev_b32_e32 v0, 1, v0
	v_and_b32_e32 v0, 0xffffffe0, v0
	v_add3_u32 v0, 0, v1, v0
	ds_read_b128 v[40:43], v0
	ds_read_b128 v[44:47], v0 offset:16
	v_mov_b32_e32 v0, v140
	s_nop 0
	v_add_u32_e32 v0, 0x600, v0
	v_lshlrev_b32_e32 v1, 5, v0
	v_lshlrev_b32_e32 v0, 1, v0
	v_and_b32_e32 v0, 0xffffffe0, v0
	v_add3_u32 v0, 0, v1, v0
	ds_read_b128 v[32:35], v0
	ds_read_b128 v[36:39], v0 offset:16
	v_mov_b32_e32 v0, v140
	s_nop 0
	v_add_u32_e32 v0, 0x800, v0
	v_lshlrev_b32_e32 v1, 5, v0
	v_lshlrev_b32_e32 v0, 1, v0
	v_and_b32_e32 v0, 0xffffffe0, v0
	v_add3_u32 v0, 0, v1, v0
	ds_read_b128 v[24:27], v0
	ds_read_b128 v[28:31], v0 offset:16
	v_mov_b32_e32 v0, v140
	s_nop 0
	v_add_u32_e32 v0, 0xa00, v0
	v_lshlrev_b32_e32 v1, 5, v0
	v_lshlrev_b32_e32 v0, 1, v0
	v_and_b32_e32 v0, 0xffffffe0, v0
	v_add3_u32 v0, 0, v1, v0
	ds_read_b128 v[12:15], v0
	ds_read_b128 v[20:23], v0 offset:16
	v_mov_b32_e32 v0, v140
	s_nop 0
	v_add_u32_e32 v0, 0xc00, v0
	v_lshlrev_b32_e32 v1, 5, v0
	v_lshlrev_b32_e32 v0, 1, v0
	v_and_b32_e32 v0, 0xffffffe0, v0
	v_add3_u32 v0, 0, v1, v0
	ds_read_b128 v[4:7], v0
	ds_read_b128 v[16:19], v0 offset:16
	v_mov_b32_e32 v0, v140
	s_nop 0
	v_add_u32_e32 v0, 0xe00, v0
	v_lshlrev_b32_e32 v1, 5, v0
	v_lshlrev_b32_e32 v0, 1, v0
	v_and_b32_e32 v0, 0xffffffe0, v0
	v_add3_u32 v8, 0, v1, v0
	ds_read_b128 v[0:3], v8
	ds_read_b128 v[8:11], v8 offset:16
	s_waitcnt lgkmcnt(0)
	s_nop 0
	s_nop 0
	v_lshlrev_b32_e32 v176, 2, v128
	s_cbranch_vccz .LBB0_715
	s_waitcnt vmcnt(15)
	ds_bpermute_b32 v134, v143, v127
	ds_bpermute_b32 v133, v145, v124
	s_waitcnt vmcnt(14)
	ds_bpermute_b32 v130, v143, v123
	ds_bpermute_b32 v129, v145, v120
	s_and_saveexec_b64 s[36:37], s[8:9]
	s_cbranch_execz .LBB0_708
	v_cmp_lt_i32_e32 vcc, 0, v176
	s_waitcnt lgkmcnt(1)
	v_mov_b32_e32 v130, 0
	v_mov_b32_e32 v134, 0
	s_and_saveexec_b64 s[38:39], vcc
	s_cbranch_execz .LBB0_705
	v_lshl_add_u64 v[134:135], v[176:177], 2, s[20:21]
	global_load_dword v134, v[134:135], off offset:-4

; #define LAS __attribute__((address_space(3)))
; __device__ __forceinline__ f32x2 cmul(f32x2 a, f32x2 b) { return (f32x2){a.x * b.x - a.y * b.y, a.x * b.y + a.y * b.x}; }
; __device__ __forceinline__ f32x2 tw32k(const LAS f32x2* TH, const LAS f32x2* TL, int n) { return cmul(TH[n >> 7], TL[n & 127]); }
; template <bool INV> __device__ __forceinline__ void bfly16(f32x2 (&x)[16], const LAS f32x2* TH, const LAS f32x2* TL, int tw) {
;     f32x2 W = tw32k(TH, TL, tw); if (INV) W.y = -W.y;
;     if (INV) { f32x2 p = W;
; #pragma unroll
;         for (int q = 1; q < 16; ++q) { x[q] = cmul(x[q], p); if (q < 15) p = cmul(p, W); } }
;     dft16<INV>(x);
;     if (!INV) { f32x2 p = W;
; #pragma unroll
;         for (int r = 1; r < 16; ++r) { x[4 * (r & 3) + (r >> 2)] = cmul(x[4 * (r & 3) + (r >> 2)], p); if (r < 15) p = cmul(p, W); } }
; }
; template <bool INV> __device__ __forceinline__ void pass16(LAS f32x2* X, const LAS f32x2* TH, const LAS f32x2* TL, int base, int stride, int tw) {
;     f32x2 x[16];
; #pragma unroll
;     for (int q = 0; q < 16; ++q) x[q] = X[base + q * stride];
;     bfly16<INV>(x, TH, TL, tw);
; #pragma unroll
;     for (int c = 0; c < 4; ++c)
; #pragma unroll
;         for (int d = 0; d < 4; ++d) X[base + (c + 4 * d) * stride] = x[4 * c + d];
; }
.LBB0_846:
	v_add_u32_e32 v128, s0, v140
	v_lshrrev_b32_e32 v147, 6, v128
	v_and_b32_e32 v157, 63, v128
	v_lshlrev_b32_e32 v151, 5, v147
	v_lshlrev_b32_e32 v155, 3, v147
	v_lshlrev_b32_e32 v157, 4, v157
	v_lshl_add_u32 v151, v128, 3, v151
	v_add_u32_e32 v155, 0x26000, v155
	v_add_u32_e32 v157, 0x26400, v157
	v_add_u32_e32 v176, 0x11000, v151
	ds_read_b64 v[64:65], v155
	ds_read_b64 v[66:67], v157
	ds_read_b64 v[68:69], v151 offset:0
	ds_read_b64 v[70:71], v176 offset:0
	ds_read_b64 v[72:73], v151 offset:8704
	ds_read_b64 v[74:75], v176 offset:8704
	ds_read_b64 v[76:77], v151 offset:17408
	ds_read_b64 v[78:79], v176 offset:17408
	ds_read_b64 v[80:81], v151 offset:26112
	ds_read_b64 v[82:83], v176 offset:26112
	ds_read_b64 v[84:85], v151 offset:34816
	ds_read_b64 v[86:87], v176 offset:34816
	ds_read_b64 v[88:89], v151 offset:43520
	ds_read_b64 v[90:91], v176 offset:43520
	ds_read_b64 v[92:93], v151 offset:52224
	ds_read_b64 v[94:95], v176 offset:52224
	ds_read_b64 v[96:97], v151 offset:60928
	ds_read_b64 v[98:99], v176 offset:60928
	s_cmp_eq_u32 s0, 0
	s_movk_i32 s0, 0x200
	s_mov_b64 s[12:13], 0
	s_waitcnt lgkmcnt(15)
	v_pk_mul_f32 v[100:101], v[64:65], v[66:67] op_sel:[0,1] op_sel_hi:[1,1]
	s_nop 0
	v_pk_fma_f32 v[100:101], v[64:65], v[66:67], v[100:101] op_sel:[0,0,1] op_sel_hi:[1,0,0] neg_lo:[0,0,1]
	s_nop 0
	v_pk_mul_f32 v[66:67], v[100:101], v[100:101] op_sel:[0,1] op_sel_hi:[1,1]
	s_nop 0
	v_pk_fma_f32 v[66:67], v[100:101], v[100:101], v[66:67] op_sel:[0,0,1] op_sel_hi:[1,0,0] neg_lo:[0,0,1]
	s_nop 0
	v_pk_mul_f32 v[64:65], v[66:67], v[100:101] op_sel:[0,1] op_sel_hi:[1,1]
	v_pk_mul_f32 v[102:103], v[66:67], v[66:67] op_sel:[0,1] op_sel_hi:[1,1]
	v_pk_fma_f32 v[64:65], v[66:67], v[100:101], v[64:65] op_sel:[0,0,1] op_sel_hi:[1,0,0] neg_lo:[0,0,1]
	v_pk_fma_f32 v[102:103], v[66:67], v[66:67], v[102:103] op_sel:[0,0,1] op_sel_hi:[1,0,0] neg_lo:[0,0,1]
	s_nop 0
	v_pk_mul_f32 v[104:105], v[102:103], v[100:101] op_sel:[0,1] op_sel_hi:[1,1]
	v_pk_mul_f32 v[106:107], v[102:103], v[66:67] op_sel:[0,1] op_sel_hi:[1,1]
	v_pk_mul_f32 v[108:109], v[102:103], v[64:65] op_sel:[0,1] op_sel_hi:[1,1]
	v_pk_fma_f32 v[104:105], v[102:103], v[100:101], v[104:105] op_sel:[0,0,1] op_sel_hi:[1,0,0] neg_lo:[0,0,1]
	v_pk_fma_f32 v[106:107], v[102:103], v[66:67], v[106:107] op_sel:[0,0,1] op_sel_hi:[1,0,0] neg_lo:[0,0,1]
	v_pk_fma_f32 v[108:109], v[102:103], v[64:65], v[108:109] op_sel:[0,0,1] op_sel_hi:[1,0,0] neg_lo:[0,0,1]
	v_pk_mul_f32 v[110:111], v[102:103], v[102:103] op_sel:[0,1] op_sel_hi:[1,1]
	s_nop 0
	v_pk_fma_f32 v[110:111], v[102:103], v[102:103], v[110:111] op_sel:[0,0,1] op_sel_hi:[1,0,0] neg_lo:[0,0,1]
	s_nop 0
	v_pk_mul_f32 v[112:113], v[110:111], v[100:101] op_sel:[0,1] op_sel_hi:[1,1]
	v_pk_mul_f32 v[114:115], v[110:111], v[66:67] op_sel:[0,1] op_sel_hi:[1,1]
	v_pk_mul_f32 v[116:117], v[110:111], v[64:65] op_sel:[0,1] op_sel_hi:[1,1]
	v_pk_fma_f32 v[112:113], v[110:111], v[100:101], v[112:113] op_sel:[0,0,1] op_sel_hi:[1,0,0] neg_lo:[0,0,1]
	v_pk_fma_f32 v[114:115], v[110:111], v[66:67], v[114:115] op_sel:[0,0,1] op_sel_hi:[1,0,0] neg_lo:[0,0,1]
	v_pk_fma_f32 v[116:117], v[110:111], v[64:65], v[116:117] op_sel:[0,0,1] op_sel_hi:[1,0,0] neg_lo:[0,0,1]
	v_pk_mul_f32 v[118:119], v[110:111], v[102:103] op_sel:[0,1] op_sel_hi:[1,1]
	v_pk_mul_f32 v[120:121], v[110:111], v[104:105] op_sel:[0,1] op_sel_hi:[1,1]
	v_pk_mul_f32 v[122:123], v[110:111], v[106:107] op_sel:[0,1] op_sel_hi:[1,1]
	v_pk_fma_f32 v[118:119], v[110:111], v[102:103], v[118:119] op_sel:[0,0,1] op_sel_hi:[1,0,0] neg_lo:[0,0,1]
	v_pk_fma_f32 v[120:121], v[110:111], v[104:105], v[120:121] op_sel:[0,0,1] op_sel_hi:[1,0,0] neg_lo:[0,0,1]
	v_pk_fma_f32 v[122:123], v[110:111], v[106:107], v[122:123] op_sel:[0,0,1] op_sel_hi:[1,0,0] neg_lo:[0,0,1]
	v_pk_mul_f32 v[124:125], v[110:111], v[108:109] op_sel:[0,1] op_sel_hi:[1,1]
	s_nop 0
	v_pk_fma_f32 v[124:125], v[110:111], v[108:109], v[124:125] op_sel:[0,0,1] op_sel_hi:[1,0,0] neg_lo:[0,0,1]
	s_waitcnt lgkmcnt(14)
	v_pk_add_f32 v[126:127], v[68:69], v[70:71]
	s_waitcnt lgkmcnt(12)
	v_pk_add_f32 v[170:171], v[72:73], v[74:75]
	s_waitcnt lgkmcnt(10)
	v_pk_add_f32 v[172:173], v[76:77], v[78:79]
	s_waitcnt lgkmcnt(8)
	v_pk_add_f32 v[174:175], v[80:81], v[82:83]
	v_pk_add_f32 v[68:69], v[68:69], v[70:71] neg_lo:[0,1] neg_hi:[0,1]
	v_pk_add_f32 v[72:73], v[72:73], v[74:75] neg_lo:[0,1] neg_hi:[0,1]
	v_pk_add_f32 v[76:77], v[76:77], v[78:79] neg_lo:[0,1] neg_hi:[0,1]
	v_pk_add_f32 v[80:81], v[80:81], v[82:83] neg_lo:[0,1] neg_hi:[0,1]
	s_waitcnt lgkmcnt(6)
	v_pk_add_f32 v[82:83], v[84:85], v[86:87]
	s_waitcnt lgkmcnt(4)
	v_pk_add_f32 v[78:79], v[88:89], v[90:91]
	s_waitcnt lgkmcnt(2)
	v_pk_add_f32 v[74:75], v[92:93], v[94:95]
	s_waitcnt lgkmcnt(0)
; __device__ __forceinline__ f32x2 cmul(f32x2 a, f32x2 b) { return (f32x2){a.x * b.x - a.y * b.y, a.x * b.y + a.y * b.x}; }
; template <bool INV> __device__ __forceinline__ void dft16(f32x2 (&x)[16]) {
; #pragma unroll
;     for (int b = 0; b < 4; ++b) r4<INV>(x[b], x[4 + b], x[8 + b], x[12 + b]);
;     const float sg = INV ? -1.f : 1.f;
;     const f32x2 W1 = {0.92387953251f, -0.38268343236f * sg}, W2 = {0.70710678118f, -0.70710678118f * sg}, W3 = {0.38268343236f, -0.92387953251f * sg},
;                 W4 = {0.f, -1.f * sg}, W6 = {-0.70710678118f, -0.70710678118f * sg}, W9 = {-0.92387953251f, 0.38268343236f * sg};
;     x[5] = cmul(x[5], W1); x[9] = cmul(x[9], W2); x[13] = cmul(x[13], W3);
;     x[6] = cmul(x[6], W2); x[10] = cmul(x[10], W4); x[14] = cmul(x[14], W6);
;     x[7] = cmul(x[7], W3); x[11] = cmul(x[11], W6); x[15] = cmul(x[15], W9);
; #pragma unroll
;     for (int c = 0; c < 4; ++c) r4<INV>(x[4 * c], x[4 * c + 1], x[4 * c + 2], x[4 * c + 3]);
; }
	v_pk_add_f32 v[70:71], v[96:97], v[98:99]
	v_pk_add_f32 v[86:87], v[84:85], v[86:87] neg_lo:[0,1] neg_hi:[0,1]
	v_pk_add_f32 v[90:91], v[88:89], v[90:91] neg_lo:[0,1] neg_hi:[0,1]
	v_pk_add_f32 v[94:95], v[92:93], v[94:95] neg_lo:[0,1] neg_hi:[0,1]
	v_pk_add_f32 v[98:99], v[96:97], v[98:99] neg_lo:[0,1] neg_hi:[0,1]
	v_pk_add_f32 v[96:97], v[126:127], v[82:83]
	v_pk_add_f32 v[92:93], v[170:171], v[78:79]
	v_pk_add_f32 v[88:89], v[172:173], v[74:75]
	v_pk_add_f32 v[84:85], v[174:175], v[70:71]
	v_pk_add_f32 v[126:127], v[126:127], v[82:83] neg_lo:[0,1] neg_hi:[0,1]
	v_pk_add_f32 v[78:79], v[170:171], v[78:79] neg_lo:[0,1] neg_hi:[0,1]
	v_pk_add_f32 v[172:173], v[172:173], v[74:75] neg_lo:[0,1] neg_hi:[0,1]
	v_pk_add_f32 v[70:71], v[174:175], v[70:71] neg_lo:[0,1] neg_hi:[0,1]
	v_pk_add_f32 v[174:175], v[68:69], v[86:87] op_sel:[0,1] op_sel_hi:[1,0] neg_hi:[0,1]
	v_pk_add_f32 v[74:75], v[72:73], v[90:91] op_sel:[0,1] op_sel_hi:[1,0] neg_hi:[0,1]
	v_pk_add_f32 v[170:171], v[76:77], v[94:95] op_sel:[0,1] op_sel_hi:[1,0] neg_hi:[0,1]
	v_pk_add_f32 v[82:83], v[80:81], v[98:99] op_sel:[0,1] op_sel_hi:[1,0] neg_hi:[0,1]
	v_pk_add_f32 v[68:69], v[68:69], v[86:87] op_sel:[0,1] op_sel_hi:[1,0] neg_lo:[0,1]
	v_pk_add_f32 v[90:91], v[72:73], v[90:91] op_sel:[0,1] op_sel_hi:[1,0] neg_lo:[0,1]
	v_pk_add_f32 v[94:95], v[76:77], v[94:95] op_sel:[0,1] op_sel_hi:[1,0] neg_lo:[0,1]
	v_pk_add_f32 v[98:99], v[80:81], v[98:99] op_sel:[0,1] op_sel_hi:[1,0] neg_lo:[0,1]
	v_pk_add_f32 v[80:81], v[96:97], v[88:89]
	v_pk_mul_f32 v[76:77], v[74:75], s[70:71] op_sel_hi:[1,0]
	v_pk_mul_f32 v[72:73], v[78:79], s[72:73] op_sel_hi:[1,0]
	v_pk_mul_f32 v[86:87], v[90:91], s[64:65] op_sel_hi:[1,0]
	v_pk_add_f32 v[88:89], v[96:97], v[88:89] neg_lo:[0,1] neg_hi:[0,1]
	v_pk_fma_f32 v[76:77], v[74:75], s[44:45], v[76:77] op_sel:[0,0,1] op_sel_hi:[1,0,0] neg_lo:[0,0,1]
	v_pk_fma_f32 v[72:73], v[78:79], s[76:77], v[72:73] op_sel:[0,0,1] op_sel_hi:[1,0,0] neg_lo:[0,0,1]
	v_pk_fma_f32 v[90:91], v[90:91], s[82:83], v[86:87] op_sel:[0,0,1] op_sel_hi:[1,0,0] neg_lo:[0,0,1]
	v_pk_add_f32 v[86:87], v[92:93], v[84:85]
	v_pk_fma_f32 v[78:79], v[170:171], s[72:73], v[174:175] op_sel:[0,0,1] op_sel_hi:[1,0,0] neg_hi:[0,0,1]
	v_pk_add_f32 v[74:75], v[126:127], v[172:173] op_sel:[0,1] op_sel_hi:[1,0] neg_hi:[0,1]
	v_pk_fma_f32 v[96:97], v[94:95], s[72:73], v[68:69] op_sel:[0,0,1] op_sel_hi:[1,0,0] neg_hi:[0,0,1]
	v_pk_add_f32 v[92:93], v[92:93], v[84:85] neg_lo:[0,1] neg_hi:[0,1]
	v_pk_fma_f32 v[170:171], v[170:171], s[76:77], v[78:79] op_sel:[0,0,1] op_sel_hi:[1,0,0] neg_lo:[0,0,1]
	v_pk_add_f32 v[172:173], v[126:127], v[172:173] op_sel:[0,1] op_sel_hi:[1,0] neg_lo:[0,1]
	v_pk_fma_f32 v[94:95], v[94:95], s[72:73], v[96:97] op_sel:[0,0,1] op_sel_hi:[1,0,0] neg_lo:[0,0,1]
	v_pk_add_f32 v[96:97], v[80:81], v[86:87]
	v_pk_fma_f32 v[174:175], v[174:175], s[100:101], v[170:171] op_sel_hi:[1,0,1] neg_lo:[0,0,1] neg_hi:[0,0,1]
	v_pk_fma_f32 v[126:127], v[70:71], s[72:73], v[72:73] op_sel:[0,0,1] op_sel_hi:[1,0,0] neg_hi:[0,0,1]
	v_pk_fma_f32 v[68:69], v[68:69], s[100:101], v[94:95] op_sel_hi:[1,0,1] neg_lo:[0,0,1] neg_hi:[0,0,1]
	v_pk_add_f32 v[86:87], v[80:81], v[86:87] neg_lo:[0,1] neg_hi:[0,1]
	v_pk_fma_f32 v[80:81], v[82:83], s[64:65], v[76:77] op_sel:[0,0,1] op_sel_hi:[1,0,0] neg_hi:[0,0,1]
	v_pk_fma_f32 v[126:127], v[70:71], s[72:73], v[126:127] op_sel:[0,0,1] op_sel_hi:[1,0,0] neg_lo:[0,0,1]
	v_pk_fma_f32 v[70:71], v[98:99], s[82:83], v[90:91] op_sel:[0,0,1] op_sel_hi:[1,0,0] neg_hi:[0,0,1]
	v_pk_add_f32 v[78:79], v[88:89], v[92:93] op_sel:[0,1] op_sel_hi:[1,0] neg_hi:[0,1]
	v_pk_fma_f32 v[82:83], v[82:83], s[82:83], v[80:81] op_sel:[0,0,1] op_sel_hi:[1,0,0] neg_lo:[0,0,1]
	v_pk_fma_f32 v[72:73], v[72:73], s[100:101], v[126:127] op_sel_hi:[1,0,1] neg_lo:[0,0,1] neg_hi:[0,0,1]
	v_pk_fma_f32 v[98:99], v[98:99], s[64:65], v[70:71] op_sel:[0,0,1] op_sel_hi:[1,0,0] neg_lo:[0,0,1]
	v_pk_add_f32 v[92:93], v[88:89], v[92:93] op_sel:[0,1] op_sel_hi:[1,0] neg_lo:[0,1]
	v_pk_fma_f32 v[76:77], v[76:77], s[100:101], v[82:83] op_sel_hi:[1,0,1] neg_lo:[0,0,1] neg_hi:[0,0,1]
	v_pk_add_f32 v[88:89], v[74:75], v[126:127]
	v_pk_fma_f32 v[90:91], v[90:91], s[100:101], v[98:99] op_sel_hi:[1,0,1] neg_lo:[0,0,1] neg_hi:[0,0,1]
	v_pk_add_f32 v[70:71], v[170:171], v[82:83]
	v_pk_add_f32 v[74:75], v[74:75], v[126:127] neg_lo:[0,1] neg_hi:[0,1]
	v_pk_add_f32 v[126:127], v[94:95], v[98:99]
	v_pk_add_f32 v[82:83], v[170:171], v[82:83] neg_lo:[0,1] neg_hi:[0,1]
	v_pk_add_f32 v[170:171], v[172:173], v[72:73] op_sel:[0,1] op_sel_hi:[1,0] neg_hi:[0,1]
	v_pk_add_f32 v[94:95], v[94:95], v[98:99] neg_lo:[0,1] neg_hi:[0,1]
	v_pk_add_f32 v[98:99], v[174:175], v[76:77] op_sel:[0,1] op_sel_hi:[1,0] neg_hi:[0,1]
	v_pk_add_f32 v[72:73], v[172:173], v[72:73] op_sel:[0,1] op_sel_hi:[1,0] neg_lo:[0,1]
	v_pk_add_f32 v[172:173], v[68:69], v[90:91] op_sel:[0,1] op_sel_hi:[1,0] neg_hi:[0,1]
	v_pk_add_f32 v[174:175], v[174:175], v[76:77] op_sel:[0,1] op_sel_hi:[1,0] neg_lo:[0,1]
	v_pk_add_f32 v[90:91], v[68:69], v[90:91] op_sel:[0,1] op_sel_hi:[1,0] neg_lo:[0,1]
	v_pk_mul_f32 v[68:69], v[70:71], v[100:101] op_sel:[0,1] op_sel_hi:[1,1]
	v_pk_mul_f32 v[76:77], v[88:89], v[66:67] op_sel:[0,1] op_sel_hi:[1,1]
	v_pk_fma_f32 v[100:101], v[70:71], v[100:101], v[68:69] op_sel:[0,0,1] op_sel_hi:[1,0,0] neg_lo:[0,0,1]
	v_pk_mul_f32 v[68:69], v[126:127], v[64:65] op_sel:[0,1] op_sel_hi:[1,1]
	v_pk_fma_f32 v[88:89], v[88:89], v[66:67], v[76:77] op_sel:[0,0,1] op_sel_hi:[1,0,0] neg_lo:[0,0,1]
	v_pk_mul_f32 v[76:77], v[78:79], v[102:103] op_sel:[0,1] op_sel_hi:[1,1]
	v_pk_fma_f32 v[126:127], v[126:127], v[64:65], v[68:69] op_sel:[0,0,1] op_sel_hi:[1,0,0] neg_lo:[0,0,1]
; #define LAS __attribute__((address_space(3)))
; __device__ __forceinline__ f32x2 cmul(f32x2 a, f32x2 b) { return (f32x2){a.x * b.x - a.y * b.y, a.x * b.y + a.y * b.x}; }
; template <bool INV> __device__ __forceinline__ void bfly16(f32x2 (&x)[16], const LAS f32x2* TH, const LAS f32x2* TL, int tw) {
;     ...
;     if (!INV) { f32x2 p = W;
; #pragma unroll
;         for (int r = 1; r < 16; ++r) { x[4 * (r & 3) + (r >> 2)] = cmul(x[4 * (r & 3) + (r >> 2)], p); if (r < 15) p = cmul(p, W); } }
; }
; template <bool INV> __device__ __forceinline__ void bfly16_tab(f32x2 (&x)[16], const LAS f32x2* T, int tstride, int j) {
;     if (INV) {
; #pragma unroll
;         for (int q = 1; q < 16; ++q) { f32x2 p = T[q * tstride + j]; p.y = -p.y; x[q] = cmul(x[q], p); } }
;     dft16<INV>(x);
;     if (!INV) {
; #pragma unroll
;         for (int r = 1; r < 16; ++r) { const f32x2 p = T[r * tstride + j]; x[4 * (r & 3) + (r >> 2)] = cmul(x[4 * (r & 3) + (r >> 2)], p); } }
; }
; template <bool INV> __device__ __forceinline__ void pass16_s64(LAS f32x2* X, const LAS f32x2* TH, int base, int j) {
;     f32x2 x[16];
; #pragma unroll
;     for (int q = 0; q < 16; ++q) x[q] = X[base + q * 68];
;     bfly16_tab<INV>(x, TH - 2048, 64, j);
; #pragma unroll
;     for (int c = 0; c < 4; ++c)
; #pragma unroll
;         for (int d = 0; d < 4; ++d) X[base + (c + 4 * d) * 68] = x[4 * c + d];
; }
	v_pk_mul_f32 v[68:69], v[98:99], v[104:105] op_sel:[0,1] op_sel_hi:[1,1]
	v_pk_fma_f32 v[76:77], v[78:79], v[102:103], v[76:77] op_sel:[0,0,1] op_sel_hi:[1,0,0] neg_lo:[0,0,1]
	v_pk_mul_f32 v[78:79], v[170:171], v[106:107] op_sel:[0,1] op_sel_hi:[1,1]
	v_pk_fma_f32 v[98:99], v[98:99], v[104:105], v[68:69] op_sel:[0,0,1] op_sel_hi:[1,0,0] neg_lo:[0,0,1]
	v_pk_mul_f32 v[68:69], v[172:173], v[108:109] op_sel:[0,1] op_sel_hi:[1,1]
	v_pk_fma_f32 v[106:107], v[170:171], v[106:107], v[78:79] op_sel:[0,0,1] op_sel_hi:[1,0,0] neg_lo:[0,0,1]
	v_pk_mul_f32 v[78:79], v[86:87], v[110:111] op_sel:[0,1] op_sel_hi:[1,1]
	v_pk_fma_f32 v[108:109], v[172:173], v[108:109], v[68:69] op_sel:[0,0,1] op_sel_hi:[1,0,0] neg_lo:[0,0,1]
	v_pk_mul_f32 v[68:69], v[82:83], v[112:113] op_sel:[0,1] op_sel_hi:[1,1]
	v_pk_fma_f32 v[78:79], v[86:87], v[110:111], v[78:79] op_sel:[0,0,1] op_sel_hi:[1,0,0] neg_lo:[0,0,1]
	v_pk_mul_f32 v[110:111], v[74:75], v[114:115] op_sel:[0,1] op_sel_hi:[1,1]
	v_pk_fma_f32 v[68:69], v[82:83], v[112:113], v[68:69] op_sel:[0,0,1] op_sel_hi:[1,0,0] neg_lo:[0,0,1]
	v_pk_mul_f32 v[112:113], v[94:95], v[116:117] op_sel:[0,1] op_sel_hi:[1,1]
	v_pk_fma_f32 v[114:115], v[74:75], v[114:115], v[110:111] op_sel:[0,0,1] op_sel_hi:[1,0,0] neg_lo:[0,0,1]
	v_pk_mul_f32 v[110:111], v[92:93], v[118:119] op_sel:[0,1] op_sel_hi:[1,1]
	v_pk_fma_f32 v[116:117], v[94:95], v[116:117], v[112:113] op_sel:[0,0,1] op_sel_hi:[1,0,0] neg_lo:[0,0,1]
	v_pk_mul_f32 v[94:95], v[174:175], v[120:121] op_sel:[0,1] op_sel_hi:[1,1]
	v_pk_fma_f32 v[110:111], v[92:93], v[118:119], v[110:111] op_sel:[0,0,1] op_sel_hi:[1,0,0] neg_lo:[0,0,1]
	v_pk_mul_f32 v[118:119], v[72:73], v[122:123] op_sel:[0,1] op_sel_hi:[1,1]
	v_pk_fma_f32 v[174:175], v[174:175], v[120:121], v[94:95] op_sel:[0,0,1] op_sel_hi:[1,0,0] neg_lo:[0,0,1]
	v_pk_mul_f32 v[94:95], v[90:91], v[124:125] op_sel:[0,1] op_sel_hi:[1,1]
	v_pk_fma_f32 v[72:73], v[72:73], v[122:123], v[118:119] op_sel:[0,0,1] op_sel_hi:[1,0,0] neg_lo:[0,0,1]
	v_pk_fma_f32 v[90:91], v[90:91], v[124:125], v[94:95] op_sel:[0,0,1] op_sel_hi:[1,0,0] neg_lo:[0,0,1]
	ds_write_b64 v151, v[96:97] offset:0
	ds_write_b64 v151, v[100:101] offset:8704
	ds_write_b64 v151, v[88:89] offset:17408
	ds_write_b64 v151, v[126:127] offset:26112
	ds_write_b64 v151, v[76:77] offset:34816
	ds_write_b64 v151, v[98:99] offset:43520
	ds_write_b64 v151, v[106:107] offset:52224
	ds_write_b64 v151, v[108:109] offset:60928
	ds_write_b64 v176, v[78:79] offset:0
	ds_write_b64 v176, v[68:69] offset:8704
	ds_write_b64 v176, v[114:115] offset:17408
	ds_write_b64 v176, v[116:117] offset:26112
	ds_write_b64 v176, v[110:111] offset:34816
	ds_write_b64 v176, v[174:175] offset:43520
	ds_write_b64 v176, v[72:73] offset:52224
	ds_write_b64 v176, v[90:91] offset:60928
	s_cbranch_scc1 .LBB0_846
	s_waitcnt lgkmcnt(0)
	s_barrier
	s_mov_b32 s0, 0
	s_mov_b64 s[12:13], -1
	ds_read2st64_b64 v[232:235], v139 offset0:1 offset1:2
	ds_read2st64_b64 v[208:211], v139 offset0:3 offset1:4
	ds_read2st64_b64 v[204:207], v139 offset0:5 offset1:6
	ds_read2st64_b64 v[200:203], v139 offset0:7 offset1:8
	ds_read2st64_b64 v[196:199], v139 offset0:9 offset1:10
	ds_read2st64_b64 v[192:195], v139 offset0:11 offset1:12
	ds_read2st64_b64 v[188:191], v139 offset0:13 offset1:14
	ds_read_b64 v[186:187], v139 offset:7680
.LBB0_848:
	v_add_u32_e32 v128, s0, v140
	v_lshrrev_b32_e32 v147, 6, v128
	v_mad_u32_u24 v151, v147, s77, v142
	ds_read_b64 v[64:65], v151 offset:0
	ds_read_b64 v[66:67], v151 offset:4352
	ds_read_b64 v[68:69], v151 offset:544
	ds_read_b64 v[70:71], v151 offset:4896
	ds_read_b64 v[72:73], v151 offset:1088
	ds_read_b64 v[74:75], v151 offset:5440
	ds_read_b64 v[76:77], v151 offset:1632
	ds_read_b64 v[78:79], v151 offset:5984
	ds_read_b64 v[80:81], v151 offset:2176
	ds_read_b64 v[82:83], v151 offset:6528
	ds_read_b64 v[84:85], v151 offset:2720
	ds_read_b64 v[86:87], v151 offset:7072
	ds_read_b64 v[88:89], v151 offset:3264
	ds_read_b64 v[90:91], v151 offset:7616
	ds_read_b64 v[92:93], v151 offset:3808
	ds_read_b64 v[94:95], v151 offset:8160
	s_cmp_eq_u32 s0, 0
	s_movk_i32 s0, 0x200
	s_mov_b64 s[12:13], 0
	s_waitcnt lgkmcnt(14)
	v_pk_add_f32 v[96:97], v[64:65], v[66:67]
	s_waitcnt lgkmcnt(12)
	v_pk_add_f32 v[98:99], v[68:69], v[70:71]
	s_waitcnt lgkmcnt(10)
	v_pk_add_f32 v[100:101], v[72:73], v[74:75]
	s_waitcnt lgkmcnt(8)
	v_pk_add_f32 v[102:103], v[76:77], v[78:79]
	v_pk_add_f32 v[66:67], v[64:65], v[66:67] neg_lo:[0,1] neg_hi:[0,1]
	v_pk_add_f32 v[68:69], v[68:69], v[70:71] neg_lo:[0,1] neg_hi:[0,1]
	v_pk_add_f32 v[74:75], v[72:73], v[74:75] neg_lo:[0,1] neg_hi:[0,1]
	v_pk_add_f32 v[78:79], v[76:77], v[78:79] neg_lo:[0,1] neg_hi:[0,1]
	s_waitcnt lgkmcnt(6)
	v_pk_add_f32 v[76:77], v[80:81], v[82:83]
	s_waitcnt lgkmcnt(4)
	v_pk_add_f32 v[72:73], v[84:85], v[86:87]
	s_waitcnt lgkmcnt(2)
	v_pk_add_f32 v[70:71], v[88:89], v[90:91]
	s_waitcnt lgkmcnt(0)
; __device__ __forceinline__ f32x2 cmul(f32x2 a, f32x2 b) { return (f32x2){a.x * b.x - a.y * b.y, a.x * b.y + a.y * b.x}; }
; template <bool INV> __device__ __forceinline__ void dft16(f32x2 (&x)[16]) {
; #pragma unroll
;     for (int b = 0; b < 4; ++b) r4<INV>(x[b], x[4 + b], x[8 + b], x[12 + b]);
;     const float sg = INV ? -1.f : 1.f;
;     const f32x2 W1 = {0.92387953251f, -0.38268343236f * sg}, W2 = {0.70710678118f, -0.70710678118f * sg}, W3 = {0.38268343236f, -0.92387953251f * sg},
;                 W4 = {0.f, -1.f * sg}, W6 = {-0.70710678118f, -0.70710678118f * sg}, W9 = {-0.92387953251f, 0.38268343236f * sg};
;     x[5] = cmul(x[5], W1); x[9] = cmul(x[9], W2); x[13] = cmul(x[13], W3);
;     x[6] = cmul(x[6], W2); x[10] = cmul(x[10], W4); x[14] = cmul(x[14], W6);
;     x[7] = cmul(x[7], W3); x[11] = cmul(x[11], W6); x[15] = cmul(x[15], W9);
; #pragma unroll
;     for (int c = 0; c < 4; ++c) r4<INV>(x[4 * c], x[4 * c + 1], x[4 * c + 2], x[4 * c + 3]);
; }
	v_pk_add_f32 v[64:65], v[92:93], v[94:95]
	v_pk_add_f32 v[80:81], v[80:81], v[82:83] neg_lo:[0,1] neg_hi:[0,1]
	v_pk_add_f32 v[84:85], v[84:85], v[86:87] neg_lo:[0,1] neg_hi:[0,1]
	v_pk_add_f32 v[90:91], v[88:89], v[90:91] neg_lo:[0,1] neg_hi:[0,1]
	v_pk_add_f32 v[92:93], v[92:93], v[94:95] neg_lo:[0,1] neg_hi:[0,1]
	v_pk_add_f32 v[94:95], v[96:97], v[76:77]
	v_pk_add_f32 v[88:89], v[98:99], v[72:73]
	v_pk_add_f32 v[86:87], v[100:101], v[70:71]
	v_pk_add_f32 v[82:83], v[102:103], v[64:65]
	v_pk_add_f32 v[76:77], v[96:97], v[76:77] neg_lo:[0,1] neg_hi:[0,1]
	v_pk_add_f32 v[98:99], v[98:99], v[72:73] neg_lo:[0,1] neg_hi:[0,1]
	v_pk_add_f32 v[100:101], v[100:101], v[70:71] neg_lo:[0,1] neg_hi:[0,1]
	v_pk_add_f32 v[102:103], v[102:103], v[64:65] neg_lo:[0,1] neg_hi:[0,1]
	v_pk_add_f32 v[64:65], v[66:67], v[80:81] op_sel:[0,1] op_sel_hi:[1,0] neg_hi:[0,1]
	v_pk_add_f32 v[70:71], v[68:69], v[84:85] op_sel:[0,1] op_sel_hi:[1,0] neg_hi:[0,1]
	v_pk_add_f32 v[72:73], v[74:75], v[90:91] op_sel:[0,1] op_sel_hi:[1,0] neg_hi:[0,1]
	v_pk_add_f32 v[96:97], v[78:79], v[92:93] op_sel:[0,1] op_sel_hi:[1,0] neg_hi:[0,1]
	v_pk_add_f32 v[80:81], v[66:67], v[80:81] op_sel:[0,1] op_sel_hi:[1,0] neg_lo:[0,1]
	v_pk_add_f32 v[68:69], v[68:69], v[84:85] op_sel:[0,1] op_sel_hi:[1,0] neg_lo:[0,1]
	v_pk_add_f32 v[90:91], v[74:75], v[90:91] op_sel:[0,1] op_sel_hi:[1,0] neg_lo:[0,1]
	v_pk_add_f32 v[92:93], v[78:79], v[92:93] op_sel:[0,1] op_sel_hi:[1,0] neg_lo:[0,1]
	v_pk_add_f32 v[78:79], v[94:95], v[86:87]
	v_pk_mul_f32 v[74:75], v[70:71], s[70:71] op_sel_hi:[1,0]
	v_pk_mul_f32 v[84:85], v[98:99], s[72:73] op_sel_hi:[1,0]
	v_pk_mul_f32 v[66:67], v[68:69], s[64:65] op_sel_hi:[1,0]
	v_pk_add_f32 v[86:87], v[94:95], v[86:87] neg_lo:[0,1] neg_hi:[0,1]
	v_pk_fma_f32 v[74:75], v[70:71], s[44:45], v[74:75] op_sel:[0,0,1] op_sel_hi:[1,0,0] neg_lo:[0,0,1]
	v_pk_fma_f32 v[84:85], v[98:99], s[76:77], v[84:85] op_sel:[0,0,1] op_sel_hi:[1,0,0] neg_lo:[0,0,1]
	v_pk_fma_f32 v[66:67], v[68:69], s[82:83], v[66:67] op_sel:[0,0,1] op_sel_hi:[1,0,0] neg_lo:[0,0,1]
	v_pk_add_f32 v[68:69], v[88:89], v[82:83]
	v_pk_fma_f32 v[98:99], v[72:73], s[72:73], v[64:65] op_sel:[0,0,1] op_sel_hi:[1,0,0] neg_hi:[0,0,1]
	v_pk_add_f32 v[70:71], v[76:77], v[100:101] op_sel:[0,1] op_sel_hi:[1,0] neg_hi:[0,1]
	v_pk_fma_f32 v[94:95], v[90:91], s[72:73], v[80:81] op_sel:[0,0,1] op_sel_hi:[1,0,0] neg_hi:[0,0,1]
	v_pk_add_f32 v[82:83], v[88:89], v[82:83] neg_lo:[0,1] neg_hi:[0,1]
	v_pk_fma_f32 v[72:73], v[72:73], s[76:77], v[98:99] op_sel:[0,0,1] op_sel_hi:[1,0,0] neg_lo:[0,0,1]
	v_pk_add_f32 v[100:101], v[76:77], v[100:101] op_sel:[0,1] op_sel_hi:[1,0] neg_lo:[0,1]
	v_pk_fma_f32 v[90:91], v[90:91], s[72:73], v[94:95] op_sel:[0,0,1] op_sel_hi:[1,0,0] neg_lo:[0,0,1]
	v_pk_add_f32 v[94:95], v[78:79], v[68:69]
	v_pk_fma_f32 v[64:65], v[64:65], s[100:101], v[72:73] op_sel_hi:[1,0,1] neg_lo:[0,0,1] neg_hi:[0,0,1]
	v_pk_fma_f32 v[76:77], v[102:103], s[72:73], v[84:85] op_sel:[0,0,1] op_sel_hi:[1,0,0] neg_hi:[0,0,1]
	v_pk_fma_f32 v[80:81], v[80:81], s[100:101], v[90:91] op_sel_hi:[1,0,1] neg_lo:[0,0,1] neg_hi:[0,0,1]
	v_pk_add_f32 v[68:69], v[78:79], v[68:69] neg_lo:[0,1] neg_hi:[0,1]
	v_pk_fma_f32 v[78:79], v[96:97], s[64:65], v[74:75] op_sel:[0,0,1] op_sel_hi:[1,0,0] neg_hi:[0,0,1]
	v_pk_fma_f32 v[76:77], v[102:103], s[72:73], v[76:77] op_sel:[0,0,1] op_sel_hi:[1,0,0] neg_lo:[0,0,1]
	v_pk_fma_f32 v[102:103], v[92:93], s[82:83], v[66:67] op_sel:[0,0,1] op_sel_hi:[1,0,0] neg_hi:[0,0,1]
	v_pk_add_f32 v[98:99], v[86:87], v[82:83] op_sel:[0,1] op_sel_hi:[1,0] neg_hi:[0,1]
	v_pk_fma_f32 v[78:79], v[96:97], s[82:83], v[78:79] op_sel:[0,0,1] op_sel_hi:[1,0,0] neg_lo:[0,0,1]
	v_pk_fma_f32 v[84:85], v[84:85], s[100:101], v[76:77] op_sel_hi:[1,0,1] neg_lo:[0,0,1] neg_hi:[0,0,1]
	v_pk_fma_f32 v[102:103], v[92:93], s[64:65], v[102:103] op_sel:[0,0,1] op_sel_hi:[1,0,0] neg_lo:[0,0,1]
	v_pk_add_f32 v[82:83], v[86:87], v[82:83] op_sel:[0,1] op_sel_hi:[1,0] neg_lo:[0,1]
	v_pk_fma_f32 v[74:75], v[74:75], s[100:101], v[78:79] op_sel_hi:[1,0,1] neg_lo:[0,0,1] neg_hi:[0,0,1]
	v_pk_add_f32 v[86:87], v[70:71], v[76:77]
	v_pk_fma_f32 v[66:67], v[66:67], s[100:101], v[102:103] op_sel_hi:[1,0,1] neg_lo:[0,0,1] neg_hi:[0,0,1]
	v_pk_add_f32 v[92:93], v[72:73], v[78:79]
	v_pk_add_f32 v[76:77], v[70:71], v[76:77] neg_lo:[0,1] neg_hi:[0,1]
	v_pk_add_f32 v[70:71], v[90:91], v[102:103]
	v_pk_add_f32 v[78:79], v[72:73], v[78:79] neg_lo:[0,1] neg_hi:[0,1]
	v_pk_add_f32 v[72:73], v[100:101], v[84:85] op_sel:[0,1] op_sel_hi:[1,0] neg_hi:[0,1]
	v_pk_add_f32 v[90:91], v[90:91], v[102:103] neg_lo:[0,1] neg_hi:[0,1]
	v_pk_add_f32 v[102:103], v[64:65], v[74:75] op_sel:[0,1] op_sel_hi:[1,0] neg_hi:[0,1]
	v_pk_add_f32 v[100:101], v[100:101], v[84:85] op_sel:[0,1] op_sel_hi:[1,0] neg_lo:[0,1]
	v_pk_add_f32 v[84:85], v[80:81], v[66:67] op_sel:[0,1] op_sel_hi:[1,0] neg_hi:[0,1]
	v_pk_add_f32 v[74:75], v[64:65], v[74:75] op_sel:[0,1] op_sel_hi:[1,0] neg_lo:[0,1]
	v_pk_add_f32 v[66:67], v[80:81], v[66:67] op_sel:[0,1] op_sel_hi:[1,0] neg_lo:[0,1]
	v_pk_mul_f32 v[80:81], v[92:93], v[232:233] op_sel:[0,1] op_sel_hi:[1,1]
	v_pk_mul_f32 v[64:65], v[86:87], v[234:235] op_sel:[0,1] op_sel_hi:[1,1]
	v_pk_fma_f32 v[80:81], v[92:93], v[232:233], v[80:81] op_sel:[0,0,1] op_sel_hi:[1,0,0] neg_lo:[0,0,1]
	v_pk_mul_f32 v[92:93], v[70:71], v[208:209] op_sel:[0,1] op_sel_hi:[1,1]
	v_pk_fma_f32 v[64:65], v[86:87], v[234:235], v[64:65] op_sel:[0,0,1] op_sel_hi:[1,0,0] neg_lo:[0,0,1]
	v_pk_mul_f32 v[86:87], v[98:99], v[210:211] op_sel:[0,1] op_sel_hi:[1,1]
	v_pk_fma_f32 v[70:71], v[70:71], v[208:209], v[92:93] op_sel:[0,0,1] op_sel_hi:[1,0,0] neg_lo:[0,0,1]
; #define LAS __attribute__((address_space(3)))
; __device__ __forceinline__ f32x2 cmul(f32x2 a, f32x2 b) { return (f32x2){a.x * b.x - a.y * b.y, a.x * b.y + a.y * b.x}; }
; template <bool INV> __device__ __forceinline__ void bfly16_tab(f32x2 (&x)[16], const LAS f32x2* T, int tstride, int j) {
;     if (INV) {
; #pragma unroll
;         for (int q = 1; q < 16; ++q) { f32x2 p = T[q * tstride + j]; p.y = -p.y; x[q] = cmul(x[q], p); } }
;     dft16<INV>(x);
;     if (!INV) {
; #pragma unroll
;         for (int r = 1; r < 16; ++r) { const f32x2 p = T[r * tstride + j]; x[4 * (r & 3) + (r >> 2)] = cmul(x[4 * (r & 3) + (r >> 2)], p); } }
; }
; template <bool INV> __device__ __forceinline__ void pass16_s64(LAS f32x2* X, const LAS f32x2* TH, int base, int j) {
;     f32x2 x[16];
; #pragma unroll
;     for (int q = 0; q < 16; ++q) x[q] = X[base + q * 68];
;     bfly16_tab<INV>(x, TH - 2048, 64, j);
; #pragma unroll
;     for (int c = 0; c < 4; ++c)
; #pragma unroll
;         for (int d = 0; d < 4; ++d) X[base + (c + 4 * d) * 68] = x[4 * c + d];
; }
; template <bool INV> __device__ __forceinline__ void pass16(LAS f32x2* X, const LAS f32x2* TH, const LAS f32x2* TL, int base, int stride, int tw) {
;     f32x2 x[16];
; #pragma unroll
;     for (int q = 0; q < 16; ++q) x[q] = X[base + q * stride];
;     bfly16<INV>(x, TH, TL, tw);
; #pragma unroll
;     for (int c = 0; c < 4; ++c)
; #pragma unroll
;         for (int d = 0; d < 4; ++d) X[base + (c + 4 * d) * stride] = x[4 * c + d];
; }
; template <bool INV> __device__ __forceinline__ void pass16_s4(LAS f32x2* X, const LAS f32x2* TH, const LAS f32x2* TL, int tid) {
; #pragma unroll 1
;     for (int s = 0; s < 2; ++s) {
;         const int b = tid + NTHR * s, blk = b >> 2, jj = b & 3;
;         LAS f32x2* P = X + blk * 68 + jj;
;         f32x2 x[16];
; #pragma unroll
;         for (int q = 0; q < 16; ++q) x[q] = P[4 * q];
;         bfly16_tab<INV>(x, TH - 1024, 4, jj);
; #pragma unroll
;         for (int c = 0; c < 4; ++c)
; #pragma unroll
;             for (int d = 0; d < 4; ++d) P[4 * (c + 4 * d)] = x[4 * c + d];
;     }
; }
	v_pk_mul_f32 v[92:93], v[102:103], v[204:205] op_sel:[0,1] op_sel_hi:[1,1]
	v_pk_fma_f32 v[86:87], v[98:99], v[210:211], v[86:87] op_sel:[0,0,1] op_sel_hi:[1,0,0] neg_lo:[0,0,1]
	v_pk_mul_f32 v[98:99], v[72:73], v[206:207] op_sel:[0,1] op_sel_hi:[1,1]
	v_pk_fma_f32 v[92:93], v[102:103], v[204:205], v[92:93] op_sel:[0,0,1] op_sel_hi:[1,0,0] neg_lo:[0,0,1]
	v_pk_mul_f32 v[102:103], v[84:85], v[200:201] op_sel:[0,1] op_sel_hi:[1,1]
	v_pk_fma_f32 v[98:99], v[72:73], v[206:207], v[98:99] op_sel:[0,0,1] op_sel_hi:[1,0,0] neg_lo:[0,0,1]
	v_pk_mul_f32 v[72:73], v[68:69], v[202:203] op_sel:[0,1] op_sel_hi:[1,1]
	v_pk_fma_f32 v[102:103], v[84:85], v[200:201], v[102:103] op_sel:[0,0,1] op_sel_hi:[1,0,0] neg_lo:[0,0,1]
	v_pk_mul_f32 v[84:85], v[78:79], v[196:197] op_sel:[0,1] op_sel_hi:[1,1]
	v_pk_fma_f32 v[72:73], v[68:69], v[202:203], v[72:73] op_sel:[0,0,1] op_sel_hi:[1,0,0] neg_lo:[0,0,1]
	v_pk_mul_f32 v[68:69], v[76:77], v[198:199] op_sel:[0,1] op_sel_hi:[1,1]
	v_pk_fma_f32 v[78:79], v[78:79], v[196:197], v[84:85] op_sel:[0,0,1] op_sel_hi:[1,0,0] neg_lo:[0,0,1]
	v_pk_mul_f32 v[84:85], v[90:91], v[192:193] op_sel:[0,1] op_sel_hi:[1,1]
	v_pk_fma_f32 v[68:69], v[76:77], v[198:199], v[68:69] op_sel:[0,0,1] op_sel_hi:[1,0,0] neg_lo:[0,0,1]
	v_pk_mul_f32 v[76:77], v[82:83], v[194:195] op_sel:[0,1] op_sel_hi:[1,1]
	v_pk_fma_f32 v[90:91], v[90:91], v[192:193], v[84:85] op_sel:[0,0,1] op_sel_hi:[1,0,0] neg_lo:[0,0,1]
	v_pk_mul_f32 v[84:85], v[74:75], v[188:189] op_sel:[0,1] op_sel_hi:[1,1]
	v_pk_fma_f32 v[76:77], v[82:83], v[194:195], v[76:77] op_sel:[0,0,1] op_sel_hi:[1,0,0] neg_lo:[0,0,1]
	v_pk_mul_f32 v[82:83], v[100:101], v[190:191] op_sel:[0,1] op_sel_hi:[1,1]
	v_pk_fma_f32 v[74:75], v[74:75], v[188:189], v[84:85] op_sel:[0,0,1] op_sel_hi:[1,0,0] neg_lo:[0,0,1]
	v_pk_mul_f32 v[84:85], v[66:67], v[186:187] op_sel:[0,1] op_sel_hi:[1,1]
	v_pk_fma_f32 v[100:101], v[100:101], v[190:191], v[82:83] op_sel:[0,0,1] op_sel_hi:[1,0,0] neg_lo:[0,0,1]
	v_pk_fma_f32 v[66:67], v[66:67], v[186:187], v[84:85] op_sel:[0,0,1] op_sel_hi:[1,0,0] neg_lo:[0,0,1]
	ds_write_b64 v151, v[94:95] offset:0
	ds_write_b64 v151, v[80:81] offset:544
	ds_write_b64 v151, v[64:65] offset:1088
	ds_write_b64 v151, v[70:71] offset:1632
	ds_write_b64 v151, v[86:87] offset:2176
	ds_write_b64 v151, v[92:93] offset:2720
	ds_write_b64 v151, v[98:99] offset:3264
	ds_write_b64 v151, v[102:103] offset:3808
	ds_write_b64 v151, v[72:73] offset:4352
	ds_write_b64 v151, v[78:79] offset:4896
	ds_write_b64 v151, v[68:69] offset:5440
	ds_write_b64 v151, v[90:91] offset:5984
	ds_write_b64 v151, v[76:77] offset:6528
	ds_write_b64 v151, v[74:75] offset:7072
	ds_write_b64 v151, v[100:101] offset:7616
	ds_write_b64 v151, v[66:67] offset:8160
	s_cbranch_scc1 .LBB0_848
	s_waitcnt lgkmcnt(0)
	s_barrier
	s_mov_b32 s0, 0
	s_mov_b64 s[12:13], -1
	ds_read2_b64 v[232:235], v141 offset0:4 offset1:8
	ds_read2_b64 v[208:211], v141 offset0:12 offset1:16
	ds_read2_b64 v[204:207], v141 offset0:20 offset1:24
	ds_read2_b64 v[200:203], v141 offset0:28 offset1:32
	ds_read2_b64 v[196:199], v141 offset0:36 offset1:40
	ds_read2_b64 v[192:195], v141 offset0:44 offset1:48
	ds_read2_b64 v[188:191], v141 offset0:52 offset1:56
	ds_read_b64 v[186:187], v141 offset:480
.LBB0_850:
	v_add_u32_e32 v128, s0, v140
	v_lshrrev_b32_e32 v147, 2, v128
	v_mad_u32_u24 v151, v147, s43, v144
	ds_read_b64 v[64:65], v151 offset:0
	ds_read_b64 v[66:67], v151 offset:256
	ds_read_b64 v[68:69], v151 offset:32
	ds_read_b64 v[70:71], v151 offset:288
	ds_read_b64 v[72:73], v151 offset:64
	ds_read_b64 v[74:75], v151 offset:320
	ds_read_b64 v[76:77], v151 offset:96
	ds_read_b64 v[78:79], v151 offset:352
	ds_read_b64 v[80:81], v151 offset:128
	ds_read_b64 v[82:83], v151 offset:384
	ds_read_b64 v[84:85], v151 offset:160
	ds_read_b64 v[86:87], v151 offset:416
	ds_read_b64 v[88:89], v151 offset:192
	ds_read_b64 v[90:91], v151 offset:448
	ds_read_b64 v[92:93], v151 offset:224
	ds_read_b64 v[94:95], v151 offset:480
	s_cmp_eq_u32 s0, 0
	s_movk_i32 s0, 0x200
	s_mov_b64 s[12:13], 0
	s_waitcnt lgkmcnt(14)
	v_pk_add_f32 v[96:97], v[64:65], v[66:67]
	s_waitcnt lgkmcnt(12)
	v_pk_add_f32 v[98:99], v[68:69], v[70:71]
	s_waitcnt lgkmcnt(10)
	v_pk_add_f32 v[100:101], v[72:73], v[74:75]
	s_waitcnt lgkmcnt(8)
	v_pk_add_f32 v[102:103], v[76:77], v[78:79]
	v_pk_add_f32 v[66:67], v[64:65], v[66:67] neg_lo:[0,1] neg_hi:[0,1]
	v_pk_add_f32 v[68:69], v[68:69], v[70:71] neg_lo:[0,1] neg_hi:[0,1]
	v_pk_add_f32 v[72:73], v[72:73], v[74:75] neg_lo:[0,1] neg_hi:[0,1]
	v_pk_add_f32 v[78:79], v[76:77], v[78:79] neg_lo:[0,1] neg_hi:[0,1]
	s_waitcnt lgkmcnt(6)
	v_pk_add_f32 v[76:77], v[80:81], v[82:83]
	s_waitcnt lgkmcnt(4)
	v_pk_add_f32 v[74:75], v[84:85], v[86:87]
	s_waitcnt lgkmcnt(2)
	v_pk_add_f32 v[70:71], v[88:89], v[90:91]
	s_waitcnt lgkmcnt(0)
; __device__ __forceinline__ f32x2 cmul(f32x2 a, f32x2 b) { return (f32x2){a.x * b.x - a.y * b.y, a.x * b.y + a.y * b.x}; }
; template <bool INV> __device__ __forceinline__ void dft16(f32x2 (&x)[16]) {
; #pragma unroll
;     for (int b = 0; b < 4; ++b) r4<INV>(x[b], x[4 + b], x[8 + b], x[12 + b]);
;     const float sg = INV ? -1.f : 1.f;
;     const f32x2 W1 = {0.92387953251f, -0.38268343236f * sg}, W2 = {0.70710678118f, -0.70710678118f * sg}, W3 = {0.38268343236f, -0.92387953251f * sg},
;                 W4 = {0.f, -1.f * sg}, W6 = {-0.70710678118f, -0.70710678118f * sg}, W9 = {-0.92387953251f, 0.38268343236f * sg};
;     x[5] = cmul(x[5], W1); x[9] = cmul(x[9], W2); x[13] = cmul(x[13], W3);
;     x[6] = cmul(x[6], W2); x[10] = cmul(x[10], W4); x[14] = cmul(x[14], W6);
;     x[7] = cmul(x[7], W3); x[11] = cmul(x[11], W6); x[15] = cmul(x[15], W9);
; #pragma unroll
;     for (int c = 0; c < 4; ++c) r4<INV>(x[4 * c], x[4 * c + 1], x[4 * c + 2], x[4 * c + 3]);
; }
	v_pk_add_f32 v[64:65], v[92:93], v[94:95]
	v_pk_add_f32 v[80:81], v[80:81], v[82:83] neg_lo:[0,1] neg_hi:[0,1]
	v_pk_add_f32 v[86:87], v[84:85], v[86:87] neg_lo:[0,1] neg_hi:[0,1]
	v_pk_add_f32 v[90:91], v[88:89], v[90:91] neg_lo:[0,1] neg_hi:[0,1]
	v_pk_add_f32 v[94:95], v[92:93], v[94:95] neg_lo:[0,1] neg_hi:[0,1]
	v_pk_add_f32 v[92:93], v[96:97], v[76:77]
	v_pk_add_f32 v[88:89], v[98:99], v[74:75]
	v_pk_add_f32 v[84:85], v[100:101], v[70:71]
	v_pk_add_f32 v[82:83], v[102:103], v[64:65]
	v_pk_add_f32 v[96:97], v[96:97], v[76:77] neg_lo:[0,1] neg_hi:[0,1]
	v_pk_add_f32 v[74:75], v[98:99], v[74:75] neg_lo:[0,1] neg_hi:[0,1]
	v_pk_add_f32 v[100:101], v[100:101], v[70:71] neg_lo:[0,1] neg_hi:[0,1]
	v_pk_add_f32 v[64:65], v[102:103], v[64:65] neg_lo:[0,1] neg_hi:[0,1]
	v_pk_add_f32 v[102:103], v[66:67], v[80:81] op_sel:[0,1] op_sel_hi:[1,0] neg_hi:[0,1]
	v_pk_add_f32 v[70:71], v[68:69], v[86:87] op_sel:[0,1] op_sel_hi:[1,0] neg_hi:[0,1]
	v_pk_add_f32 v[98:99], v[72:73], v[90:91] op_sel:[0,1] op_sel_hi:[1,0] neg_hi:[0,1]
	v_pk_add_f32 v[76:77], v[78:79], v[94:95] op_sel:[0,1] op_sel_hi:[1,0] neg_hi:[0,1]
	v_pk_add_f32 v[80:81], v[66:67], v[80:81] op_sel:[0,1] op_sel_hi:[1,0] neg_lo:[0,1]
	v_pk_add_f32 v[68:69], v[68:69], v[86:87] op_sel:[0,1] op_sel_hi:[1,0] neg_lo:[0,1]
	v_pk_add_f32 v[90:91], v[72:73], v[90:91] op_sel:[0,1] op_sel_hi:[1,0] neg_lo:[0,1]
	v_pk_add_f32 v[78:79], v[78:79], v[94:95] op_sel:[0,1] op_sel_hi:[1,0] neg_lo:[0,1]
	v_pk_add_f32 v[94:95], v[92:93], v[84:85]
	v_pk_mul_f32 v[72:73], v[70:71], s[70:71] op_sel_hi:[1,0]
	v_pk_mul_f32 v[86:87], v[74:75], s[72:73] op_sel_hi:[1,0]
	v_pk_mul_f32 v[66:67], v[68:69], s[64:65] op_sel_hi:[1,0]
	v_pk_add_f32 v[84:85], v[92:93], v[84:85] neg_lo:[0,1] neg_hi:[0,1]
	v_pk_fma_f32 v[70:71], v[70:71], s[44:45], v[72:73] op_sel:[0,0,1] op_sel_hi:[1,0,0] neg_lo:[0,0,1]
	v_pk_fma_f32 v[86:87], v[74:75], s[76:77], v[86:87] op_sel:[0,0,1] op_sel_hi:[1,0,0] neg_lo:[0,0,1]
	v_pk_fma_f32 v[68:69], v[68:69], s[82:83], v[66:67] op_sel:[0,0,1] op_sel_hi:[1,0,0] neg_lo:[0,0,1]
	v_pk_add_f32 v[66:67], v[88:89], v[82:83]
	v_pk_fma_f32 v[74:75], v[98:99], s[72:73], v[102:103] op_sel:[0,0,1] op_sel_hi:[1,0,0] neg_hi:[0,0,1]
	v_pk_add_f32 v[72:73], v[96:97], v[100:101] op_sel:[0,1] op_sel_hi:[1,0] neg_hi:[0,1]
	v_pk_fma_f32 v[92:93], v[90:91], s[72:73], v[80:81] op_sel:[0,0,1] op_sel_hi:[1,0,0] neg_hi:[0,0,1]
	v_pk_add_f32 v[88:89], v[88:89], v[82:83] neg_lo:[0,1] neg_hi:[0,1]
	v_pk_fma_f32 v[98:99], v[98:99], s[76:77], v[74:75] op_sel:[0,0,1] op_sel_hi:[1,0,0] neg_lo:[0,0,1]
	v_pk_add_f32 v[100:101], v[96:97], v[100:101] op_sel:[0,1] op_sel_hi:[1,0] neg_lo:[0,1]
	v_pk_fma_f32 v[92:93], v[90:91], s[72:73], v[92:93] op_sel:[0,0,1] op_sel_hi:[1,0,0] neg_lo:[0,0,1]
	v_pk_add_f32 v[90:91], v[94:95], v[66:67]
	v_pk_fma_f32 v[102:103], v[102:103], s[100:101], v[98:99] op_sel_hi:[1,0,1] neg_lo:[0,0,1] neg_hi:[0,0,1]
	v_pk_fma_f32 v[96:97], v[64:65], s[72:73], v[86:87] op_sel:[0,0,1] op_sel_hi:[1,0,0] neg_hi:[0,0,1]
	v_pk_fma_f32 v[80:81], v[80:81], s[100:101], v[92:93] op_sel_hi:[1,0,1] neg_lo:[0,0,1] neg_hi:[0,0,1]
	v_pk_add_f32 v[66:67], v[94:95], v[66:67] neg_lo:[0,1] neg_hi:[0,1]
	v_pk_fma_f32 v[94:95], v[76:77], s[64:65], v[70:71] op_sel:[0,0,1] op_sel_hi:[1,0,0] neg_hi:[0,0,1]
	v_pk_fma_f32 v[96:97], v[64:65], s[72:73], v[96:97] op_sel:[0,0,1] op_sel_hi:[1,0,0] neg_lo:[0,0,1]
	v_pk_fma_f32 v[64:65], v[78:79], s[82:83], v[68:69] op_sel:[0,0,1] op_sel_hi:[1,0,0] neg_hi:[0,0,1]
	v_pk_add_f32 v[74:75], v[84:85], v[88:89] op_sel:[0,1] op_sel_hi:[1,0] neg_hi:[0,1]
	v_pk_fma_f32 v[76:77], v[76:77], s[82:83], v[94:95] op_sel:[0,0,1] op_sel_hi:[1,0,0] neg_lo:[0,0,1]
	v_pk_fma_f32 v[86:87], v[86:87], s[100:101], v[96:97] op_sel_hi:[1,0,1] neg_lo:[0,0,1] neg_hi:[0,0,1]
	v_pk_fma_f32 v[64:65], v[78:79], s[64:65], v[64:65] op_sel:[0,0,1] op_sel_hi:[1,0,0] neg_lo:[0,0,1]
	v_pk_add_f32 v[84:85], v[84:85], v[88:89] op_sel:[0,1] op_sel_hi:[1,0] neg_lo:[0,1]
	v_pk_fma_f32 v[70:71], v[70:71], s[100:101], v[76:77] op_sel_hi:[1,0,1] neg_lo:[0,0,1] neg_hi:[0,0,1]
	v_pk_add_f32 v[88:89], v[72:73], v[96:97]
	v_pk_fma_f32 v[68:69], v[68:69], s[100:101], v[64:65] op_sel_hi:[1,0,1] neg_lo:[0,0,1] neg_hi:[0,0,1]
	v_pk_add_f32 v[78:79], v[98:99], v[76:77]
	v_pk_add_f32 v[96:97], v[72:73], v[96:97] neg_lo:[0,1] neg_hi:[0,1]
	v_pk_add_f32 v[72:73], v[92:93], v[64:65]
	v_pk_add_f32 v[76:77], v[98:99], v[76:77] neg_lo:[0,1] neg_hi:[0,1]
	v_pk_add_f32 v[98:99], v[100:101], v[86:87] op_sel:[0,1] op_sel_hi:[1,0] neg_hi:[0,1]
	v_pk_add_f32 v[64:65], v[92:93], v[64:65] neg_lo:[0,1] neg_hi:[0,1]
	v_pk_add_f32 v[92:93], v[102:103], v[70:71] op_sel:[0,1] op_sel_hi:[1,0] neg_hi:[0,1]
	v_pk_add_f32 v[86:87], v[100:101], v[86:87] op_sel:[0,1] op_sel_hi:[1,0] neg_lo:[0,1]
	v_pk_add_f32 v[100:101], v[80:81], v[68:69] op_sel:[0,1] op_sel_hi:[1,0] neg_hi:[0,1]
	v_pk_add_f32 v[70:71], v[102:103], v[70:71] op_sel:[0,1] op_sel_hi:[1,0] neg_lo:[0,1]
	v_pk_add_f32 v[68:69], v[80:81], v[68:69] op_sel:[0,1] op_sel_hi:[1,0] neg_lo:[0,1]
	v_pk_mul_f32 v[80:81], v[78:79], v[232:233] op_sel:[0,1] op_sel_hi:[1,1]
	v_pk_mul_f32 v[102:103], v[88:89], v[234:235] op_sel:[0,1] op_sel_hi:[1,1]
	v_pk_fma_f32 v[80:81], v[78:79], v[232:233], v[80:81] op_sel:[0,0,1] op_sel_hi:[1,0,0] neg_lo:[0,0,1]
	v_pk_mul_f32 v[78:79], v[72:73], v[208:209] op_sel:[0,1] op_sel_hi:[1,1]
	v_pk_fma_f32 v[102:103], v[88:89], v[234:235], v[102:103] op_sel:[0,0,1] op_sel_hi:[1,0,0] neg_lo:[0,0,1]
	v_pk_mul_f32 v[88:89], v[74:75], v[210:211] op_sel:[0,1] op_sel_hi:[1,1]
	v_pk_fma_f32 v[78:79], v[72:73], v[208:209], v[78:79] op_sel:[0,0,1] op_sel_hi:[1,0,0] neg_lo:[0,0,1]
; #define LAS __attribute__((address_space(3)))
; #define LT() ({ int lt_ = tid; asm volatile("" : "+v"(lt_)); lt_; })
; template <bool INV> __device__ __forceinline__ void pass16_s4(LAS f32x2* X, const LAS f32x2* TH, const LAS f32x2* TL, int tid) {
; #pragma unroll 1
;     for (int s = 0; s < 2; ++s) {
;         const int b = tid + NTHR * s, blk = b >> 2, jj = b & 3;
;         LAS f32x2* P = X + blk * 68 + jj;
;         f32x2 x[16];
; #pragma unroll
;         for (int q = 0; q < 16; ++q) x[q] = P[4 * q];
;         bfly16_tab<INV>(x, TH - 1024, 4, jj);
; #pragma unroll
;         for (int c = 0; c < 4; ++c)
; #pragma unroll
;             for (int d = 0; d < 4; ++d) P[4 * (c + 4 * d)] = x[4 * c + d];
;     }
; }
; __device__ __forceinline__ void hyena_latent(Frame& F, int l, int ch, LAS f32x2* X, const LAS f32x2* TH, const LAS f32x2* TL, GAS f32x2* KS, const LAS float* CT  , bool wr = true) {
;     ...
; #pragma unroll
;             for (int i = 0; i < 8; ++i) { const int b = LT() + NTHR * i; const LAS f32x4* P = (const LAS f32x4*)(X + 4 * b + ((b >> 4) << 2)); const f32x4 u = P[0], v = P[1];
;                 f32x2 x0 = {u.x, u.y}, x1 = {u.z, u.w}, x2 = {v.x, v.y}, x3 = {v.z, v.w}; r4<false>(x0, x1, x2, x3);
;                 kreg[2 * i] = (f32x4){x0.x, x0.y, x1.x, x1.y}; kreg[2 * i + 1] = (f32x4){x2.x, x2.y, x3.x, x3.y}; }
	v_pk_mul_f32 v[72:73], v[92:93], v[204:205] op_sel:[0,1] op_sel_hi:[1,1]
	v_pk_fma_f32 v[88:89], v[74:75], v[210:211], v[88:89] op_sel:[0,0,1] op_sel_hi:[1,0,0] neg_lo:[0,0,1]
	v_pk_mul_f32 v[74:75], v[98:99], v[206:207] op_sel:[0,1] op_sel_hi:[1,1]
	v_pk_fma_f32 v[92:93], v[92:93], v[204:205], v[72:73] op_sel:[0,0,1] op_sel_hi:[1,0,0] neg_lo:[0,0,1]
	v_pk_mul_f32 v[72:73], v[100:101], v[200:201] op_sel:[0,1] op_sel_hi:[1,1]
	v_pk_fma_f32 v[98:99], v[98:99], v[206:207], v[74:75] op_sel:[0,0,1] op_sel_hi:[1,0,0] neg_lo:[0,0,1]
	v_pk_mul_f32 v[74:75], v[66:67], v[202:203] op_sel:[0,1] op_sel_hi:[1,1]
	v_pk_fma_f32 v[100:101], v[100:101], v[200:201], v[72:73] op_sel:[0,0,1] op_sel_hi:[1,0,0] neg_lo:[0,0,1]
	v_pk_mul_f32 v[72:73], v[76:77], v[196:197] op_sel:[0,1] op_sel_hi:[1,1]
	v_pk_fma_f32 v[66:67], v[66:67], v[202:203], v[74:75] op_sel:[0,0,1] op_sel_hi:[1,0,0] neg_lo:[0,0,1]
	v_pk_mul_f32 v[74:75], v[96:97], v[198:199] op_sel:[0,1] op_sel_hi:[1,1]
	v_pk_fma_f32 v[76:77], v[76:77], v[196:197], v[72:73] op_sel:[0,0,1] op_sel_hi:[1,0,0] neg_lo:[0,0,1]
	v_pk_mul_f32 v[72:73], v[64:65], v[192:193] op_sel:[0,1] op_sel_hi:[1,1]
	v_pk_fma_f32 v[96:97], v[96:97], v[198:199], v[74:75] op_sel:[0,0,1] op_sel_hi:[1,0,0] neg_lo:[0,0,1]
	v_pk_mul_f32 v[74:75], v[84:85], v[194:195] op_sel:[0,1] op_sel_hi:[1,1]
	v_pk_fma_f32 v[64:65], v[64:65], v[192:193], v[72:73] op_sel:[0,0,1] op_sel_hi:[1,0,0] neg_lo:[0,0,1]
	v_pk_mul_f32 v[72:73], v[70:71], v[188:189] op_sel:[0,1] op_sel_hi:[1,1]
	v_pk_fma_f32 v[74:75], v[84:85], v[194:195], v[74:75] op_sel:[0,0,1] op_sel_hi:[1,0,0] neg_lo:[0,0,1]
	v_pk_mul_f32 v[84:85], v[86:87], v[190:191] op_sel:[0,1] op_sel_hi:[1,1]
	v_pk_fma_f32 v[70:71], v[70:71], v[188:189], v[72:73] op_sel:[0,0,1] op_sel_hi:[1,0,0] neg_lo:[0,0,1]
	v_pk_mul_f32 v[72:73], v[68:69], v[186:187] op_sel:[0,1] op_sel_hi:[1,1]
	v_pk_fma_f32 v[84:85], v[86:87], v[190:191], v[84:85] op_sel:[0,0,1] op_sel_hi:[1,0,0] neg_lo:[0,0,1]
	v_pk_fma_f32 v[72:73], v[68:69], v[186:187], v[72:73] op_sel:[0,0,1] op_sel_hi:[1,0,0] neg_lo:[0,0,1]
	ds_write_b64 v151, v[90:91] offset:0
	ds_write_b64 v151, v[80:81] offset:32
	ds_write_b64 v151, v[102:103] offset:64
	ds_write_b64 v151, v[78:79] offset:96
	ds_write_b64 v151, v[88:89] offset:128
	ds_write_b64 v151, v[92:93] offset:160
	ds_write_b64 v151, v[98:99] offset:192
	ds_write_b64 v151, v[100:101] offset:224
	ds_write_b64 v151, v[66:67] offset:256
	ds_write_b64 v151, v[76:77] offset:288
	ds_write_b64 v151, v[96:97] offset:320
	ds_write_b64 v151, v[64:65] offset:352
	ds_write_b64 v151, v[74:75] offset:384
	ds_write_b64 v151, v[70:71] offset:416
	ds_write_b64 v151, v[84:85] offset:448
	ds_write_b64 v151, v[72:73] offset:480
	s_cbranch_scc1 .LBB0_850
	v_pk_add_f32 v[68:69], v[56:57], v[60:61]
	v_pk_add_f32 v[56:57], v[56:57], v[60:61] neg_lo:[0,1] neg_hi:[0,1]
	v_pk_add_f32 v[60:61], v[58:59], v[62:63]
	v_pk_add_f32 v[58:59], v[58:59], v[62:63] neg_lo:[0,1] neg_hi:[0,1]
	v_pk_add_f32 v[66:67], v[68:69], v[60:61]
	v_xor_b32_e32 v71, 0x80000000, v58
	v_mov_b32_e32 v70, v59
	v_pk_add_f32 v[62:63], v[68:69], v[60:61] neg_lo:[0,1] neg_hi:[0,1]
	v_pk_add_f32 v[68:69], v[48:49], v[52:53]
	v_pk_add_f32 v[48:49], v[48:49], v[52:53] neg_lo:[0,1] neg_hi:[0,1]
	v_pk_add_f32 v[52:53], v[50:51], v[54:55]
	v_pk_add_f32 v[50:51], v[50:51], v[54:55] neg_lo:[0,1] neg_hi:[0,1]
	v_pk_add_f32 v[64:65], v[56:57], v[70:71]
	v_pk_add_f32 v[60:61], v[56:57], v[70:71] neg_lo:[0,1] neg_hi:[0,1]
	v_xor_b32_e32 v71, 0x80000000, v50
	v_mov_b32_e32 v70, v51
	v_pk_add_f32 v[58:59], v[68:69], v[52:53]
	v_pk_add_f32 v[54:55], v[68:69], v[52:53] neg_lo:[0,1] neg_hi:[0,1]
	v_pk_add_f32 v[68:69], v[40:41], v[44:45]
	v_pk_add_f32 v[40:41], v[40:41], v[44:45] neg_lo:[0,1] neg_hi:[0,1]
	v_pk_add_f32 v[44:45], v[42:43], v[46:47]
	v_pk_add_f32 v[42:43], v[42:43], v[46:47] neg_lo:[0,1] neg_hi:[0,1]
	v_pk_add_f32 v[56:57], v[48:49], v[70:71]
	v_pk_add_f32 v[52:53], v[48:49], v[70:71] neg_lo:[0,1] neg_hi:[0,1]
	v_xor_b32_e32 v71, 0x80000000, v42
	v_mov_b32_e32 v70, v43
	v_pk_add_f32 v[50:51], v[68:69], v[44:45]
	v_pk_add_f32 v[46:47], v[68:69], v[44:45] neg_lo:[0,1] neg_hi:[0,1]
	v_pk_add_f32 v[68:69], v[32:33], v[36:37]
	v_pk_add_f32 v[32:33], v[32:33], v[36:37] neg_lo:[0,1] neg_hi:[0,1]
	v_pk_add_f32 v[36:37], v[34:35], v[38:39]
	v_pk_add_f32 v[34:35], v[34:35], v[38:39] neg_lo:[0,1] neg_hi:[0,1]
	v_pk_add_f32 v[48:49], v[40:41], v[70:71]
	v_pk_add_f32 v[44:45], v[40:41], v[70:71] neg_lo:[0,1] neg_hi:[0,1]
	v_xor_b32_e32 v71, 0x80000000, v34
	v_mov_b32_e32 v70, v35
	v_pk_add_f32 v[42:43], v[68:69], v[36:37]
	v_pk_add_f32 v[38:39], v[68:69], v[36:37] neg_lo:[0,1] neg_hi:[0,1]
	v_pk_add_f32 v[68:69], v[24:25], v[28:29]
	v_pk_add_f32 v[24:25], v[24:25], v[28:29] neg_lo:[0,1] neg_hi:[0,1]
	v_pk_add_f32 v[28:29], v[26:27], v[30:31]
	v_pk_add_f32 v[26:27], v[26:27], v[30:31] neg_lo:[0,1] neg_hi:[0,1]
	v_pk_add_f32 v[40:41], v[32:33], v[70:71]
	v_pk_add_f32 v[36:37], v[32:33], v[70:71] neg_lo:[0,1] neg_hi:[0,1]
	v_xor_b32_e32 v71, 0x80000000, v26
	v_mov_b32_e32 v70, v27
	v_pk_add_f32 v[34:35], v[68:69], v[28:29]
	v_pk_add_f32 v[30:31], v[68:69], v[28:29] neg_lo:[0,1] neg_hi:[0,1]
	v_pk_add_f32 v[68:69], v[12:13], v[20:21]
	v_pk_add_f32 v[12:13], v[12:13], v[20:21] neg_lo:[0,1] neg_hi:[0,1]
	v_pk_add_f32 v[20:21], v[14:15], v[22:23]
	v_pk_add_f32 v[14:15], v[14:15], v[22:23] neg_lo:[0,1] neg_hi:[0,1]
	v_pk_add_f32 v[32:33], v[24:25], v[70:71]
	v_pk_add_f32 v[28:29], v[24:25], v[70:71] neg_lo:[0,1] neg_hi:[0,1]
	v_xor_b32_e32 v71, 0x80000000, v14
	v_mov_b32_e32 v70, v15
	v_pk_add_f32 v[14:15], v[6:7], v[18:19]
	v_pk_add_f32 v[6:7], v[6:7], v[18:19] neg_lo:[0,1] neg_hi:[0,1]
	v_pk_add_f32 v[26:27], v[68:69], v[20:21]
	v_pk_add_f32 v[24:25], v[12:13], v[70:71]
	v_pk_add_f32 v[22:23], v[68:69], v[20:21] neg_lo:[0,1] neg_hi:[0,1]
	v_pk_add_f32 v[20:21], v[12:13], v[70:71] neg_lo:[0,1] neg_hi:[0,1]
	v_pk_add_f32 v[12:13], v[4:5], v[16:17]
	v_pk_add_f32 v[4:5], v[4:5], v[16:17] neg_lo:[0,1] neg_hi:[0,1]
	v_xor_b32_e32 v69, 0x80000000, v6
	v_mov_b32_e32 v68, v7
	v_pk_add_f32 v[18:19], v[12:13], v[14:15]
	v_pk_add_f32 v[16:17], v[4:5], v[68:69]
	v_pk_add_f32 v[14:15], v[12:13], v[14:15] neg_lo:[0,1] neg_hi:[0,1]
	v_pk_add_f32 v[12:13], v[4:5], v[68:69] neg_lo:[0,1] neg_hi:[0,1]
	v_pk_add_f32 v[68:69], v[0:1], v[8:9]
	v_pk_add_f32 v[0:1], v[0:1], v[8:9] neg_lo:[0,1] neg_hi:[0,1]
	v_pk_add_f32 v[8:9], v[2:3], v[10:11]
	v_pk_add_f32 v[2:3], v[2:3], v[10:11] neg_lo:[0,1] neg_hi:[0,1]
	v_pk_add_f32 v[6:7], v[68:69], v[8:9]
	v_xor_b32_e32 v11, 0x80000000, v2
	v_mov_b32_e32 v10, v3
	v_pk_add_f32 v[2:3], v[68:69], v[8:9] neg_lo:[0,1] neg_hi:[0,1]
	v_mov_b32_e32 v8, v140
	s_waitcnt lgkmcnt(0)
	s_barrier
; #define LAS __attribute__((address_space(3)))
; __device__ __forceinline__ f32x2 cmul(f32x2 a, f32x2 b) { return (f32x2){a.x * b.x - a.y * b.y, a.x * b.y + a.y * b.x}; }
; #define LT() ({ int lt_ = tid; asm volatile("" : "+v"(lt_)); lt_; })
; __device__ __forceinline__ void hyena_latent(Frame& F, int l, int ch, LAS f32x2* X, const LAS f32x2* TH, const LAS f32x2* TL, GAS f32x2* KS, const LAS float* CT  , bool wr = true) {
;     ...
;             for (int i = 0; i < 8; ++i) { const int b = LT() + NTHR * i; LAS f32x4* P = (LAS f32x4*)(X + 4 * b + ((b >> 4) << 2)); const f32x4 u = P[0], v = P[1], k0 = kreg[2 * i], k1 = kreg[2 * i + 1];
;                 f32x2 x0 = {u.x, u.y}, x1 = {u.z, u.w}, x2 = {v.x, v.y}, x3 = {v.z, v.w}; r4<false>(x0, x1, x2, x3);
;                 x0 = cmul(x0, (f32x2){k0.x, k0.y}); x1 = cmul(x1, (f32x2){k0.z, k0.w}); x2 = cmul(x2, (f32x2){k1.x, k1.y}); x3 = cmul(x3, (f32x2){k1.z, k1.w});
;                 r4<true>(x0, x1, x2, x3);
;                 P[0] = (f32x4){x0.x, x0.y, x1.x, x1.y}; P[1] = (f32x4){x2.x, x2.y, x3.x, x3.y};
	v_pk_add_f32 v[4:5], v[0:1], v[10:11]
	v_lshlrev_b32_e32 v201, 1, v140
	v_lshlrev_b32_e32 v200, 5, v140
	v_pk_add_f32 v[0:1], v[0:1], v[10:11] neg_lo:[0,1] neg_hi:[0,1]
	v_and_b32_e32 v201, 0xffffffe0, v201
	v_add3_u32 v200, 0, v200, v201
	v_add_u32_e32 v201, 0x11000, v200
	ds_read_b128 v[68:71], v200 offset:0
	ds_read_b128 v[72:75], v200 offset:16
	ds_read_b128 v[76:79], v200 offset:17408
	ds_read_b128 v[80:83], v200 offset:17424
	ds_read_b128 v[84:87], v200 offset:34816
	ds_read_b128 v[88:91], v200 offset:34832
	ds_read_b128 v[92:95], v200 offset:52224
	ds_read_b128 v[96:99], v200 offset:52240
	ds_read_b128 v[100:103], v201 offset:0
	ds_read_b128 v[104:107], v201 offset:16
	ds_read_b128 v[108:111], v201 offset:17408
	ds_read_b128 v[112:115], v201 offset:17424
	ds_read_b128 v[116:119], v201 offset:34816
	ds_read_b128 v[120:123], v201 offset:34832
	ds_read_b128 v[124:127], v201 offset:52224
	ds_read_b128 v[178:181], v201 offset:52240
	s_mov_b32 s0, 0
	s_mov_b64 s[12:13], -1
	s_waitcnt lgkmcnt(14)
	v_pk_add_f32 v[190:191], v[68:69], v[72:73]
	v_pk_add_f32 v[192:193], v[70:71], v[74:75]
	v_pk_add_f32 v[68:69], v[68:69], v[72:73] neg_lo:[0,1] neg_hi:[0,1]
	v_pk_add_f32 v[70:71], v[70:71], v[74:75] neg_lo:[0,1] neg_hi:[0,1]
	v_pk_add_f32 v[72:73], v[190:191], v[192:193]
	v_pk_add_f32 v[74:75], v[190:191], v[192:193] neg_lo:[0,1] neg_hi:[0,1]
	v_pk_add_f32 v[190:191], v[68:69], v[70:71] op_sel:[0,1] op_sel_hi:[1,0] neg_hi:[0,1]
	v_pk_add_f32 v[192:193], v[68:69], v[70:71] op_sel:[0,1] op_sel_hi:[1,0] neg_lo:[0,1]
	v_pk_mul_f32 v[194:195], v[72:73], v[66:67] op_sel:[0,1] op_sel_hi:[1,1]
	v_pk_mul_f32 v[196:197], v[190:191], v[64:65] op_sel:[0,1] op_sel_hi:[1,1]
	v_pk_mul_f32 v[198:199], v[74:75], v[62:63] op_sel:[0,1] op_sel_hi:[1,1]
	v_pk_mul_f32 v[68:69], v[192:193], v[60:61] op_sel:[0,1] op_sel_hi:[1,1]
	v_pk_fma_f32 v[72:73], v[72:73], v[66:67], v[194:195] op_sel:[0,0,1] op_sel_hi:[1,0,0] neg_lo:[0,0,1]
	v_pk_fma_f32 v[190:191], v[190:191], v[64:65], v[196:197] op_sel:[0,0,1] op_sel_hi:[1,0,0] neg_lo:[0,0,1]
	v_pk_fma_f32 v[74:75], v[74:75], v[62:63], v[198:199] op_sel:[0,0,1] op_sel_hi:[1,0,0] neg_lo:[0,0,1]
	v_pk_fma_f32 v[192:193], v[192:193], v[60:61], v[68:69] op_sel:[0,0,1] op_sel_hi:[1,0,0] neg_lo:[0,0,1]
	v_pk_add_f32 v[194:195], v[72:73], v[74:75]
	v_pk_add_f32 v[196:197], v[190:191], v[192:193]
	v_pk_add_f32 v[198:199], v[72:73], v[74:75] neg_lo:[0,1] neg_hi:[0,1]
	v_pk_add_f32 v[68:69], v[190:191], v[192:193] neg_lo:[0,1] neg_hi:[0,1]
	v_pk_add_f32 v[182:183], v[194:195], v[196:197]
	v_pk_add_f32 v[186:187], v[194:195], v[196:197] neg_lo:[0,1] neg_hi:[0,1]
	v_pk_add_f32 v[184:185], v[198:199], v[68:69] op_sel:[0,1] op_sel_hi:[1,0] neg_lo:[0,1]
	v_pk_add_f32 v[188:189], v[198:199], v[68:69] op_sel:[0,1] op_sel_hi:[1,0] neg_hi:[0,1]
	s_nop 0
	ds_write_b128 v200, v[182:185] offset:0
	ds_write_b128 v200, v[186:189] offset:16
	s_waitcnt lgkmcnt(14)
	v_pk_add_f32 v[190:191], v[76:77], v[80:81]
	v_pk_add_f32 v[192:193], v[78:79], v[82:83]
	v_pk_add_f32 v[76:77], v[76:77], v[80:81] neg_lo:[0,1] neg_hi:[0,1]
	v_pk_add_f32 v[78:79], v[78:79], v[82:83] neg_lo:[0,1] neg_hi:[0,1]
	v_pk_add_f32 v[80:81], v[190:191], v[192:193]
	v_pk_add_f32 v[82:83], v[190:191], v[192:193] neg_lo:[0,1] neg_hi:[0,1]
	v_pk_add_f32 v[190:191], v[76:77], v[78:79] op_sel:[0,1] op_sel_hi:[1,0] neg_hi:[0,1]
	v_pk_add_f32 v[192:193], v[76:77], v[78:79] op_sel:[0,1] op_sel_hi:[1,0] neg_lo:[0,1]
	v_pk_mul_f32 v[194:195], v[80:81], v[58:59] op_sel:[0,1] op_sel_hi:[1,1]
	v_pk_mul_f32 v[196:197], v[190:191], v[56:57] op_sel:[0,1] op_sel_hi:[1,1]
	v_pk_mul_f32 v[198:199], v[82:83], v[54:55] op_sel:[0,1] op_sel_hi:[1,1]
	v_pk_mul_f32 v[76:77], v[192:193], v[52:53] op_sel:[0,1] op_sel_hi:[1,1]
	v_pk_fma_f32 v[80:81], v[80:81], v[58:59], v[194:195] op_sel:[0,0,1] op_sel_hi:[1,0,0] neg_lo:[0,0,1]
	v_pk_fma_f32 v[190:191], v[190:191], v[56:57], v[196:197] op_sel:[0,0,1] op_sel_hi:[1,0,0] neg_lo:[0,0,1]
	v_pk_fma_f32 v[82:83], v[82:83], v[54:55], v[198:199] op_sel:[0,0,1] op_sel_hi:[1,0,0] neg_lo:[0,0,1]
	v_pk_fma_f32 v[192:193], v[192:193], v[52:53], v[76:77] op_sel:[0,0,1] op_sel_hi:[1,0,0] neg_lo:[0,0,1]
	v_pk_add_f32 v[194:195], v[80:81], v[82:83]
	v_pk_add_f32 v[196:197], v[190:191], v[192:193]
	v_pk_add_f32 v[198:199], v[80:81], v[82:83] neg_lo:[0,1] neg_hi:[0,1]
	v_pk_add_f32 v[76:77], v[190:191], v[192:193] neg_lo:[0,1] neg_hi:[0,1]
	v_pk_add_f32 v[182:183], v[194:195], v[196:197]
	v_pk_add_f32 v[186:187], v[194:195], v[196:197] neg_lo:[0,1] neg_hi:[0,1]
	v_pk_add_f32 v[184:185], v[198:199], v[76:77] op_sel:[0,1] op_sel_hi:[1,0] neg_lo:[0,1]
	v_pk_add_f32 v[188:189], v[198:199], v[76:77] op_sel:[0,1] op_sel_hi:[1,0] neg_hi:[0,1]
	s_nop 0
	ds_write_b128 v200, v[182:185] offset:17408
	ds_write_b128 v200, v[186:189] offset:17424
	s_waitcnt lgkmcnt(14)
; #define LAS __attribute__((address_space(3)))
; __device__ __forceinline__ f32x2 cmul(f32x2 a, f32x2 b) { return (f32x2){a.x * b.x - a.y * b.y, a.x * b.y + a.y * b.x}; }
; #define LT() ({ int lt_ = tid; asm volatile("" : "+v"(lt_)); lt_; })
; __device__ __forceinline__ void hyena_latent(Frame& F, int l, int ch, LAS f32x2* X, const LAS f32x2* TH, const LAS f32x2* TL, GAS f32x2* KS, const LAS float* CT  , bool wr = true) {
;     ...
;             for (int i = 0; i < 8; ++i) { const int b = LT() + NTHR * i; LAS f32x4* P = (LAS f32x4*)(X + 4 * b + ((b >> 4) << 2)); const f32x4 u = P[0], v = P[1], k0 = kreg[2 * i], k1 = kreg[2 * i + 1];
;                 f32x2 x0 = {u.x, u.y}, x1 = {u.z, u.w}, x2 = {v.x, v.y}, x3 = {v.z, v.w}; r4<false>(x0, x1, x2, x3);
;                 x0 = cmul(x0, (f32x2){k0.x, k0.y}); x1 = cmul(x1, (f32x2){k0.z, k0.w}); x2 = cmul(x2, (f32x2){k1.x, k1.y}); x3 = cmul(x3, (f32x2){k1.z, k1.w});
;                 r4<true>(x0, x1, x2, x3);
;                 P[0] = (f32x4){x0.x, x0.y, x1.x, x1.y}; P[1] = (f32x4){x2.x, x2.y, x3.x, x3.y};
	v_pk_add_f32 v[190:191], v[84:85], v[88:89]
	v_pk_add_f32 v[192:193], v[86:87], v[90:91]
	v_pk_add_f32 v[84:85], v[84:85], v[88:89] neg_lo:[0,1] neg_hi:[0,1]
	v_pk_add_f32 v[86:87], v[86:87], v[90:91] neg_lo:[0,1] neg_hi:[0,1]
	v_pk_add_f32 v[88:89], v[190:191], v[192:193]
	v_pk_add_f32 v[90:91], v[190:191], v[192:193] neg_lo:[0,1] neg_hi:[0,1]
	v_pk_add_f32 v[190:191], v[84:85], v[86:87] op_sel:[0,1] op_sel_hi:[1,0] neg_hi:[0,1]
	v_pk_add_f32 v[192:193], v[84:85], v[86:87] op_sel:[0,1] op_sel_hi:[1,0] neg_lo:[0,1]
	v_pk_mul_f32 v[194:195], v[88:89], v[50:51] op_sel:[0,1] op_sel_hi:[1,1]
	v_pk_mul_f32 v[196:197], v[190:191], v[48:49] op_sel:[0,1] op_sel_hi:[1,1]
	v_pk_mul_f32 v[198:199], v[90:91], v[46:47] op_sel:[0,1] op_sel_hi:[1,1]
	v_pk_mul_f32 v[84:85], v[192:193], v[44:45] op_sel:[0,1] op_sel_hi:[1,1]
	v_pk_fma_f32 v[88:89], v[88:89], v[50:51], v[194:195] op_sel:[0,0,1] op_sel_hi:[1,0,0] neg_lo:[0,0,1]
	v_pk_fma_f32 v[190:191], v[190:191], v[48:49], v[196:197] op_sel:[0,0,1] op_sel_hi:[1,0,0] neg_lo:[0,0,1]
	v_pk_fma_f32 v[90:91], v[90:91], v[46:47], v[198:199] op_sel:[0,0,1] op_sel_hi:[1,0,0] neg_lo:[0,0,1]
	v_pk_fma_f32 v[192:193], v[192:193], v[44:45], v[84:85] op_sel:[0,0,1] op_sel_hi:[1,0,0] neg_lo:[0,0,1]
	v_pk_add_f32 v[194:195], v[88:89], v[90:91]
	v_pk_add_f32 v[196:197], v[190:191], v[192:193]
	v_pk_add_f32 v[198:199], v[88:89], v[90:91] neg_lo:[0,1] neg_hi:[0,1]
	v_pk_add_f32 v[84:85], v[190:191], v[192:193] neg_lo:[0,1] neg_hi:[0,1]
	v_pk_add_f32 v[182:183], v[194:195], v[196:197]
	v_pk_add_f32 v[186:187], v[194:195], v[196:197] neg_lo:[0,1] neg_hi:[0,1]
	v_pk_add_f32 v[184:185], v[198:199], v[84:85] op_sel:[0,1] op_sel_hi:[1,0] neg_lo:[0,1]
	v_pk_add_f32 v[188:189], v[198:199], v[84:85] op_sel:[0,1] op_sel_hi:[1,0] neg_hi:[0,1]
	s_nop 0
	ds_write_b128 v200, v[182:185] offset:34816
	ds_write_b128 v200, v[186:189] offset:34832
	s_waitcnt lgkmcnt(14)
	v_pk_add_f32 v[190:191], v[92:93], v[96:97]
	v_pk_add_f32 v[192:193], v[94:95], v[98:99]
	v_pk_add_f32 v[92:93], v[92:93], v[96:97] neg_lo:[0,1] neg_hi:[0,1]
	v_pk_add_f32 v[94:95], v[94:95], v[98:99] neg_lo:[0,1] neg_hi:[0,1]
	v_pk_add_f32 v[96:97], v[190:191], v[192:193]
	v_pk_add_f32 v[98:99], v[190:191], v[192:193] neg_lo:[0,1] neg_hi:[0,1]
	v_pk_add_f32 v[190:191], v[92:93], v[94:95] op_sel:[0,1] op_sel_hi:[1,0] neg_hi:[0,1]
	v_pk_add_f32 v[192:193], v[92:93], v[94:95] op_sel:[0,1] op_sel_hi:[1,0] neg_lo:[0,1]
	v_pk_mul_f32 v[194:195], v[96:97], v[42:43] op_sel:[0,1] op_sel_hi:[1,1]
	v_pk_mul_f32 v[196:197], v[190:191], v[40:41] op_sel:[0,1] op_sel_hi:[1,1]
	v_pk_mul_f32 v[198:199], v[98:99], v[38:39] op_sel:[0,1] op_sel_hi:[1,1]
	v_pk_mul_f32 v[92:93], v[192:193], v[36:37] op_sel:[0,1] op_sel_hi:[1,1]
	v_pk_fma_f32 v[96:97], v[96:97], v[42:43], v[194:195] op_sel:[0,0,1] op_sel_hi:[1,0,0] neg_lo:[0,0,1]
	v_pk_fma_f32 v[190:191], v[190:191], v[40:41], v[196:197] op_sel:[0,0,1] op_sel_hi:[1,0,0] neg_lo:[0,0,1]
	v_pk_fma_f32 v[98:99], v[98:99], v[38:39], v[198:199] op_sel:[0,0,1] op_sel_hi:[1,0,0] neg_lo:[0,0,1]
	v_pk_fma_f32 v[192:193], v[192:193], v[36:37], v[92:93] op_sel:[0,0,1] op_sel_hi:[1,0,0] neg_lo:[0,0,1]
	v_pk_add_f32 v[194:195], v[96:97], v[98:99]
	v_pk_add_f32 v[196:197], v[190:191], v[192:193]
	v_pk_add_f32 v[198:199], v[96:97], v[98:99] neg_lo:[0,1] neg_hi:[0,1]
	v_pk_add_f32 v[92:93], v[190:191], v[192:193] neg_lo:[0,1] neg_hi:[0,1]
	v_pk_add_f32 v[182:183], v[194:195], v[196:197]
	v_pk_add_f32 v[186:187], v[194:195], v[196:197] neg_lo:[0,1] neg_hi:[0,1]
	v_pk_add_f32 v[184:185], v[198:199], v[92:93] op_sel:[0,1] op_sel_hi:[1,0] neg_lo:[0,1]
	v_pk_add_f32 v[188:189], v[198:199], v[92:93] op_sel:[0,1] op_sel_hi:[1,0] neg_hi:[0,1]
	s_nop 0
	ds_write_b128 v200, v[182:185] offset:52224
	ds_write_b128 v200, v[186:189] offset:52240
	s_waitcnt lgkmcnt(14)
	v_pk_add_f32 v[190:191], v[100:101], v[104:105]
	v_pk_add_f32 v[192:193], v[102:103], v[106:107]
	v_pk_add_f32 v[100:101], v[100:101], v[104:105] neg_lo:[0,1] neg_hi:[0,1]
	v_pk_add_f32 v[102:103], v[102:103], v[106:107] neg_lo:[0,1] neg_hi:[0,1]
	v_pk_add_f32 v[104:105], v[190:191], v[192:193]
	v_pk_add_f32 v[106:107], v[190:191], v[192:193] neg_lo:[0,1] neg_hi:[0,1]
	v_pk_add_f32 v[190:191], v[100:101], v[102:103] op_sel:[0,1] op_sel_hi:[1,0] neg_hi:[0,1]
	v_pk_add_f32 v[192:193], v[100:101], v[102:103] op_sel:[0,1] op_sel_hi:[1,0] neg_lo:[0,1]
	v_pk_mul_f32 v[194:195], v[104:105], v[34:35] op_sel:[0,1] op_sel_hi:[1,1]
	v_pk_mul_f32 v[196:197], v[190:191], v[32:33] op_sel:[0,1] op_sel_hi:[1,1]
	v_pk_mul_f32 v[198:199], v[106:107], v[30:31] op_sel:[0,1] op_sel_hi:[1,1]
	v_pk_mul_f32 v[100:101], v[192:193], v[28:29] op_sel:[0,1] op_sel_hi:[1,1]
	v_pk_fma_f32 v[104:105], v[104:105], v[34:35], v[194:195] op_sel:[0,0,1] op_sel_hi:[1,0,0] neg_lo:[0,0,1]
	v_pk_fma_f32 v[190:191], v[190:191], v[32:33], v[196:197] op_sel:[0,0,1] op_sel_hi:[1,0,0] neg_lo:[0,0,1]
	v_pk_fma_f32 v[106:107], v[106:107], v[30:31], v[198:199] op_sel:[0,0,1] op_sel_hi:[1,0,0] neg_lo:[0,0,1]
	v_pk_fma_f32 v[192:193], v[192:193], v[28:29], v[100:101] op_sel:[0,0,1] op_sel_hi:[1,0,0] neg_lo:[0,0,1]
	v_pk_add_f32 v[194:195], v[104:105], v[106:107]
	v_pk_add_f32 v[196:197], v[190:191], v[192:193]
	v_pk_add_f32 v[198:199], v[104:105], v[106:107] neg_lo:[0,1] neg_hi:[0,1]
	v_pk_add_f32 v[100:101], v[190:191], v[192:193] neg_lo:[0,1] neg_hi:[0,1]
	v_pk_add_f32 v[182:183], v[194:195], v[196:197]
	v_pk_add_f32 v[186:187], v[194:195], v[196:197] neg_lo:[0,1] neg_hi:[0,1]
	v_pk_add_f32 v[184:185], v[198:199], v[100:101] op_sel:[0,1] op_sel_hi:[1,0] neg_lo:[0,1]
	v_pk_add_f32 v[188:189], v[198:199], v[100:101] op_sel:[0,1] op_sel_hi:[1,0] neg_hi:[0,1]
	s_nop 0
	ds_write_b128 v201, v[182:185] offset:0
	ds_write_b128 v201, v[186:189] offset:16
	s_waitcnt lgkmcnt(14)
; #define LAS __attribute__((address_space(3)))
; __device__ __forceinline__ f32x2 cmul(f32x2 a, f32x2 b) { return (f32x2){a.x * b.x - a.y * b.y, a.x * b.y + a.y * b.x}; }
; #define LT() ({ int lt_ = tid; asm volatile("" : "+v"(lt_)); lt_; })
; __device__ __forceinline__ void fft_inv_tail(LAS f32x2* X, const LAS f32x2* TH, const LAS f32x2* TL, int tid) {
;     pass16_s4<true>(X, TH, TL, tid);
; __device__ __forceinline__ void hyena_latent(Frame& F, int l, int ch, LAS f32x2* X, const LAS f32x2* TH, const LAS f32x2* TL, GAS f32x2* KS, const LAS float* CT  , bool wr = true) {
;     ...
;             for (int i = 0; i < 8; ++i) { const int b = LT() + NTHR * i; LAS f32x4* P = (LAS f32x4*)(X + 4 * b + ((b >> 4) << 2)); const f32x4 u = P[0], v = P[1], k0 = kreg[2 * i], k1 = kreg[2 * i + 1];
;                 f32x2 x0 = {u.x, u.y}, x1 = {u.z, u.w}, x2 = {v.x, v.y}, x3 = {v.z, v.w}; r4<false>(x0, x1, x2, x3);
;                 x0 = cmul(x0, (f32x2){k0.x, k0.y}); x1 = cmul(x1, (f32x2){k0.z, k0.w}); x2 = cmul(x2, (f32x2){k1.x, k1.y}); x3 = cmul(x3, (f32x2){k1.z, k1.w});
;                 r4<true>(x0, x1, x2, x3);
;                 P[0] = (f32x4){x0.x, x0.y, x1.x, x1.y}; P[1] = (f32x4){x2.x, x2.y, x3.x, x3.y};
;                 if (i & 1) asm volatile("" ::: "memory"); }
;             __syncthreads();
	v_pk_add_f32 v[190:191], v[108:109], v[112:113]
	v_pk_add_f32 v[192:193], v[110:111], v[114:115]
	v_pk_add_f32 v[108:109], v[108:109], v[112:113] neg_lo:[0,1] neg_hi:[0,1]
	v_pk_add_f32 v[110:111], v[110:111], v[114:115] neg_lo:[0,1] neg_hi:[0,1]
	v_pk_add_f32 v[112:113], v[190:191], v[192:193]
	v_pk_add_f32 v[114:115], v[190:191], v[192:193] neg_lo:[0,1] neg_hi:[0,1]
	v_pk_add_f32 v[190:191], v[108:109], v[110:111] op_sel:[0,1] op_sel_hi:[1,0] neg_hi:[0,1]
	v_pk_add_f32 v[192:193], v[108:109], v[110:111] op_sel:[0,1] op_sel_hi:[1,0] neg_lo:[0,1]
	v_pk_mul_f32 v[194:195], v[112:113], v[26:27] op_sel:[0,1] op_sel_hi:[1,1]
	v_pk_mul_f32 v[196:197], v[190:191], v[24:25] op_sel:[0,1] op_sel_hi:[1,1]
	v_pk_mul_f32 v[198:199], v[114:115], v[22:23] op_sel:[0,1] op_sel_hi:[1,1]
	v_pk_mul_f32 v[108:109], v[192:193], v[20:21] op_sel:[0,1] op_sel_hi:[1,1]
	v_pk_fma_f32 v[112:113], v[112:113], v[26:27], v[194:195] op_sel:[0,0,1] op_sel_hi:[1,0,0] neg_lo:[0,0,1]
	v_pk_fma_f32 v[190:191], v[190:191], v[24:25], v[196:197] op_sel:[0,0,1] op_sel_hi:[1,0,0] neg_lo:[0,0,1]
	v_pk_fma_f32 v[114:115], v[114:115], v[22:23], v[198:199] op_sel:[0,0,1] op_sel_hi:[1,0,0] neg_lo:[0,0,1]
	v_pk_fma_f32 v[192:193], v[192:193], v[20:21], v[108:109] op_sel:[0,0,1] op_sel_hi:[1,0,0] neg_lo:[0,0,1]
	v_pk_add_f32 v[194:195], v[112:113], v[114:115]
	v_pk_add_f32 v[196:197], v[190:191], v[192:193]
	v_pk_add_f32 v[198:199], v[112:113], v[114:115] neg_lo:[0,1] neg_hi:[0,1]
	v_pk_add_f32 v[108:109], v[190:191], v[192:193] neg_lo:[0,1] neg_hi:[0,1]
	v_pk_add_f32 v[182:183], v[194:195], v[196:197]
	v_pk_add_f32 v[186:187], v[194:195], v[196:197] neg_lo:[0,1] neg_hi:[0,1]
	v_pk_add_f32 v[184:185], v[198:199], v[108:109] op_sel:[0,1] op_sel_hi:[1,0] neg_lo:[0,1]
	v_pk_add_f32 v[188:189], v[198:199], v[108:109] op_sel:[0,1] op_sel_hi:[1,0] neg_hi:[0,1]
	s_nop 0
	ds_write_b128 v201, v[182:185] offset:17408
	ds_write_b128 v201, v[186:189] offset:17424
	s_waitcnt lgkmcnt(14)
	v_pk_add_f32 v[190:191], v[116:117], v[120:121]
	v_pk_add_f32 v[192:193], v[118:119], v[122:123]
	v_pk_add_f32 v[116:117], v[116:117], v[120:121] neg_lo:[0,1] neg_hi:[0,1]
	v_pk_add_f32 v[118:119], v[118:119], v[122:123] neg_lo:[0,1] neg_hi:[0,1]
	v_pk_add_f32 v[120:121], v[190:191], v[192:193]
	v_pk_add_f32 v[122:123], v[190:191], v[192:193] neg_lo:[0,1] neg_hi:[0,1]
	v_pk_add_f32 v[190:191], v[116:117], v[118:119] op_sel:[0,1] op_sel_hi:[1,0] neg_hi:[0,1]
	v_pk_add_f32 v[192:193], v[116:117], v[118:119] op_sel:[0,1] op_sel_hi:[1,0] neg_lo:[0,1]
	v_pk_mul_f32 v[194:195], v[120:121], v[18:19] op_sel:[0,1] op_sel_hi:[1,1]
	v_pk_mul_f32 v[196:197], v[190:191], v[16:17] op_sel:[0,1] op_sel_hi:[1,1]
	v_pk_mul_f32 v[198:199], v[122:123], v[14:15] op_sel:[0,1] op_sel_hi:[1,1]
	v_pk_mul_f32 v[116:117], v[192:193], v[12:13] op_sel:[0,1] op_sel_hi:[1,1]
	v_pk_fma_f32 v[120:121], v[120:121], v[18:19], v[194:195] op_sel:[0,0,1] op_sel_hi:[1,0,0] neg_lo:[0,0,1]
	v_pk_fma_f32 v[190:191], v[190:191], v[16:17], v[196:197] op_sel:[0,0,1] op_sel_hi:[1,0,0] neg_lo:[0,0,1]
	v_pk_fma_f32 v[122:123], v[122:123], v[14:15], v[198:199] op_sel:[0,0,1] op_sel_hi:[1,0,0] neg_lo:[0,0,1]
	v_pk_fma_f32 v[192:193], v[192:193], v[12:13], v[116:117] op_sel:[0,0,1] op_sel_hi:[1,0,0] neg_lo:[0,0,1]
	v_pk_add_f32 v[194:195], v[120:121], v[122:123]
	v_pk_add_f32 v[196:197], v[190:191], v[192:193]
	v_pk_add_f32 v[198:199], v[120:121], v[122:123] neg_lo:[0,1] neg_hi:[0,1]
	v_pk_add_f32 v[116:117], v[190:191], v[192:193] neg_lo:[0,1] neg_hi:[0,1]
	v_pk_add_f32 v[182:183], v[194:195], v[196:197]
	v_pk_add_f32 v[186:187], v[194:195], v[196:197] neg_lo:[0,1] neg_hi:[0,1]
	v_pk_add_f32 v[184:185], v[198:199], v[116:117] op_sel:[0,1] op_sel_hi:[1,0] neg_lo:[0,1]
	v_pk_add_f32 v[188:189], v[198:199], v[116:117] op_sel:[0,1] op_sel_hi:[1,0] neg_hi:[0,1]
	s_nop 0
	ds_write_b128 v201, v[182:185] offset:34816
	ds_write_b128 v201, v[186:189] offset:34832
	s_waitcnt lgkmcnt(14)
	v_pk_add_f32 v[190:191], v[124:125], v[178:179]
	v_pk_add_f32 v[192:193], v[126:127], v[180:181]
	v_pk_add_f32 v[124:125], v[124:125], v[178:179] neg_lo:[0,1] neg_hi:[0,1]
	v_pk_add_f32 v[126:127], v[126:127], v[180:181] neg_lo:[0,1] neg_hi:[0,1]
	v_pk_add_f32 v[178:179], v[190:191], v[192:193]
	v_pk_add_f32 v[180:181], v[190:191], v[192:193] neg_lo:[0,1] neg_hi:[0,1]
	v_pk_add_f32 v[190:191], v[124:125], v[126:127] op_sel:[0,1] op_sel_hi:[1,0] neg_hi:[0,1]
	v_pk_add_f32 v[192:193], v[124:125], v[126:127] op_sel:[0,1] op_sel_hi:[1,0] neg_lo:[0,1]
	v_pk_mul_f32 v[194:195], v[178:179], v[6:7] op_sel:[0,1] op_sel_hi:[1,1]
	v_pk_mul_f32 v[196:197], v[190:191], v[4:5] op_sel:[0,1] op_sel_hi:[1,1]
	v_pk_mul_f32 v[198:199], v[180:181], v[2:3] op_sel:[0,1] op_sel_hi:[1,1]
	v_pk_mul_f32 v[124:125], v[192:193], v[0:1] op_sel:[0,1] op_sel_hi:[1,1]
	v_pk_fma_f32 v[178:179], v[178:179], v[6:7], v[194:195] op_sel:[0,0,1] op_sel_hi:[1,0,0] neg_lo:[0,0,1]
	v_pk_fma_f32 v[190:191], v[190:191], v[4:5], v[196:197] op_sel:[0,0,1] op_sel_hi:[1,0,0] neg_lo:[0,0,1]
	v_pk_fma_f32 v[180:181], v[180:181], v[2:3], v[198:199] op_sel:[0,0,1] op_sel_hi:[1,0,0] neg_lo:[0,0,1]
	v_pk_fma_f32 v[192:193], v[192:193], v[0:1], v[124:125] op_sel:[0,0,1] op_sel_hi:[1,0,0] neg_lo:[0,0,1]
	v_pk_add_f32 v[194:195], v[178:179], v[180:181]
	v_pk_add_f32 v[196:197], v[190:191], v[192:193]
	v_pk_add_f32 v[198:199], v[178:179], v[180:181] neg_lo:[0,1] neg_hi:[0,1]
	v_pk_add_f32 v[124:125], v[190:191], v[192:193] neg_lo:[0,1] neg_hi:[0,1]
	v_pk_add_f32 v[182:183], v[194:195], v[196:197]
	v_pk_add_f32 v[186:187], v[194:195], v[196:197] neg_lo:[0,1] neg_hi:[0,1]
	v_pk_add_f32 v[184:185], v[198:199], v[124:125] op_sel:[0,1] op_sel_hi:[1,0] neg_lo:[0,1]
	v_pk_add_f32 v[188:189], v[198:199], v[124:125] op_sel:[0,1] op_sel_hi:[1,0] neg_hi:[0,1]
	s_nop 0
	ds_write_b128 v201, v[182:185] offset:52224
	ds_write_b128 v201, v[186:189] offset:52240
	s_waitcnt lgkmcnt(0)
	s_barrier
	ds_read2_b64 v[232:235], v141 offset0:4 offset1:8
	ds_read2_b64 v[208:211], v141 offset0:12 offset1:16
	ds_read2_b64 v[204:207], v141 offset0:20 offset1:24
	ds_read2_b64 v[200:203], v141 offset0:28 offset1:32
	ds_read2_b64 v[196:199], v141 offset0:36 offset1:40
	ds_read2_b64 v[192:195], v141 offset0:44 offset1:48
	ds_read2_b64 v[188:191], v141 offset0:52 offset1:56
	ds_read_b64 v[186:187], v141 offset:480
; #define LAS __attribute__((address_space(3)))
; template <bool INV> __device__ __forceinline__ void dft16(f32x2 (&x)[16]) {
; #pragma unroll
;     for (int b = 0; b < 4; ++b) r4<INV>(x[b], x[4 + b], x[8 + b], x[12 + b]);
;     const float sg = INV ? -1.f : 1.f;
;     const f32x2 W1 = {0.92387953251f, -0.38268343236f * sg}, W2 = {0.70710678118f, -0.70710678118f * sg}, W3 = {0.38268343236f, -0.92387953251f * sg},
;                 W4 = {0.f, -1.f * sg}, W6 = {-0.70710678118f, -0.70710678118f * sg}, W9 = {-0.92387953251f, 0.38268343236f * sg};
;     x[5] = cmul(x[5], W1); x[9] = cmul(x[9], W2); x[13] = cmul(x[13], W3);
;     x[6] = cmul(x[6], W2); x[10] = cmul(x[10], W4); x[14] = cmul(x[14], W6);
;     x[7] = cmul(x[7], W3); x[11] = cmul(x[11], W6); x[15] = cmul(x[15], W9);
; #pragma unroll
;     for (int c = 0; c < 4; ++c) r4<INV>(x[4 * c], x[4 * c + 1], x[4 * c + 2], x[4 * c + 3]);
; }
; template <bool INV> __device__ __forceinline__ void bfly16(f32x2 (&x)[16], const LAS f32x2* TH, const LAS f32x2* TL, int tw) {
;     f32x2 W = tw32k(TH, TL, tw); if (INV) W.y = -W.y;
;     if (INV) { f32x2 p = W;
; #pragma unroll
;         for (int q = 1; q < 16; ++q) { x[q] = cmul(x[q], p); if (q < 15) p = cmul(p, W); } }
;     dft16<INV>(x);
;     if (!INV) { f32x2 p = W;
; #pragma unroll
;         for (int r = 1; r < 16; ++r) { x[4 * (r & 3) + (r >> 2)] = cmul(x[4 * (r & 3) + (r >> 2)], p); if (r < 15) p = cmul(p, W); } }
; }
; template <bool INV> __device__ __forceinline__ void bfly16_tab(f32x2 (&x)[16], const LAS f32x2* T, int tstride, int j) {
;     if (INV) {
; #pragma unroll
;         for (int q = 1; q < 16; ++q) { f32x2 p = T[q * tstride + j]; p.y = -p.y; x[q] = cmul(x[q], p); } }
;     dft16<INV>(x);
;     if (!INV) {
; #pragma unroll
; template <bool INV> __device__ __forceinline__ void pass16_s4(LAS f32x2* X, const LAS f32x2* TH, const LAS f32x2* TL, int tid) {
; #pragma unroll 1
;     for (int s = 0; s < 2; ++s) {
;         const int b = tid + NTHR * s, blk = b >> 2, jj = b & 3;
;         LAS f32x2* P = X + blk * 68 + jj;
;         f32x2 x[16];
; #pragma unroll
;         for (int q = 0; q < 16; ++q) x[q] = P[4 * q];
;         bfly16_tab<INV>(x, TH - 1024, 4, jj);
; #pragma unroll
;         for (int c = 0; c < 4; ++c)
; #pragma unroll
;             for (int d = 0; d < 4; ++d) P[4 * (c + 4 * d)] = x[4 * c + d];
;     }
; }
.LBB0_852:
	v_add_u32_e32 v128, s0, v140
	v_lshrrev_b32_e32 v147, 2, v128
	v_mad_u32_u24 v151, v147, s43, v144
	ds_read_b64 v[0:1], v151 offset:128
	ds_read_b64 v[2:3], v151 offset:32
	ds_read_b64 v[4:5], v151 offset:64
	ds_read_b64 v[6:7], v151 offset:96
	ds_read_b64 v[8:9], v151 offset:160
	ds_read_b64 v[10:11], v151 offset:192
	ds_read_b64 v[12:13], v151 offset:224
	ds_read_b64 v[14:15], v151 offset:0
	ds_read_b64 v[16:17], v151 offset:256
	ds_read_b64 v[18:19], v151 offset:384
	ds_read_b64 v[20:21], v151 offset:288
	ds_read_b64 v[22:23], v151 offset:320
	ds_read_b64 v[24:25], v151 offset:352
	ds_read_b64 v[26:27], v151 offset:416
	ds_read_b64 v[28:29], v151 offset:448
	ds_read_b64 v[30:31], v151 offset:480
	s_cmp_eq_u32 s0, 0
	s_movk_i32 s0, 0x200
	s_mov_b64 s[12:13], 0
	s_waitcnt lgkmcnt(15)
	v_pk_mul_f32 v[32:33], v[0:1], v[210:211] op_sel:[0,1] op_sel_hi:[1,1]
	s_waitcnt lgkmcnt(14)
	v_pk_mul_f32 v[34:35], v[2:3], v[232:233] op_sel:[0,1] op_sel_hi:[1,1]
	s_waitcnt lgkmcnt(13)
	v_pk_mul_f32 v[36:37], v[4:5], v[234:235] op_sel:[0,1] op_sel_hi:[1,1]
	s_waitcnt lgkmcnt(12)
	v_pk_mul_f32 v[38:39], v[6:7], v[208:209] op_sel:[0,1] op_sel_hi:[1,1]
	v_pk_fma_f32 v[32:33], v[0:1], v[210:211], v[32:33] op_sel:[0,0,1] op_sel_hi:[1,0,0] neg_hi:[0,0,1]
	s_waitcnt lgkmcnt(11)
	v_pk_mul_f32 v[0:1], v[8:9], v[204:205] op_sel:[0,1] op_sel_hi:[1,1]
	s_waitcnt lgkmcnt(10)
	v_pk_mul_f32 v[40:41], v[10:11], v[206:207] op_sel:[0,1] op_sel_hi:[1,1]
	s_waitcnt lgkmcnt(9)
	v_pk_mul_f32 v[42:43], v[12:13], v[200:201] op_sel:[0,1] op_sel_hi:[1,1]
	s_waitcnt lgkmcnt(7)
	v_pk_fma_f32 v[44:45], v[16:17], v[202:203], v[14:15] op_sel:[0,1,1] op_sel_hi:[1,1,0] neg_lo:[0,0,1]
	v_pk_fma_f32 v[2:3], v[2:3], v[232:233], v[34:35] op_sel:[0,0,1] op_sel_hi:[1,0,0] neg_hi:[0,0,1]
	v_pk_fma_f32 v[4:5], v[4:5], v[234:235], v[36:37] op_sel:[0,0,1] op_sel_hi:[1,0,0] neg_hi:[0,0,1]
	v_pk_fma_f32 v[38:39], v[6:7], v[208:209], v[38:39] op_sel:[0,0,1] op_sel_hi:[1,0,0] neg_hi:[0,0,1]
	v_pk_fma_f32 v[16:17], v[16:17], v[202:203], v[44:45] op_sel:[0,0,1] op_sel_hi:[1,0,0] neg_hi:[0,0,1]
	v_pk_fma_f32 v[8:9], v[8:9], v[204:205], v[0:1] op_sel:[0,0,1] op_sel_hi:[1,0,0] neg_hi:[0,0,1]
	v_pk_fma_f32 v[10:11], v[10:11], v[206:207], v[40:41] op_sel:[0,0,1] op_sel_hi:[1,0,0] neg_hi:[0,0,1]
	v_pk_fma_f32 v[12:13], v[12:13], v[200:201], v[42:43] op_sel:[0,0,1] op_sel_hi:[1,0,0] neg_hi:[0,0,1]
	s_waitcnt lgkmcnt(6)
	v_pk_fma_f32 v[42:43], v[18:19], v[194:195], v[32:33] op_sel:[0,1,1] op_sel_hi:[1,1,0] neg_lo:[0,0,1]
	s_waitcnt lgkmcnt(5)
	v_pk_fma_f32 v[40:41], v[20:21], v[196:197], v[2:3] op_sel:[0,1,1] op_sel_hi:[1,1,0] neg_lo:[0,0,1]
	s_waitcnt lgkmcnt(4)
	v_pk_fma_f32 v[0:1], v[22:23], v[198:199], v[4:5] op_sel:[0,1,1] op_sel_hi:[1,1,0] neg_lo:[0,0,1]
	s_waitcnt lgkmcnt(3)
	v_pk_fma_f32 v[44:45], v[24:25], v[192:193], v[38:39] op_sel:[0,1,1] op_sel_hi:[1,1,0] neg_lo:[0,0,1]
	v_pk_fma_f32 v[18:19], v[18:19], v[194:195], v[42:43] op_sel:[0,0,1] op_sel_hi:[1,0,0] neg_hi:[0,0,1]
	v_pk_fma_f32 v[40:41], v[20:21], v[196:197], v[40:41] op_sel:[0,0,1] op_sel_hi:[1,0,0] neg_hi:[0,0,1]
	v_pk_fma_f32 v[0:1], v[22:23], v[198:199], v[0:1] op_sel:[0,0,1] op_sel_hi:[1,0,0] neg_hi:[0,0,1]
	v_pk_fma_f32 v[44:45], v[24:25], v[192:193], v[44:45] op_sel:[0,0,1] op_sel_hi:[1,0,0] neg_hi:[0,0,1]
	v_pk_fma_f32 v[14:15], v[14:15], s[100:101], v[16:17] op_sel_hi:[1,0,1] neg_lo:[0,0,1] neg_hi:[0,0,1]
	s_waitcnt lgkmcnt(2)
	v_pk_fma_f32 v[24:25], v[26:27], v[188:189], v[8:9] op_sel:[0,1,1] op_sel_hi:[1,1,0] neg_lo:[0,0,1]
	s_waitcnt lgkmcnt(1)
	v_pk_fma_f32 v[22:23], v[28:29], v[190:191], v[10:11] op_sel:[0,1,1] op_sel_hi:[1,1,0] neg_lo:[0,0,1]
	s_waitcnt lgkmcnt(0)
	v_pk_fma_f32 v[20:21], v[30:31], v[186:187], v[12:13] op_sel:[0,1,1] op_sel_hi:[1,1,0] neg_lo:[0,0,1]
	v_pk_fma_f32 v[32:33], v[32:33], s[100:101], v[18:19] op_sel_hi:[1,0,1] neg_lo:[0,0,1] neg_hi:[0,0,1]
	v_pk_fma_f32 v[24:25], v[26:27], v[188:189], v[24:25] op_sel:[0,0,1] op_sel_hi:[1,0,0] neg_hi:[0,0,1]
	v_pk_fma_f32 v[28:29], v[28:29], v[190:191], v[22:23] op_sel:[0,0,1] op_sel_hi:[1,0,0] neg_hi:[0,0,1]
	v_pk_fma_f32 v[30:31], v[30:31], v[186:187], v[20:21] op_sel:[0,0,1] op_sel_hi:[1,0,0] neg_hi:[0,0,1]
	v_pk_add_f32 v[20:21], v[16:17], v[18:19]
	v_pk_fma_f32 v[2:3], v[2:3], s[100:101], v[40:41] op_sel_hi:[1,0,1] neg_lo:[0,0,1] neg_hi:[0,0,1]
	v_pk_fma_f32 v[4:5], v[4:5], s[100:101], v[0:1] op_sel_hi:[1,0,1] neg_lo:[0,0,1] neg_hi:[0,0,1]
	v_pk_fma_f32 v[38:39], v[38:39], s[100:101], v[44:45] op_sel_hi:[1,0,1] neg_lo:[0,0,1] neg_hi:[0,0,1]
	v_pk_add_f32 v[16:17], v[16:17], v[18:19] neg_lo:[0,1] neg_hi:[0,1]
	v_pk_fma_f32 v[8:9], v[8:9], s[100:101], v[24:25] op_sel_hi:[1,0,1] neg_lo:[0,0,1] neg_hi:[0,0,1]
	v_pk_fma_f32 v[10:11], v[10:11], s[100:101], v[28:29] op_sel_hi:[1,0,1] neg_lo:[0,0,1] neg_hi:[0,0,1]
	v_pk_fma_f32 v[12:13], v[12:13], s[100:101], v[30:31] op_sel_hi:[1,0,1] neg_lo:[0,0,1] neg_hi:[0,0,1]
	v_pk_add_f32 v[18:19], v[14:15], v[32:33] op_sel:[0,1] op_sel_hi:[1,0] neg_lo:[0,1]
	v_pk_add_f32 v[22:23], v[40:41], v[24:25]
	v_pk_add_f32 v[26:27], v[0:1], v[28:29]
	v_pk_add_f32 v[42:43], v[44:45], v[30:31]
	v_pk_add_f32 v[14:15], v[14:15], v[32:33] op_sel:[0,1] op_sel_hi:[1,0] neg_hi:[0,1]
	v_pk_add_f32 v[24:25], v[40:41], v[24:25] neg_lo:[0,1] neg_hi:[0,1]
	v_pk_add_f32 v[0:1], v[0:1], v[28:29] neg_lo:[0,1] neg_hi:[0,1]
	v_pk_add_f32 v[30:31], v[44:45], v[30:31] neg_lo:[0,1] neg_hi:[0,1]
	v_pk_add_f32 v[44:45], v[2:3], v[8:9] op_sel:[0,1] op_sel_hi:[1,0] neg_lo:[0,1]
	v_pk_add_f32 v[28:29], v[4:5], v[10:11] op_sel:[0,1] op_sel_hi:[1,0] neg_lo:[0,1]
	v_pk_add_f32 v[40:41], v[38:39], v[12:13] op_sel:[0,1] op_sel_hi:[1,0] neg_lo:[0,1]
; template <bool INV> __device__ __forceinline__ void dft16(f32x2 (&x)[16]) {
; #pragma unroll
;     for (int b = 0; b < 4; ++b) r4<INV>(x[b], x[4 + b], x[8 + b], x[12 + b]);
;     const float sg = INV ? -1.f : 1.f;
;     const f32x2 W1 = {0.92387953251f, -0.38268343236f * sg}, W2 = {0.70710678118f, -0.70710678118f * sg}, W3 = {0.38268343236f, -0.92387953251f * sg},
;                 W4 = {0.f, -1.f * sg}, W6 = {-0.70710678118f, -0.70710678118f * sg}, W9 = {-0.92387953251f, 0.38268343236f * sg};
;     x[5] = cmul(x[5], W1); x[9] = cmul(x[9], W2); x[13] = cmul(x[13], W3);
;     x[6] = cmul(x[6], W2); x[10] = cmul(x[10], W4); x[14] = cmul(x[14], W6);
;     x[7] = cmul(x[7], W3); x[11] = cmul(x[11], W6); x[15] = cmul(x[15], W9);
; #pragma unroll
;     for (int c = 0; c < 4; ++c) r4<INV>(x[4 * c], x[4 * c + 1], x[4 * c + 2], x[4 * c + 3]);
; }
; template <bool INV> __device__ __forceinline__ void bfly16(f32x2 (&x)[16], const LAS f32x2* TH, const LAS f32x2* TL, int tw) {
;     f32x2 W = tw32k(TH, TL, tw); if (INV) W.y = -W.y;
;     if (INV) { f32x2 p = W;
; #pragma unroll
;         for (int q = 1; q < 16; ++q) { x[q] = cmul(x[q], p); if (q < 15) p = cmul(p, W); } }
;     dft16<INV>(x);
;     if (!INV) { f32x2 p = W;
; #pragma unroll
;         for (int r = 1; r < 16; ++r) { x[4 * (r & 3) + (r >> 2)] = cmul(x[4 * (r & 3) + (r >> 2)], p); if (r < 15) p = cmul(p, W); } }
; }
; template <bool INV> __device__ __forceinline__ void bfly16_tab(f32x2 (&x)[16], const LAS f32x2* T, int tstride, int j) {
;     if (INV) {
; #pragma unroll
;         for (int q = 1; q < 16; ++q) { f32x2 p = T[q * tstride + j]; p.y = -p.y; x[q] = cmul(x[q], p); } }
;     dft16<INV>(x);
;     if (!INV) {
; #pragma unroll
;         for (int r = 1; r < 16; ++r) { const f32x2 p = T[r * tstride + j]; x[4 * (r & 3) + (r >> 2)] = cmul(x[4 * (r & 3) + (r >> 2)], p); } }
; }
; template <bool INV> __device__ __forceinline__ void pass16_s4(LAS f32x2* X, const LAS f32x2* TH, const LAS f32x2* TL, int tid) {
; #pragma unroll 1
;     for (int s = 0; s < 2; ++s) {
;         const int b = tid + NTHR * s, blk = b >> 2, jj = b & 3;
;         LAS f32x2* P = X + blk * 68 + jj;
;         f32x2 x[16];
; #pragma unroll
;         for (int q = 0; q < 16; ++q) x[q] = P[4 * q];
;         bfly16_tab<INV>(x, TH - 1024, 4, jj);
; #pragma unroll
;         for (int c = 0; c < 4; ++c)
; #pragma unroll
	v_pk_add_f32 v[8:9], v[2:3], v[8:9] op_sel:[0,1] op_sel_hi:[1,0] neg_hi:[0,1]
	v_pk_add_f32 v[4:5], v[4:5], v[10:11] op_sel:[0,1] op_sel_hi:[1,0] neg_hi:[0,1]
	v_pk_add_f32 v[38:39], v[38:39], v[12:13] op_sel:[0,1] op_sel_hi:[1,0] neg_hi:[0,1]
	v_pk_add_f32 v[12:13], v[20:21], v[26:27]
	v_pk_mul_f32 v[10:11], v[44:45], s[82:83] op_sel_hi:[1,0]
	v_pk_mul_f32 v[2:3], v[24:25], s[76:77] op_sel_hi:[1,0]
	v_pk_mul_f32 v[32:33], v[8:9], s[44:45] op_sel_hi:[1,0]
	v_pk_add_f32 v[26:27], v[20:21], v[26:27] neg_lo:[0,1] neg_hi:[0,1]
	v_pk_fma_f32 v[10:11], v[44:45], s[44:45], v[10:11] op_sel:[0,0,1] op_sel_hi:[1,0,0] neg_lo:[0,0,1]
	v_pk_fma_f32 v[24:25], v[24:25], s[76:77], v[2:3] op_sel:[0,0,1] op_sel_hi:[1,0,0] neg_lo:[0,0,1]
	v_pk_fma_f32 v[8:9], v[8:9], s[82:83], v[32:33] op_sel:[0,0,1] op_sel_hi:[1,0,0] neg_lo:[0,0,1]
	v_pk_add_f32 v[32:33], v[22:23], v[42:43]
	v_pk_fma_f32 v[2:3], v[28:29], s[76:77], v[18:19] op_sel:[0,0,1] op_sel_hi:[1,0,0] neg_hi:[0,0,1]
	v_pk_add_f32 v[44:45], v[16:17], v[0:1] op_sel:[0,1] op_sel_hi:[1,0] neg_lo:[0,1]
	v_pk_fma_f32 v[20:21], v[4:5], s[76:77], v[14:15] op_sel:[0,0,1] op_sel_hi:[1,0,0] neg_hi:[0,0,1]
	v_pk_add_f32 v[22:23], v[22:23], v[42:43] neg_lo:[0,1] neg_hi:[0,1]
	v_pk_fma_f32 v[28:29], v[28:29], s[76:77], v[2:3] op_sel:[0,0,1] op_sel_hi:[1,0,0] neg_lo:[0,0,1]
	v_pk_add_f32 v[16:17], v[16:17], v[0:1] op_sel:[0,1] op_sel_hi:[1,0] neg_hi:[0,1]
	v_pk_fma_f32 v[20:21], v[4:5], s[72:73], v[20:21] op_sel:[0,0,1] op_sel_hi:[1,0,0] neg_lo:[0,0,1]
	v_pk_add_f32 v[4:5], v[12:13], v[32:33]
	v_pk_fma_f32 v[18:19], v[18:19], s[100:101], v[28:29] op_sel_hi:[1,0,1] neg_lo:[0,0,1] neg_hi:[0,0,1]
	v_pk_fma_f32 v[0:1], v[30:31], s[76:77], v[24:25] op_sel:[0,0,1] op_sel_hi:[1,0,0] neg_hi:[0,0,1]
	v_pk_fma_f32 v[14:15], v[14:15], s[100:101], v[20:21] op_sel_hi:[1,0,1] neg_lo:[0,0,1] neg_hi:[0,0,1]
	v_pk_add_f32 v[32:33], v[12:13], v[32:33] neg_lo:[0,1] neg_hi:[0,1]
	v_pk_fma_f32 v[12:13], v[40:41], s[44:45], v[10:11] op_sel:[0,0,1] op_sel_hi:[1,0,0] neg_hi:[0,0,1]
	v_pk_fma_f32 v[0:1], v[30:31], s[72:73], v[0:1] op_sel:[0,0,1] op_sel_hi:[1,0,0] neg_lo:[0,0,1]
	v_pk_fma_f32 v[30:31], v[38:39], s[70:71], v[8:9] op_sel:[0,0,1] op_sel_hi:[1,0,0] neg_hi:[0,0,1]
	v_pk_add_f32 v[2:3], v[26:27], v[22:23] op_sel:[0,1] op_sel_hi:[1,0] neg_lo:[0,1]
	v_pk_fma_f32 v[40:41], v[40:41], s[82:83], v[12:13] op_sel:[0,0,1] op_sel_hi:[1,0,0] neg_lo:[0,0,1]
	v_pk_fma_f32 v[24:25], v[24:25], s[100:101], v[0:1] op_sel_hi:[1,0,1] neg_lo:[0,0,1] neg_hi:[0,0,1]
	v_pk_fma_f32 v[38:39], v[38:39], s[64:65], v[30:31] op_sel:[0,0,1] op_sel_hi:[1,0,0] neg_lo:[0,0,1]
	v_pk_add_f32 v[22:23], v[26:27], v[22:23] op_sel:[0,1] op_sel_hi:[1,0] neg_hi:[0,1]
	v_pk_fma_f32 v[10:11], v[10:11], s[100:101], v[40:41] op_sel_hi:[1,0,1] neg_lo:[0,0,1] neg_hi:[0,0,1]
	v_pk_add_f32 v[26:27], v[44:45], v[0:1]
	v_pk_fma_f32 v[8:9], v[8:9], s[100:101], v[38:39] op_sel_hi:[1,0,1] neg_lo:[0,0,1] neg_hi:[0,0,1]
	v_pk_add_f32 v[30:31], v[28:29], v[40:41]
	v_pk_add_f32 v[44:45], v[44:45], v[0:1] neg_lo:[0,1] neg_hi:[0,1]
	v_pk_add_f32 v[0:1], v[20:21], v[38:39]
	v_pk_add_f32 v[40:41], v[28:29], v[40:41] neg_lo:[0,1] neg_hi:[0,1]
	v_pk_add_f32 v[28:29], v[16:17], v[24:25] op_sel:[0,1] op_sel_hi:[1,0] neg_lo:[0,1]
	v_pk_add_f32 v[38:39], v[20:21], v[38:39] neg_lo:[0,1] neg_hi:[0,1]
	v_pk_add_f32 v[20:21], v[18:19], v[10:11] op_sel:[0,1] op_sel_hi:[1,0] neg_lo:[0,1]
	v_pk_add_f32 v[24:25], v[16:17], v[24:25] op_sel:[0,1] op_sel_hi:[1,0] neg_hi:[0,1]
	v_pk_add_f32 v[16:17], v[14:15], v[8:9] op_sel:[0,1] op_sel_hi:[1,0] neg_lo:[0,1]
	v_pk_add_f32 v[18:19], v[18:19], v[10:11] op_sel:[0,1] op_sel_hi:[1,0] neg_hi:[0,1]
	v_pk_add_f32 v[14:15], v[14:15], v[8:9] op_sel:[0,1] op_sel_hi:[1,0] neg_hi:[0,1]
	ds_write_b64 v151, v[4:5] offset:0
	ds_write_b64 v151, v[30:31] offset:32
	ds_write_b64 v151, v[26:27] offset:64
	ds_write_b64 v151, v[0:1] offset:96
	ds_write_b64 v151, v[2:3] offset:128
	ds_write_b64 v151, v[20:21] offset:160
	ds_write_b64 v151, v[28:29] offset:192
	ds_write_b64 v151, v[16:17] offset:224
	ds_write_b64 v151, v[32:33] offset:256
	ds_write_b64 v151, v[40:41] offset:288
	ds_write_b64 v151, v[44:45] offset:320
	ds_write_b64 v151, v[38:39] offset:352
	ds_write_b64 v151, v[22:23] offset:384
	ds_write_b64 v151, v[18:19] offset:416
	ds_write_b64 v151, v[24:25] offset:448
	ds_write_b64 v151, v[14:15] offset:480
	s_cbranch_scc1 .LBB0_852
	s_waitcnt lgkmcnt(0)
	s_barrier
	s_mov_b32 s0, 0
	s_mov_b64 s[12:13], -1
	ds_read2st64_b64 v[232:235], v139 offset0:1 offset1:2
	ds_read2st64_b64 v[208:211], v139 offset0:3 offset1:4
	ds_read2st64_b64 v[204:207], v139 offset0:5 offset1:6
	ds_read2st64_b64 v[200:203], v139 offset0:7 offset1:8
	ds_read2st64_b64 v[196:199], v139 offset0:9 offset1:10
	ds_read2st64_b64 v[192:195], v139 offset0:11 offset1:12
	ds_read2st64_b64 v[188:191], v139 offset0:13 offset1:14
	ds_read_b64 v[186:187], v139 offset:7680
; #define LAS __attribute__((address_space(3)))
; template <bool INV> __device__ __forceinline__ void dft16(f32x2 (&x)[16]) {
; #pragma unroll
;     for (int b = 0; b < 4; ++b) r4<INV>(x[b], x[4 + b], x[8 + b], x[12 + b]);
;     const float sg = INV ? -1.f : 1.f;
;     const f32x2 W1 = {0.92387953251f, -0.38268343236f * sg}, W2 = {0.70710678118f, -0.70710678118f * sg}, W3 = {0.38268343236f, -0.92387953251f * sg},
;                 W4 = {0.f, -1.f * sg}, W6 = {-0.70710678118f, -0.70710678118f * sg}, W9 = {-0.92387953251f, 0.38268343236f * sg};
;     x[5] = cmul(x[5], W1); x[9] = cmul(x[9], W2); x[13] = cmul(x[13], W3);
;     x[6] = cmul(x[6], W2); x[10] = cmul(x[10], W4); x[14] = cmul(x[14], W6);
;     x[7] = cmul(x[7], W3); x[11] = cmul(x[11], W6); x[15] = cmul(x[15], W9);
; #pragma unroll
;     for (int c = 0; c < 4; ++c) r4<INV>(x[4 * c], x[4 * c + 1], x[4 * c + 2], x[4 * c + 3]);
; }
; template <bool INV> __device__ __forceinline__ void bfly16(f32x2 (&x)[16], const LAS f32x2* TH, const LAS f32x2* TL, int tw) {
;     f32x2 W = tw32k(TH, TL, tw); if (INV) W.y = -W.y;
;     if (INV) { f32x2 p = W;
; #pragma unroll
;         for (int q = 1; q < 16; ++q) { x[q] = cmul(x[q], p); if (q < 15) p = cmul(p, W); } }
;     dft16<INV>(x);
;     if (!INV) { f32x2 p = W;
; #pragma unroll
;         for (int r = 1; r < 16; ++r) { x[4 * (r & 3) + (r >> 2)] = cmul(x[4 * (r & 3) + (r >> 2)], p); if (r < 15) p = cmul(p, W); } }
; }
; template <bool INV> __device__ __forceinline__ void bfly16_tab(f32x2 (&x)[16], const LAS f32x2* T, int tstride, int j) {
;     if (INV) {
; #pragma unroll
;         for (int q = 1; q < 16; ++q) { f32x2 p = T[q * tstride + j]; p.y = -p.y; x[q] = cmul(x[q], p); } }
;     dft16<INV>(x);
;     if (!INV) {
; #pragma unroll
;         for (int r = 1; r < 16; ++r) { const f32x2 p = T[r * tstride + j]; x[4 * (r & 3) + (r >> 2)] = cmul(x[4 * (r & 3) + (r >> 2)], p); } }
; }
; template <bool INV> __device__ __forceinline__ void pass16_s64(LAS f32x2* X, const LAS f32x2* TH, int base, int j) {
;     f32x2 x[16];
; #pragma unroll
;     for (int q = 0; q < 16; ++q) x[q] = X[base + q * 68];
;     bfly16_tab<INV>(x, TH - 2048, 64, j);
; #pragma unroll
;     for (int c = 0; c < 4; ++c)
; #pragma unroll
;         for (int d = 0; d < 4; ++d) X[base + (c + 4 * d) * 68] = x[4 * c + d];
; }
.LBB0_854:
	v_add_u32_e32 v128, s0, v140
	v_lshrrev_b32_e32 v147, 6, v128
	v_mad_u32_u24 v151, v147, s77, v142
	ds_read_b64 v[0:1], v151 offset:2176
	ds_read_b64 v[2:3], v151 offset:544
	ds_read_b64 v[4:5], v151 offset:1088
	ds_read_b64 v[6:7], v151 offset:1632
	ds_read_b64 v[8:9], v151 offset:2720
	ds_read_b64 v[10:11], v151 offset:3264
	ds_read_b64 v[12:13], v151 offset:3808
	ds_read_b64 v[14:15], v151 offset:0
	ds_read_b64 v[16:17], v151 offset:4352
	ds_read_b64 v[18:19], v151 offset:6528
	ds_read_b64 v[20:21], v151 offset:4896
	ds_read_b64 v[22:23], v151 offset:5440
	ds_read_b64 v[24:25], v151 offset:5984
	ds_read_b64 v[26:27], v151 offset:7072
	ds_read_b64 v[28:29], v151 offset:7616
	ds_read_b64 v[30:31], v151 offset:8160
	s_cmp_eq_u32 s0, 0
	s_movk_i32 s0, 0x200
	s_mov_b64 s[12:13], 0
	s_waitcnt lgkmcnt(15)
	v_pk_mul_f32 v[32:33], v[0:1], v[210:211] op_sel:[0,1] op_sel_hi:[1,1]
	s_waitcnt lgkmcnt(14)
	v_pk_mul_f32 v[34:35], v[2:3], v[232:233] op_sel:[0,1] op_sel_hi:[1,1]
	s_waitcnt lgkmcnt(13)
	v_pk_mul_f32 v[36:37], v[4:5], v[234:235] op_sel:[0,1] op_sel_hi:[1,1]
	s_waitcnt lgkmcnt(12)
	v_pk_mul_f32 v[38:39], v[6:7], v[208:209] op_sel:[0,1] op_sel_hi:[1,1]
	v_pk_fma_f32 v[32:33], v[0:1], v[210:211], v[32:33] op_sel:[0,0,1] op_sel_hi:[1,0,0] neg_hi:[0,0,1]
	s_waitcnt lgkmcnt(11)
	v_pk_mul_f32 v[0:1], v[8:9], v[204:205] op_sel:[0,1] op_sel_hi:[1,1]
	s_waitcnt lgkmcnt(10)
	v_pk_mul_f32 v[40:41], v[10:11], v[206:207] op_sel:[0,1] op_sel_hi:[1,1]
	s_waitcnt lgkmcnt(9)
	v_pk_mul_f32 v[42:43], v[12:13], v[200:201] op_sel:[0,1] op_sel_hi:[1,1]
	s_waitcnt lgkmcnt(7)
	v_pk_fma_f32 v[44:45], v[16:17], v[202:203], v[14:15] op_sel:[0,1,1] op_sel_hi:[1,1,0] neg_lo:[0,0,1]
	v_pk_fma_f32 v[2:3], v[2:3], v[232:233], v[34:35] op_sel:[0,0,1] op_sel_hi:[1,0,0] neg_hi:[0,0,1]
	v_pk_fma_f32 v[4:5], v[4:5], v[234:235], v[36:37] op_sel:[0,0,1] op_sel_hi:[1,0,0] neg_hi:[0,0,1]
	v_pk_fma_f32 v[38:39], v[6:7], v[208:209], v[38:39] op_sel:[0,0,1] op_sel_hi:[1,0,0] neg_hi:[0,0,1]
	v_pk_fma_f32 v[44:45], v[16:17], v[202:203], v[44:45] op_sel:[0,0,1] op_sel_hi:[1,0,0] neg_hi:[0,0,1]
	v_pk_fma_f32 v[0:1], v[8:9], v[204:205], v[0:1] op_sel:[0,0,1] op_sel_hi:[1,0,0] neg_hi:[0,0,1]
	v_pk_fma_f32 v[40:41], v[10:11], v[206:207], v[40:41] op_sel:[0,0,1] op_sel_hi:[1,0,0] neg_hi:[0,0,1]
	v_pk_fma_f32 v[12:13], v[12:13], v[200:201], v[42:43] op_sel:[0,0,1] op_sel_hi:[1,0,0] neg_hi:[0,0,1]
	s_waitcnt lgkmcnt(6)
	v_pk_fma_f32 v[42:43], v[18:19], v[194:195], v[32:33] op_sel:[0,1,1] op_sel_hi:[1,1,0] neg_lo:[0,0,1]
	s_waitcnt lgkmcnt(5)
	v_pk_fma_f32 v[10:11], v[20:21], v[196:197], v[2:3] op_sel:[0,1,1] op_sel_hi:[1,1,0] neg_lo:[0,0,1]
	s_waitcnt lgkmcnt(4)
	v_pk_fma_f32 v[8:9], v[22:23], v[198:199], v[4:5] op_sel:[0,1,1] op_sel_hi:[1,1,0] neg_lo:[0,0,1]
	s_waitcnt lgkmcnt(3)
	v_pk_fma_f32 v[16:17], v[24:25], v[192:193], v[38:39] op_sel:[0,1,1] op_sel_hi:[1,1,0] neg_lo:[0,0,1]
	v_pk_fma_f32 v[18:19], v[18:19], v[194:195], v[42:43] op_sel:[0,0,1] op_sel_hi:[1,0,0] neg_hi:[0,0,1]
	v_pk_fma_f32 v[20:21], v[20:21], v[196:197], v[10:11] op_sel:[0,0,1] op_sel_hi:[1,0,0] neg_hi:[0,0,1]
	v_pk_fma_f32 v[22:23], v[22:23], v[198:199], v[8:9] op_sel:[0,0,1] op_sel_hi:[1,0,0] neg_hi:[0,0,1]
	v_pk_fma_f32 v[24:25], v[24:25], v[192:193], v[16:17] op_sel:[0,0,1] op_sel_hi:[1,0,0] neg_hi:[0,0,1]
	v_pk_fma_f32 v[14:15], v[14:15], s[100:101], v[44:45] op_sel_hi:[1,0,1] neg_lo:[0,0,1] neg_hi:[0,0,1]
	s_waitcnt lgkmcnt(2)
	v_pk_fma_f32 v[16:17], v[26:27], v[188:189], v[0:1] op_sel:[0,1,1] op_sel_hi:[1,1,0] neg_lo:[0,0,1]
	s_waitcnt lgkmcnt(1)
	v_pk_fma_f32 v[8:9], v[28:29], v[190:191], v[40:41] op_sel:[0,1,1] op_sel_hi:[1,1,0] neg_lo:[0,0,1]
	s_waitcnt lgkmcnt(0)
	v_pk_fma_f32 v[10:11], v[30:31], v[186:187], v[12:13] op_sel:[0,1,1] op_sel_hi:[1,1,0] neg_lo:[0,0,1]
	v_pk_fma_f32 v[32:33], v[32:33], s[100:101], v[18:19] op_sel_hi:[1,0,1] neg_lo:[0,0,1] neg_hi:[0,0,1]
	v_pk_fma_f32 v[16:17], v[26:27], v[188:189], v[16:17] op_sel:[0,0,1] op_sel_hi:[1,0,0] neg_hi:[0,0,1]
	v_pk_fma_f32 v[28:29], v[28:29], v[190:191], v[8:9] op_sel:[0,0,1] op_sel_hi:[1,0,0] neg_hi:[0,0,1]
	v_pk_fma_f32 v[10:11], v[30:31], v[186:187], v[10:11] op_sel:[0,0,1] op_sel_hi:[1,0,0] neg_hi:[0,0,1]
	v_pk_add_f32 v[30:31], v[44:45], v[18:19]
	v_pk_fma_f32 v[2:3], v[2:3], s[100:101], v[20:21] op_sel_hi:[1,0,1] neg_lo:[0,0,1] neg_hi:[0,0,1]
	v_pk_fma_f32 v[4:5], v[4:5], s[100:101], v[22:23] op_sel_hi:[1,0,1] neg_lo:[0,0,1] neg_hi:[0,0,1]
	v_pk_fma_f32 v[38:39], v[38:39], s[100:101], v[24:25] op_sel_hi:[1,0,1] neg_lo:[0,0,1] neg_hi:[0,0,1]
	v_pk_add_f32 v[18:19], v[44:45], v[18:19] neg_lo:[0,1] neg_hi:[0,1]
	v_pk_fma_f32 v[0:1], v[0:1], s[100:101], v[16:17] op_sel_hi:[1,0,1] neg_lo:[0,0,1] neg_hi:[0,0,1]
	v_pk_fma_f32 v[40:41], v[40:41], s[100:101], v[28:29] op_sel_hi:[1,0,1] neg_lo:[0,0,1] neg_hi:[0,0,1]
	v_pk_fma_f32 v[12:13], v[12:13], s[100:101], v[10:11] op_sel_hi:[1,0,1] neg_lo:[0,0,1] neg_hi:[0,0,1]
	v_pk_add_f32 v[44:45], v[14:15], v[32:33] op_sel:[0,1] op_sel_hi:[1,0] neg_lo:[0,1]
	v_pk_add_f32 v[8:9], v[20:21], v[16:17]
	v_pk_add_f32 v[26:27], v[22:23], v[28:29]
	v_pk_add_f32 v[42:43], v[24:25], v[10:11]
	v_pk_add_f32 v[32:33], v[14:15], v[32:33] op_sel:[0,1] op_sel_hi:[1,0] neg_hi:[0,1]
	v_pk_add_f32 v[16:17], v[20:21], v[16:17] neg_lo:[0,1] neg_hi:[0,1]
	v_pk_add_f32 v[28:29], v[22:23], v[28:29] neg_lo:[0,1] neg_hi:[0,1]
	v_pk_add_f32 v[24:25], v[24:25], v[10:11] neg_lo:[0,1] neg_hi:[0,1]
	v_pk_add_f32 v[10:11], v[2:3], v[0:1] op_sel:[0,1] op_sel_hi:[1,0] neg_lo:[0,1]
	v_pk_add_f32 v[22:23], v[4:5], v[40:41] op_sel:[0,1] op_sel_hi:[1,0] neg_lo:[0,1]
	v_pk_add_f32 v[20:21], v[38:39], v[12:13] op_sel:[0,1] op_sel_hi:[1,0] neg_lo:[0,1]
; #define LAS __attribute__((address_space(3)))
; template <bool INV> __device__ __forceinline__ void dft16(f32x2 (&x)[16]) {
; #pragma unroll
;     for (int b = 0; b < 4; ++b) r4<INV>(x[b], x[4 + b], x[8 + b], x[12 + b]);
;     const float sg = INV ? -1.f : 1.f;
;     const f32x2 W1 = {0.92387953251f, -0.38268343236f * sg}, W2 = {0.70710678118f, -0.70710678118f * sg}, W3 = {0.38268343236f, -0.92387953251f * sg},
;                 W4 = {0.f, -1.f * sg}, W6 = {-0.70710678118f, -0.70710678118f * sg}, W9 = {-0.92387953251f, 0.38268343236f * sg};
;     x[5] = cmul(x[5], W1); x[9] = cmul(x[9], W2); x[13] = cmul(x[13], W3);
;     x[6] = cmul(x[6], W2); x[10] = cmul(x[10], W4); x[14] = cmul(x[14], W6);
;     x[7] = cmul(x[7], W3); x[11] = cmul(x[11], W6); x[15] = cmul(x[15], W9);
; #pragma unroll
;     for (int c = 0; c < 4; ++c) r4<INV>(x[4 * c], x[4 * c + 1], x[4 * c + 2], x[4 * c + 3]);
; }
; template <bool INV> __device__ __forceinline__ void bfly16(f32x2 (&x)[16], const LAS f32x2* TH, const LAS f32x2* TL, int tw) {
;     f32x2 W = tw32k(TH, TL, tw); if (INV) W.y = -W.y;
;     if (INV) { f32x2 p = W;
; #pragma unroll
;         for (int q = 1; q < 16; ++q) { x[q] = cmul(x[q], p); if (q < 15) p = cmul(p, W); } }
;     dft16<INV>(x);
;     if (!INV) { f32x2 p = W;
; #pragma unroll
;         for (int r = 1; r < 16; ++r) { x[4 * (r & 3) + (r >> 2)] = cmul(x[4 * (r & 3) + (r >> 2)], p); if (r < 15) p = cmul(p, W); } }
; }
; template <bool INV> __device__ __forceinline__ void bfly16_tab(f32x2 (&x)[16], const LAS f32x2* T, int tstride, int j) {
;     if (INV) {
; #pragma unroll
;         for (int q = 1; q < 16; ++q) { f32x2 p = T[q * tstride + j]; p.y = -p.y; x[q] = cmul(x[q], p); } }
;     dft16<INV>(x);
;     if (!INV) {
; #pragma unroll
;         for (int r = 1; r < 16; ++r) { const f32x2 p = T[r * tstride + j]; x[4 * (r & 3) + (r >> 2)] = cmul(x[4 * (r & 3) + (r >> 2)], p); } }
; }
; template <bool INV> __device__ __forceinline__ void pass16_s64(LAS f32x2* X, const LAS f32x2* TH, int base, int j) {
;     f32x2 x[16];
; #pragma unroll
;     for (int q = 0; q < 16; ++q) x[q] = X[base + q * 68];
;     bfly16_tab<INV>(x, TH - 2048, 64, j);
; #pragma unroll
;     for (int c = 0; c < 4; ++c)
; #pragma unroll
;         for (int d = 0; d < 4; ++d) X[base + (c + 4 * d) * 68] = x[4 * c + d];
; }
	v_pk_add_f32 v[0:1], v[2:3], v[0:1] op_sel:[0,1] op_sel_hi:[1,0] neg_hi:[0,1]
	v_pk_add_f32 v[4:5], v[4:5], v[40:41] op_sel:[0,1] op_sel_hi:[1,0] neg_hi:[0,1]
	v_pk_add_f32 v[38:39], v[38:39], v[12:13] op_sel:[0,1] op_sel_hi:[1,0] neg_hi:[0,1]
	v_pk_add_f32 v[12:13], v[30:31], v[26:27]
	v_pk_mul_f32 v[40:41], v[10:11], s[82:83] op_sel_hi:[1,0]
	v_pk_mul_f32 v[2:3], v[16:17], s[76:77] op_sel_hi:[1,0]
	v_pk_mul_f32 v[14:15], v[0:1], s[44:45] op_sel_hi:[1,0]
	v_pk_add_f32 v[30:31], v[30:31], v[26:27] neg_lo:[0,1] neg_hi:[0,1]
	v_pk_fma_f32 v[40:41], v[10:11], s[44:45], v[40:41] op_sel:[0,0,1] op_sel_hi:[1,0,0] neg_lo:[0,0,1]
	v_pk_fma_f32 v[2:3], v[16:17], s[76:77], v[2:3] op_sel:[0,0,1] op_sel_hi:[1,0,0] neg_lo:[0,0,1]
	v_pk_fma_f32 v[0:1], v[0:1], s[82:83], v[14:15] op_sel:[0,0,1] op_sel_hi:[1,0,0] neg_lo:[0,0,1]
	v_pk_add_f32 v[14:15], v[8:9], v[42:43]
	v_pk_fma_f32 v[16:17], v[22:23], s[76:77], v[44:45] op_sel:[0,0,1] op_sel_hi:[1,0,0] neg_hi:[0,0,1]
	v_pk_add_f32 v[10:11], v[18:19], v[28:29] op_sel:[0,1] op_sel_hi:[1,0] neg_lo:[0,1]
	v_pk_fma_f32 v[26:27], v[4:5], s[76:77], v[32:33] op_sel:[0,0,1] op_sel_hi:[1,0,0] neg_hi:[0,0,1]
	v_pk_add_f32 v[8:9], v[8:9], v[42:43] neg_lo:[0,1] neg_hi:[0,1]
	v_pk_fma_f32 v[22:23], v[22:23], s[76:77], v[16:17] op_sel:[0,0,1] op_sel_hi:[1,0,0] neg_lo:[0,0,1]
	v_pk_add_f32 v[18:19], v[18:19], v[28:29] op_sel:[0,1] op_sel_hi:[1,0] neg_hi:[0,1]
	v_pk_fma_f32 v[4:5], v[4:5], s[72:73], v[26:27] op_sel:[0,0,1] op_sel_hi:[1,0,0] neg_lo:[0,0,1]
	v_pk_add_f32 v[26:27], v[12:13], v[14:15]
	v_pk_fma_f32 v[44:45], v[44:45], s[100:101], v[22:23] op_sel_hi:[1,0,1] neg_lo:[0,0,1] neg_hi:[0,0,1]
	v_pk_fma_f32 v[28:29], v[24:25], s[76:77], v[2:3] op_sel:[0,0,1] op_sel_hi:[1,0,0] neg_hi:[0,0,1]
	v_pk_fma_f32 v[32:33], v[32:33], s[100:101], v[4:5] op_sel_hi:[1,0,1] neg_lo:[0,0,1] neg_hi:[0,0,1]
	v_pk_add_f32 v[14:15], v[12:13], v[14:15] neg_lo:[0,1] neg_hi:[0,1]
	v_pk_fma_f32 v[12:13], v[20:21], s[44:45], v[40:41] op_sel:[0,0,1] op_sel_hi:[1,0,0] neg_hi:[0,0,1]
	v_pk_fma_f32 v[28:29], v[24:25], s[72:73], v[28:29] op_sel:[0,0,1] op_sel_hi:[1,0,0] neg_lo:[0,0,1]
	v_pk_fma_f32 v[24:25], v[38:39], s[70:71], v[0:1] op_sel:[0,0,1] op_sel_hi:[1,0,0] neg_hi:[0,0,1]
	v_pk_add_f32 v[16:17], v[30:31], v[8:9] op_sel:[0,1] op_sel_hi:[1,0] neg_lo:[0,1]
	v_pk_fma_f32 v[20:21], v[20:21], s[82:83], v[12:13] op_sel:[0,0,1] op_sel_hi:[1,0,0] neg_lo:[0,0,1]
	v_pk_fma_f32 v[2:3], v[2:3], s[100:101], v[28:29] op_sel_hi:[1,0,1] neg_lo:[0,0,1] neg_hi:[0,0,1]
	v_pk_fma_f32 v[38:39], v[38:39], s[64:65], v[24:25] op_sel:[0,0,1] op_sel_hi:[1,0,0] neg_lo:[0,0,1]
	v_pk_add_f32 v[8:9], v[30:31], v[8:9] op_sel:[0,1] op_sel_hi:[1,0] neg_hi:[0,1]
	v_pk_fma_f32 v[40:41], v[40:41], s[100:101], v[20:21] op_sel_hi:[1,0,1] neg_lo:[0,0,1] neg_hi:[0,0,1]
	v_pk_add_f32 v[30:31], v[10:11], v[28:29]
	v_pk_fma_f32 v[0:1], v[0:1], s[100:101], v[38:39] op_sel_hi:[1,0,1] neg_lo:[0,0,1] neg_hi:[0,0,1]
	v_pk_add_f32 v[24:25], v[22:23], v[20:21]
	v_pk_add_f32 v[28:29], v[10:11], v[28:29] neg_lo:[0,1] neg_hi:[0,1]
	v_pk_add_f32 v[10:11], v[4:5], v[38:39]
	v_pk_add_f32 v[20:21], v[22:23], v[20:21] neg_lo:[0,1] neg_hi:[0,1]
	v_pk_add_f32 v[22:23], v[18:19], v[2:3] op_sel:[0,1] op_sel_hi:[1,0] neg_lo:[0,1]
	v_pk_add_f32 v[38:39], v[4:5], v[38:39] neg_lo:[0,1] neg_hi:[0,1]
	v_pk_add_f32 v[4:5], v[44:45], v[40:41] op_sel:[0,1] op_sel_hi:[1,0] neg_lo:[0,1]
	v_pk_add_f32 v[2:3], v[18:19], v[2:3] op_sel:[0,1] op_sel_hi:[1,0] neg_hi:[0,1]
	v_pk_add_f32 v[18:19], v[32:33], v[0:1] op_sel:[0,1] op_sel_hi:[1,0] neg_lo:[0,1]
	v_pk_add_f32 v[44:45], v[44:45], v[40:41] op_sel:[0,1] op_sel_hi:[1,0] neg_hi:[0,1]
	v_pk_add_f32 v[32:33], v[32:33], v[0:1] op_sel:[0,1] op_sel_hi:[1,0] neg_hi:[0,1]
	ds_write_b64 v151, v[26:27] offset:0
	ds_write_b64 v151, v[24:25] offset:544
	ds_write_b64 v151, v[30:31] offset:1088
	ds_write_b64 v151, v[10:11] offset:1632
	ds_write_b64 v151, v[16:17] offset:2176
	ds_write_b64 v151, v[4:5] offset:2720
	ds_write_b64 v151, v[22:23] offset:3264
	ds_write_b64 v151, v[18:19] offset:3808
	ds_write_b64 v151, v[14:15] offset:4352
	ds_write_b64 v151, v[20:21] offset:4896
	ds_write_b64 v151, v[28:29] offset:5440
	ds_write_b64 v151, v[38:39] offset:5984
	ds_write_b64 v151, v[8:9] offset:6528
	ds_write_b64 v151, v[44:45] offset:7072
	ds_write_b64 v151, v[2:3] offset:7616
	ds_write_b64 v151, v[32:33] offset:8160
	s_cbranch_scc1 .LBB0_854
	s_waitcnt lgkmcnt(0)
	s_barrier
	s_mov_b32 s0, 0
	s_mov_b64 s[12:13], -1
; #define LAS __attribute__((address_space(3)))
; __device__ __forceinline__ f32x2 cmul(f32x2 a, f32x2 b) { return (f32x2){a.x * b.x - a.y * b.y, a.x * b.y + a.y * b.x}; }
; __device__ __forceinline__ f32x2 tw32k(const LAS f32x2* TH, const LAS f32x2* TL, int n) { return cmul(TH[n >> 7], TL[n & 127]); }
; template <bool INV> __device__ __forceinline__ void bfly16(f32x2 (&x)[16], const LAS f32x2* TH, const LAS f32x2* TL, int tw) {
;     f32x2 W = tw32k(TH, TL, tw); if (INV) W.y = -W.y;
;     if (INV) { f32x2 p = W;
; #pragma unroll
;         for (int q = 1; q < 16; ++q) { x[q] = cmul(x[q], p); if (q < 15) p = cmul(p, W); } }
;     dft16<INV>(x);
;     if (!INV) { f32x2 p = W;
; #pragma unroll
;         for (int r = 1; r < 16; ++r) { x[4 * (r & 3) + (r >> 2)] = cmul(x[4 * (r & 3) + (r >> 2)], p); if (r < 15) p = cmul(p, W); } }
; }
; template <bool INV> __device__ __forceinline__ void bfly16_tab(f32x2 (&x)[16], const LAS f32x2* T, int tstride, int j) {
;     if (INV) {
; #pragma unroll
;         for (int q = 1; q < 16; ++q) { f32x2 p = T[q * tstride + j]; p.y = -p.y; x[q] = cmul(x[q], p); } }
;     dft16<INV>(x);
;     if (!INV) {
; #pragma unroll
;         for (int r = 1; r < 16; ++r) { const f32x2 p = T[r * tstride + j]; x[4 * (r & 3) + (r >> 2)] = cmul(x[4 * (r & 3) + (r >> 2)], p); } }
; }
; template <bool INV> __device__ __forceinline__ void pass16_s64(LAS f32x2* X, const LAS f32x2* TH, int base, int j) {
;     f32x2 x[16];
; #pragma unroll
;     for (int q = 0; q < 16; ++q) x[q] = X[base + q * 68];
;     bfly16_tab<INV>(x, TH - 2048, 64, j);
; #pragma unroll
;     for (int c = 0; c < 4; ++c)
; #pragma unroll
;         for (int d = 0; d < 4; ++d) X[base + (c + 4 * d) * 68] = x[4 * c + d];
; }
; template <bool INV> __device__ __forceinline__ void pass16(LAS f32x2* X, const LAS f32x2* TH, const LAS f32x2* TL, int base, int stride, int tw) {
;     f32x2 x[16];
; #pragma unroll
;     for (int q = 0; q < 16; ++q) x[q] = X[base + q * stride];
;     bfly16<INV>(x, TH, TL, tw);
; #pragma unroll
;     for (int c = 0; c < 4; ++c)
; #pragma unroll
;         for (int d = 0; d < 4; ++d) X[base + (c + 4 * d) * stride] = x[4 * c + d];
; }
.LBB0_856:
	v_add_u32_e32 v128, s0, v140
	v_lshrrev_b32_e32 v147, 6, v128
	v_and_b32_e32 v157, 63, v128
	v_lshlrev_b32_e32 v151, 5, v147
	v_lshlrev_b32_e32 v155, 3, v147
	v_lshlrev_b32_e32 v157, 4, v157
	v_lshl_add_u32 v151, v128, 3, v151
	v_add_u32_e32 v155, 0x26000, v155
	v_add_u32_e32 v157, 0x26400, v157
	v_add_u32_e32 v176, 0x11000, v151
	ds_read_b64 v[0:1], v155
	ds_read_b64 v[2:3], v157
	ds_read_b64 v[4:5], v151 offset:34816
	ds_read_b64 v[6:7], v151 offset:8704
	ds_read_b64 v[8:9], v151 offset:17408
	ds_read_b64 v[10:11], v151 offset:26112
	ds_read_b64 v[12:13], v151 offset:43520
	ds_read_b64 v[14:15], v151 offset:52224
	ds_read_b64 v[16:17], v151 offset:60928
	ds_read_b64 v[18:19], v151 offset:0
	ds_read_b64 v[20:21], v176 offset:0
	ds_read_b64 v[22:23], v176 offset:34816
	ds_read_b64 v[24:25], v176 offset:8704
	ds_read_b64 v[26:27], v176 offset:17408
	ds_read_b64 v[28:29], v176 offset:26112
	ds_read_b64 v[30:31], v176 offset:43520
	ds_read_b64 v[32:33], v176 offset:52224
	ds_read_b64 v[34:35], v176 offset:60928
	s_cmp_eq_u32 s0, 0
	s_movk_i32 s0, 0x200
	s_mov_b64 s[12:13], 0
	s_waitcnt lgkmcnt(15)
	v_pk_mul_f32 v[36:37], v[0:1], v[2:3] op_sel:[0,1] op_sel_hi:[1,1]
	s_nop 0
	v_pk_fma_f32 v[2:3], v[0:1], v[2:3], v[36:37] op_sel:[0,0,1] op_sel_hi:[1,0,0] neg_lo:[0,0,1]
	s_nop 0
	v_pk_mul_f32 v[0:1], v[2:3], v[2:3] op_sel:[0,1] op_sel_hi:[1,1]
	s_nop 0
	v_pk_fma_f32 v[0:1], v[2:3], v[2:3], v[0:1] op_sel:[0,0,1] op_sel_hi:[1,0,0] neg_lo:[0,0,1]
	s_nop 0
	v_pk_mul_f32 v[36:37], v[0:1], v[2:3] op_sel:[0,1] op_sel_hi:[1,1]
	v_pk_mul_f32 v[38:39], v[0:1], v[0:1] op_sel:[0,1] op_sel_hi:[1,1]
	v_pk_fma_f32 v[36:37], v[0:1], v[2:3], v[36:37] op_sel:[0,0,1] op_sel_hi:[1,0,0] neg_lo:[0,0,1]
	v_pk_fma_f32 v[38:39], v[0:1], v[0:1], v[38:39] op_sel:[0,0,1] op_sel_hi:[1,0,0] neg_lo:[0,0,1]
	s_nop 0
	v_pk_mul_f32 v[40:41], v[38:39], v[2:3] op_sel:[0,1] op_sel_hi:[1,1]
	v_pk_mul_f32 v[42:43], v[38:39], v[0:1] op_sel:[0,1] op_sel_hi:[1,1]
	v_pk_mul_f32 v[44:45], v[38:39], v[36:37] op_sel:[0,1] op_sel_hi:[1,1]
	v_pk_fma_f32 v[40:41], v[38:39], v[2:3], v[40:41] op_sel:[0,0,1] op_sel_hi:[1,0,0] neg_lo:[0,0,1]
	v_pk_fma_f32 v[42:43], v[38:39], v[0:1], v[42:43] op_sel:[0,0,1] op_sel_hi:[1,0,0] neg_lo:[0,0,1]
	v_pk_fma_f32 v[44:45], v[38:39], v[36:37], v[44:45] op_sel:[0,0,1] op_sel_hi:[1,0,0] neg_lo:[0,0,1]
	v_pk_mul_f32 v[46:47], v[38:39], v[38:39] op_sel:[0,1] op_sel_hi:[1,1]
	s_nop 0
	v_pk_fma_f32 v[46:47], v[38:39], v[38:39], v[46:47] op_sel:[0,0,1] op_sel_hi:[1,0,0] neg_lo:[0,0,1]
	s_nop 0
	v_pk_mul_f32 v[48:49], v[46:47], v[2:3] op_sel:[0,1] op_sel_hi:[1,1]
	v_pk_mul_f32 v[50:51], v[46:47], v[0:1] op_sel:[0,1] op_sel_hi:[1,1]
	v_pk_mul_f32 v[52:53], v[46:47], v[36:37] op_sel:[0,1] op_sel_hi:[1,1]
	v_pk_fma_f32 v[48:49], v[46:47], v[2:3], v[48:49] op_sel:[0,0,1] op_sel_hi:[1,0,0] neg_lo:[0,0,1]
	v_pk_fma_f32 v[50:51], v[46:47], v[0:1], v[50:51] op_sel:[0,0,1] op_sel_hi:[1,0,0] neg_lo:[0,0,1]
	v_pk_fma_f32 v[52:53], v[46:47], v[36:37], v[52:53] op_sel:[0,0,1] op_sel_hi:[1,0,0] neg_lo:[0,0,1]
	v_pk_mul_f32 v[54:55], v[46:47], v[38:39] op_sel:[0,1] op_sel_hi:[1,1]
	v_pk_mul_f32 v[56:57], v[46:47], v[40:41] op_sel:[0,1] op_sel_hi:[1,1]
	v_pk_mul_f32 v[58:59], v[46:47], v[42:43] op_sel:[0,1] op_sel_hi:[1,1]
	v_pk_fma_f32 v[54:55], v[46:47], v[38:39], v[54:55] op_sel:[0,0,1] op_sel_hi:[1,0,0] neg_lo:[0,0,1]
	v_pk_fma_f32 v[56:57], v[46:47], v[40:41], v[56:57] op_sel:[0,0,1] op_sel_hi:[1,0,0] neg_lo:[0,0,1]
	v_pk_fma_f32 v[58:59], v[46:47], v[42:43], v[58:59] op_sel:[0,0,1] op_sel_hi:[1,0,0] neg_lo:[0,0,1]
	v_pk_mul_f32 v[60:61], v[46:47], v[44:45] op_sel:[0,1] op_sel_hi:[1,1]
	s_nop 0
	v_pk_fma_f32 v[60:61], v[46:47], v[44:45], v[60:61] op_sel:[0,0,1] op_sel_hi:[1,0,0] neg_lo:[0,0,1]
	v_pk_mul_f32 v[62:63], v[4:5], v[38:39] op_sel:[0,1] op_sel_hi:[1,1]
	s_waitcnt lgkmcnt(14)
	v_pk_mul_f32 v[64:65], v[6:7], v[2:3] op_sel:[0,1] op_sel_hi:[1,1]
	s_waitcnt lgkmcnt(13)
	v_pk_mul_f32 v[66:67], v[8:9], v[0:1] op_sel:[0,1] op_sel_hi:[1,1]
	s_waitcnt lgkmcnt(12)
	v_pk_mul_f32 v[68:69], v[10:11], v[36:37] op_sel:[0,1] op_sel_hi:[1,1]
	v_pk_fma_f32 v[38:39], v[4:5], v[38:39], v[62:63] op_sel:[0,0,1] op_sel_hi:[1,0,0] neg_hi:[0,0,1]
	s_waitcnt lgkmcnt(11)
	v_pk_mul_f32 v[62:63], v[12:13], v[40:41] op_sel:[0,1] op_sel_hi:[1,1]
	s_waitcnt lgkmcnt(10)
	v_pk_mul_f32 v[4:5], v[14:15], v[42:43] op_sel:[0,1] op_sel_hi:[1,1]
	s_waitcnt lgkmcnt(9)
	v_pk_mul_f32 v[70:71], v[16:17], v[44:45] op_sel:[0,1] op_sel_hi:[1,1]
	s_waitcnt lgkmcnt(7)
	v_pk_fma_f32 v[72:73], v[20:21], v[46:47], v[18:19] op_sel:[0,1,1] op_sel_hi:[1,1,0] neg_lo:[0,0,1]
	v_pk_fma_f32 v[2:3], v[6:7], v[2:3], v[64:65] op_sel:[0,0,1] op_sel_hi:[1,0,0] neg_hi:[0,0,1]
	v_pk_fma_f32 v[8:9], v[8:9], v[0:1], v[66:67] op_sel:[0,0,1] op_sel_hi:[1,0,0] neg_hi:[0,0,1]
	v_pk_fma_f32 v[68:69], v[10:11], v[36:37], v[68:69] op_sel:[0,0,1] op_sel_hi:[1,0,0] neg_hi:[0,0,1]
	v_pk_fma_f32 v[72:73], v[20:21], v[46:47], v[72:73] op_sel:[0,0,1] op_sel_hi:[1,0,0] neg_hi:[0,0,1]
	v_pk_fma_f32 v[12:13], v[12:13], v[40:41], v[62:63] op_sel:[0,0,1] op_sel_hi:[1,0,0] neg_hi:[0,0,1]
	v_pk_fma_f32 v[4:5], v[14:15], v[42:43], v[4:5] op_sel:[0,0,1] op_sel_hi:[1,0,0] neg_hi:[0,0,1]
	v_pk_fma_f32 v[70:71], v[16:17], v[44:45], v[70:71] op_sel:[0,0,1] op_sel_hi:[1,0,0] neg_hi:[0,0,1]
	s_waitcnt lgkmcnt(6)
	v_pk_fma_f32 v[16:17], v[22:23], v[54:55], v[38:39] op_sel:[0,1,1] op_sel_hi:[1,1,0] neg_lo:[0,0,1]
	s_waitcnt lgkmcnt(5)
	v_pk_fma_f32 v[44:45], v[24:25], v[48:49], v[2:3] op_sel:[0,1,1] op_sel_hi:[1,1,0] neg_lo:[0,0,1]
	s_waitcnt lgkmcnt(4)
	v_pk_fma_f32 v[14:15], v[26:27], v[50:51], v[8:9] op_sel:[0,1,1] op_sel_hi:[1,1,0] neg_lo:[0,0,1]
	s_waitcnt lgkmcnt(3)
; #define LAS __attribute__((address_space(3)))
; template <bool INV> __device__ __forceinline__ void dft16(f32x2 (&x)[16]) {
; #pragma unroll
;     for (int b = 0; b < 4; ++b) r4<INV>(x[b], x[4 + b], x[8 + b], x[12 + b]);
;     const float sg = INV ? -1.f : 1.f;
;     const f32x2 W1 = {0.92387953251f, -0.38268343236f * sg}, W2 = {0.70710678118f, -0.70710678118f * sg}, W3 = {0.38268343236f, -0.92387953251f * sg},
;                 W4 = {0.f, -1.f * sg}, W6 = {-0.70710678118f, -0.70710678118f * sg}, W9 = {-0.92387953251f, 0.38268343236f * sg};
;     x[5] = cmul(x[5], W1); x[9] = cmul(x[9], W2); x[13] = cmul(x[13], W3);
;     x[6] = cmul(x[6], W2); x[10] = cmul(x[10], W4); x[14] = cmul(x[14], W6);
;     x[7] = cmul(x[7], W3); x[11] = cmul(x[11], W6); x[15] = cmul(x[15], W9);
; #pragma unroll
;     for (int c = 0; c < 4; ++c) r4<INV>(x[4 * c], x[4 * c + 1], x[4 * c + 2], x[4 * c + 3]);
; }
; template <bool INV> __device__ __forceinline__ void bfly16(f32x2 (&x)[16], const LAS f32x2* TH, const LAS f32x2* TL, int tw) {
;     f32x2 W = tw32k(TH, TL, tw); if (INV) W.y = -W.y;
;     if (INV) { f32x2 p = W;
; #pragma unroll
;         for (int q = 1; q < 16; ++q) { x[q] = cmul(x[q], p); if (q < 15) p = cmul(p, W); } }
;     dft16<INV>(x);
;     if (!INV) { f32x2 p = W;
; #pragma unroll
;         for (int r = 1; r < 16; ++r) { x[4 * (r & 3) + (r >> 2)] = cmul(x[4 * (r & 3) + (r >> 2)], p); if (r < 15) p = cmul(p, W); } }
; }
; template <bool INV> __device__ __forceinline__ void bfly16_tab(f32x2 (&x)[16], const LAS f32x2* T, int tstride, int j) {
;     if (INV) {
; #pragma unroll
;         for (int q = 1; q < 16; ++q) { f32x2 p = T[q * tstride + j]; p.y = -p.y; x[q] = cmul(x[q], p); } }
;     dft16<INV>(x);
;     if (!INV) {
; #pragma unroll
;         for (int r = 1; r < 16; ++r) { const f32x2 p = T[r * tstride + j]; x[4 * (r & 3) + (r >> 2)] = cmul(x[4 * (r & 3) + (r >> 2)], p); } }
; }
; template <bool INV> __device__ __forceinline__ void pass16_s64(LAS f32x2* X, const LAS f32x2* TH, int base, int j) {
;     f32x2 x[16];
; #pragma unroll
;     for (int q = 0; q < 16; ++q) x[q] = X[base + q * 68];
;     bfly16_tab<INV>(x, TH - 2048, 64, j);
; #pragma unroll
;     for (int c = 0; c < 4; ++c)
; #pragma unroll
;         for (int d = 0; d < 4; ++d) X[base + (c + 4 * d) * 68] = x[4 * c + d];
; }
	v_pk_fma_f32 v[42:43], v[28:29], v[52:53], v[68:69] op_sel:[0,1,1] op_sel_hi:[1,1,0] neg_lo:[0,0,1]
	v_pk_fma_f32 v[22:23], v[22:23], v[54:55], v[16:17] op_sel:[0,0,1] op_sel_hi:[1,0,0] neg_hi:[0,0,1]
	v_pk_fma_f32 v[48:49], v[24:25], v[48:49], v[44:45] op_sel:[0,0,1] op_sel_hi:[1,0,0] neg_hi:[0,0,1]
	v_pk_fma_f32 v[50:51], v[26:27], v[50:51], v[14:15] op_sel:[0,0,1] op_sel_hi:[1,0,0] neg_hi:[0,0,1]
	v_pk_fma_f32 v[42:43], v[28:29], v[52:53], v[42:43] op_sel:[0,0,1] op_sel_hi:[1,0,0] neg_hi:[0,0,1]
	v_pk_fma_f32 v[18:19], v[18:19], s[100:101], v[72:73] op_sel_hi:[1,0,1] neg_lo:[0,0,1] neg_hi:[0,0,1]
	s_waitcnt lgkmcnt(2)
	v_pk_fma_f32 v[28:29], v[30:31], v[56:57], v[12:13] op_sel:[0,1,1] op_sel_hi:[1,1,0] neg_lo:[0,0,1]
	s_waitcnt lgkmcnt(1)
	v_pk_fma_f32 v[52:53], v[32:33], v[58:59], v[4:5] op_sel:[0,1,1] op_sel_hi:[1,1,0] neg_lo:[0,0,1]
	s_waitcnt lgkmcnt(0)
	v_pk_fma_f32 v[26:27], v[34:35], v[60:61], v[70:71] op_sel:[0,1,1] op_sel_hi:[1,1,0] neg_lo:[0,0,1]
	v_pk_fma_f32 v[38:39], v[38:39], s[100:101], v[22:23] op_sel_hi:[1,0,1] neg_lo:[0,0,1] neg_hi:[0,0,1]
	v_pk_fma_f32 v[30:31], v[30:31], v[56:57], v[28:29] op_sel:[0,0,1] op_sel_hi:[1,0,0] neg_hi:[0,0,1]
	v_pk_fma_f32 v[58:59], v[32:33], v[58:59], v[52:53] op_sel:[0,0,1] op_sel_hi:[1,0,0] neg_hi:[0,0,1]
	v_pk_fma_f32 v[26:27], v[34:35], v[60:61], v[26:27] op_sel:[0,0,1] op_sel_hi:[1,0,0] neg_hi:[0,0,1]
	v_pk_add_f32 v[60:61], v[72:73], v[22:23]
	v_pk_fma_f32 v[2:3], v[2:3], s[100:101], v[48:49] op_sel_hi:[1,0,1] neg_lo:[0,0,1] neg_hi:[0,0,1]
	v_pk_fma_f32 v[8:9], v[8:9], s[100:101], v[50:51] op_sel_hi:[1,0,1] neg_lo:[0,0,1] neg_hi:[0,0,1]
	v_pk_fma_f32 v[68:69], v[68:69], s[100:101], v[42:43] op_sel_hi:[1,0,1] neg_lo:[0,0,1] neg_hi:[0,0,1]
	v_pk_add_f32 v[72:73], v[72:73], v[22:23] neg_lo:[0,1] neg_hi:[0,1]
	v_pk_fma_f32 v[12:13], v[12:13], s[100:101], v[30:31] op_sel_hi:[1,0,1] neg_lo:[0,0,1] neg_hi:[0,0,1]
	v_pk_fma_f32 v[4:5], v[4:5], s[100:101], v[58:59] op_sel_hi:[1,0,1] neg_lo:[0,0,1] neg_hi:[0,0,1]
	v_pk_fma_f32 v[70:71], v[70:71], s[100:101], v[26:27] op_sel_hi:[1,0,1] neg_lo:[0,0,1] neg_hi:[0,0,1]
	v_pk_add_f32 v[22:23], v[18:19], v[38:39] op_sel:[0,1] op_sel_hi:[1,0] neg_lo:[0,1]
	v_pk_add_f32 v[34:35], v[48:49], v[30:31]
	v_pk_add_f32 v[32:33], v[50:51], v[58:59]
	v_pk_add_f32 v[52:53], v[42:43], v[26:27]
	v_pk_add_f32 v[38:39], v[18:19], v[38:39] op_sel:[0,1] op_sel_hi:[1,0] neg_hi:[0,1]
	v_pk_add_f32 v[30:31], v[48:49], v[30:31] neg_lo:[0,1] neg_hi:[0,1]
	v_pk_add_f32 v[58:59], v[50:51], v[58:59] neg_lo:[0,1] neg_hi:[0,1]
	v_pk_add_f32 v[26:27], v[42:43], v[26:27] neg_lo:[0,1] neg_hi:[0,1]
	v_pk_add_f32 v[42:43], v[2:3], v[12:13] op_sel:[0,1] op_sel_hi:[1,0] neg_lo:[0,1]
	v_pk_add_f32 v[50:51], v[8:9], v[4:5] op_sel:[0,1] op_sel_hi:[1,0] neg_lo:[0,1]
	v_pk_add_f32 v[48:49], v[68:69], v[70:71] op_sel:[0,1] op_sel_hi:[1,0] neg_lo:[0,1]
	v_pk_add_f32 v[12:13], v[2:3], v[12:13] op_sel:[0,1] op_sel_hi:[1,0] neg_hi:[0,1]
	v_pk_add_f32 v[8:9], v[8:9], v[4:5] op_sel:[0,1] op_sel_hi:[1,0] neg_hi:[0,1]
	v_pk_add_f32 v[68:69], v[68:69], v[70:71] op_sel:[0,1] op_sel_hi:[1,0] neg_hi:[0,1]
	v_pk_add_f32 v[70:71], v[60:61], v[32:33]
	v_pk_mul_f32 v[4:5], v[42:43], s[82:83] op_sel_hi:[1,0]
	v_pk_mul_f32 v[2:3], v[30:31], s[76:77] op_sel_hi:[1,0]
	v_pk_mul_f32 v[18:19], v[12:13], s[44:45] op_sel_hi:[1,0]
	v_pk_add_f32 v[60:61], v[60:61], v[32:33] neg_lo:[0,1] neg_hi:[0,1]
	v_pk_fma_f32 v[4:5], v[42:43], s[44:45], v[4:5] op_sel:[0,0,1] op_sel_hi:[1,0,0] neg_lo:[0,0,1]
	v_pk_fma_f32 v[30:31], v[30:31], s[76:77], v[2:3] op_sel:[0,0,1] op_sel_hi:[1,0,0] neg_lo:[0,0,1]
	v_pk_fma_f32 v[18:19], v[12:13], s[82:83], v[18:19] op_sel:[0,0,1] op_sel_hi:[1,0,0] neg_lo:[0,0,1]
	v_pk_add_f32 v[12:13], v[34:35], v[52:53]
	v_pk_fma_f32 v[2:3], v[50:51], s[76:77], v[22:23] op_sel:[0,0,1] op_sel_hi:[1,0,0] neg_hi:[0,0,1]
	v_pk_add_f32 v[42:43], v[72:73], v[58:59] op_sel:[0,1] op_sel_hi:[1,0] neg_lo:[0,1]
	v_pk_fma_f32 v[32:33], v[8:9], s[76:77], v[38:39] op_sel:[0,0,1] op_sel_hi:[1,0,0] neg_hi:[0,0,1]
	v_pk_add_f32 v[34:35], v[34:35], v[52:53] neg_lo:[0,1] neg_hi:[0,1]
	v_pk_fma_f32 v[50:51], v[50:51], s[76:77], v[2:3] op_sel:[0,0,1] op_sel_hi:[1,0,0] neg_lo:[0,0,1]
	v_pk_add_f32 v[72:73], v[72:73], v[58:59] op_sel:[0,1] op_sel_hi:[1,0] neg_hi:[0,1]
	v_pk_fma_f32 v[8:9], v[8:9], s[72:73], v[32:33] op_sel:[0,0,1] op_sel_hi:[1,0,0] neg_lo:[0,0,1]
	v_pk_add_f32 v[32:33], v[70:71], v[12:13]
	v_pk_fma_f32 v[22:23], v[22:23], s[100:101], v[50:51] op_sel_hi:[1,0,1] neg_lo:[0,0,1] neg_hi:[0,0,1]
	v_pk_fma_f32 v[58:59], v[26:27], s[76:77], v[30:31] op_sel:[0,0,1] op_sel_hi:[1,0,0] neg_hi:[0,0,1]
	v_pk_fma_f32 v[38:39], v[38:39], s[100:101], v[8:9] op_sel_hi:[1,0,1] neg_lo:[0,0,1] neg_hi:[0,0,1]
	v_pk_add_f32 v[70:71], v[70:71], v[12:13] neg_lo:[0,1] neg_hi:[0,1]
	v_pk_fma_f32 v[12:13], v[48:49], s[44:45], v[4:5] op_sel:[0,0,1] op_sel_hi:[1,0,0] neg_hi:[0,0,1]
	v_pk_fma_f32 v[26:27], v[26:27], s[72:73], v[58:59] op_sel:[0,0,1] op_sel_hi:[1,0,0] neg_lo:[0,0,1]
	v_pk_fma_f32 v[58:59], v[68:69], s[70:71], v[18:19] op_sel:[0,0,1] op_sel_hi:[1,0,0] neg_hi:[0,0,1]
	v_pk_add_f32 v[2:3], v[60:61], v[34:35] op_sel:[0,1] op_sel_hi:[1,0] neg_lo:[0,1]
	v_pk_fma_f32 v[48:49], v[48:49], s[82:83], v[12:13] op_sel:[0,0,1] op_sel_hi:[1,0,0] neg_lo:[0,0,1]
	v_pk_fma_f32 v[30:31], v[30:31], s[100:101], v[26:27] op_sel_hi:[1,0,1] neg_lo:[0,0,1] neg_hi:[0,0,1]
	v_pk_fma_f32 v[68:69], v[68:69], s[64:65], v[58:59] op_sel:[0,0,1] op_sel_hi:[1,0,0] neg_lo:[0,0,1]
	v_pk_add_f32 v[60:61], v[60:61], v[34:35] op_sel:[0,1] op_sel_hi:[1,0] neg_hi:[0,1]
; #define LAS __attribute__((address_space(3)))
; #define LT() ({ int lt_ = tid; asm volatile("" : "+v"(lt_)); lt_; })
; template <bool INV> __device__ __forceinline__ void pass16(LAS f32x2* X, const LAS f32x2* TH, const LAS f32x2* TL, int base, int stride, int tw) {
;     f32x2 x[16];
; #pragma unroll
;     for (int q = 0; q < 16; ++q) x[q] = X[base + q * stride];
;     bfly16<INV>(x, TH, TL, tw);
; #pragma unroll
;     for (int c = 0; c < 4; ++c)
; #pragma unroll
;         for (int d = 0; d < 4; ++d) X[base + (c + 4 * d) * stride] = x[4 * c + d];
; }
; __device__ __forceinline__ void hyena_latent(Frame& F, int l, int ch, LAS f32x2* X, const LAS f32x2* TH, const LAS f32x2* TL, GAS f32x2* KS, const LAS float* CT  , bool wr = true) {
;     ...
;             if (par == 0) {
; #pragma unroll
;                 for (int i = 0; i < 8; ++i) { const int g = LT() + NTHR * i; const LAS f32x4* XP = (const LAS f32x4*)(X + phys(4 * g)); KE4[2 * g] = XP[0]; KE4[2 * g + 1] = XP[1]; }
;                 __syncthreads();
;             }
	v_pk_fma_f32 v[4:5], v[4:5], s[100:101], v[48:49] op_sel_hi:[1,0,1] neg_lo:[0,0,1] neg_hi:[0,0,1]
	v_pk_add_f32 v[34:35], v[42:43], v[26:27]
	v_pk_fma_f32 v[18:19], v[18:19], s[100:101], v[68:69] op_sel_hi:[1,0,1] neg_lo:[0,0,1] neg_hi:[0,0,1]
	v_pk_add_f32 v[58:59], v[50:51], v[48:49]
	v_pk_add_f32 v[26:27], v[42:43], v[26:27] neg_lo:[0,1] neg_hi:[0,1]
	v_pk_add_f32 v[42:43], v[8:9], v[68:69]
	v_pk_add_f32 v[50:51], v[50:51], v[48:49] neg_lo:[0,1] neg_hi:[0,1]
	v_pk_add_f32 v[48:49], v[72:73], v[30:31] op_sel:[0,1] op_sel_hi:[1,0] neg_lo:[0,1]
	v_pk_add_f32 v[68:69], v[8:9], v[68:69] neg_lo:[0,1] neg_hi:[0,1]
	v_pk_add_f32 v[8:9], v[22:23], v[4:5] op_sel:[0,1] op_sel_hi:[1,0] neg_lo:[0,1]
	v_pk_add_f32 v[30:31], v[72:73], v[30:31] op_sel:[0,1] op_sel_hi:[1,0] neg_hi:[0,1]
	v_pk_add_f32 v[72:73], v[38:39], v[18:19] op_sel:[0,1] op_sel_hi:[1,0] neg_lo:[0,1]
	v_pk_add_f32 v[22:23], v[22:23], v[4:5] op_sel:[0,1] op_sel_hi:[1,0] neg_hi:[0,1]
	v_pk_add_f32 v[38:39], v[38:39], v[18:19] op_sel:[0,1] op_sel_hi:[1,0] neg_hi:[0,1]
	ds_write_b64 v151, v[32:33] offset:0
	ds_write_b64 v151, v[58:59] offset:8704
	ds_write_b64 v151, v[34:35] offset:17408
	ds_write_b64 v151, v[42:43] offset:26112
	ds_write_b64 v151, v[2:3] offset:34816
	ds_write_b64 v151, v[8:9] offset:43520
	ds_write_b64 v151, v[48:49] offset:52224
	ds_write_b64 v151, v[72:73] offset:60928
	ds_write_b64 v176, v[70:71] offset:0
	ds_write_b64 v176, v[50:51] offset:8704
	ds_write_b64 v176, v[26:27] offset:17408
	ds_write_b64 v176, v[68:69] offset:26112
	ds_write_b64 v176, v[60:61] offset:34816
	ds_write_b64 v176, v[22:23] offset:43520
	ds_write_b64 v176, v[30:31] offset:52224
	ds_write_b64 v176, v[38:39] offset:60928
	s_cbranch_scc1 .LBB0_856
	s_waitcnt lgkmcnt(0)
	s_barrier
	s_andn2_b64 vcc, exec, s[34:35]
	s_mov_b64 s[12:13], -1
	s_cbranch_vccnz .LBB0_662
	v_mov_b32_e32 v1, v140
	s_mov_b64 s[12:13], 0
	v_lshlrev_b32_e32 v0, 1, v1
	v_and_b32_e32 v2, 0xffffffe0, v0
	v_lshlrev_b32_e32 v1, 5, v1
	v_add3_u32 v4, 0, v2, v1
	v_ashrrev_i32_e32 v1, 31, v0
	v_lshl_add_u64 v[8:9], v[0:1], 4, s[18:19]
	ds_read_b128 v[0:3], v4
	ds_read_b128 v[4:7], v4 offset:16
	s_waitcnt lgkmcnt(1)
	global_store_dwordx4 v[8:9], v[0:3], off
	s_waitcnt lgkmcnt(0)
	global_store_dwordx4 v[8:9], v[4:7], off offset:16
	v_mov_b32_e32 v0, v140
	s_nop 0
	v_add_u32_e32 v1, 0x200, v0
	v_lshlrev_b32_e32 v0, 1, v1
	v_and_b32_e32 v2, 0xffffffe0, v0
	v_lshlrev_b32_e32 v1, 5, v1
	v_add3_u32 v4, 0, v2, v1
	v_ashrrev_i32_e32 v1, 31, v0
	v_lshl_add_u64 v[8:9], v[0:1], 4, s[18:19]
	ds_read_b128 v[0:3], v4
	ds_read_b128 v[4:7], v4 offset:16
	s_waitcnt lgkmcnt(1)
	global_store_dwordx4 v[8:9], v[0:3], off
	s_waitcnt lgkmcnt(0)
	global_store_dwordx4 v[8:9], v[4:7], off offset:16
	v_mov_b32_e32 v0, v140
	s_nop 0
	v_add_u32_e32 v1, 0x400, v0
	v_lshlrev_b32_e32 v0, 1, v1
	v_and_b32_e32 v2, 0xffffffe0, v0
	v_lshlrev_b32_e32 v1, 5, v1
	v_add3_u32 v4, 0, v2, v1
	v_ashrrev_i32_e32 v1, 31, v0
	v_lshl_add_u64 v[8:9], v[0:1], 4, s[18:19]
	ds_read_b128 v[0:3], v4
	ds_read_b128 v[4:7], v4 offset:16
	s_waitcnt lgkmcnt(1)
	global_store_dwordx4 v[8:9], v[0:3], off
	s_waitcnt lgkmcnt(0)
	global_store_dwordx4 v[8:9], v[4:7], off offset:16
	v_mov_b32_e32 v0, v140
	s_nop 0
	v_add_u32_e32 v1, 0x600, v0
	v_lshlrev_b32_e32 v0, 1, v1
	v_and_b32_e32 v2, 0xffffffe0, v0
	v_lshlrev_b32_e32 v1, 5, v1
	v_add3_u32 v4, 0, v2, v1
	v_ashrrev_i32_e32 v1, 31, v0
	v_lshl_add_u64 v[8:9], v[0:1], 4, s[18:19]
	ds_read_b128 v[0:3], v4
	ds_read_b128 v[4:7], v4 offset:16
	s_waitcnt lgkmcnt(1)
	global_store_dwordx4 v[8:9], v[0:3], off
	s_waitcnt lgkmcnt(0)
	global_store_dwordx4 v[8:9], v[4:7], off offset:16
	v_mov_b32_e32 v0, v140
	s_nop 0
	v_add_u32_e32 v1, 0x800, v0
	v_lshlrev_b32_e32 v0, 1, v1
	v_and_b32_e32 v2, 0xffffffe0, v0
	v_lshlrev_b32_e32 v1, 5, v1
	v_add3_u32 v4, 0, v2, v1
	v_ashrrev_i32_e32 v1, 31, v0
	v_lshl_add_u64 v[8:9], v[0:1], 4, s[18:19]
	ds_read_b128 v[0:3], v4
	ds_read_b128 v[4:7], v4 offset:16
	s_waitcnt lgkmcnt(1)
	global_store_dwordx4 v[8:9], v[0:3], off
	s_waitcnt lgkmcnt(0)
	global_store_dwordx4 v[8:9], v[4:7], off offset:16
	v_mov_b32_e32 v0, v140
	s_nop 0
	v_add_u32_e32 v1, 0xa00, v0
	v_lshlrev_b32_e32 v0, 1, v1
	v_and_b32_e32 v2, 0xffffffe0, v0
	v_lshlrev_b32_e32 v1, 5, v1
	v_add3_u32 v4, 0, v2, v1
	v_ashrrev_i32_e32 v1, 31, v0
	v_lshl_add_u64 v[8:9], v[0:1], 4, s[18:19]
	ds_read_b128 v[0:3], v4
	ds_read_b128 v[4:7], v4 offset:16
	s_waitcnt lgkmcnt(1)
	global_store_dwordx4 v[8:9], v[0:3], off
	s_waitcnt lgkmcnt(0)
	global_store_dwordx4 v[8:9], v[4:7], off offset:16
	v_mov_b32_e32 v0, v140
	s_nop 0
	v_add_u32_e32 v1, 0xc00, v0
	v_lshlrev_b32_e32 v0, 1, v1
	v_and_b32_e32 v2, 0xffffffe0, v0
	v_lshlrev_b32_e32 v1, 5, v1
	v_add3_u32 v4, 0, v2, v1
	v_ashrrev_i32_e32 v1, 31, v0
	v_lshl_add_u64 v[8:9], v[0:1], 4, s[18:19]
	ds_read_b128 v[0:3], v4
	ds_read_b128 v[4:7], v4 offset:16
	s_waitcnt lgkmcnt(1)
	global_store_dwordx4 v[8:9], v[0:3], off
	s_waitcnt lgkmcnt(0)
	global_store_dwordx4 v[8:9], v[4:7], off offset:16
	v_mov_b32_e32 v0, v140
	s_nop 0
	v_add_u32_e32 v1, 0xe00, v0
	v_lshlrev_b32_e32 v0, 1, v1
	v_and_b32_e32 v2, 0xffffffe0, v0
	v_lshlrev_b32_e32 v1, 5, v1
	v_add3_u32 v4, 0, v2, v1
	v_ashrrev_i32_e32 v1, 31, v0
	v_lshl_add_u64 v[8:9], v[0:1], 4, s[18:19]
	ds_read_b128 v[0:3], v4
	ds_read_b128 v[4:7], v4 offset:16
	s_waitcnt lgkmcnt(1)
	global_store_dwordx4 v[8:9], v[0:3], off
	s_waitcnt lgkmcnt(0)
	global_store_dwordx4 v[8:9], v[4:7], off offset:16
	s_nop 0
	s_branch .LBB0_662

; #define LAS __attribute__((address_space(3)))
; template <bool INV> __device__ __forceinline__ void dft16(f32x2 (&x)[16]) {
; #pragma unroll
;     for (int b = 0; b < 4; ++b) r4<INV>(x[b], x[4 + b], x[8 + b], x[12 + b]);
;     const float sg = INV ? -1.f : 1.f;
;     const f32x2 W1 = {0.92387953251f, -0.38268343236f * sg}, W2 = {0.70710678118f, -0.70710678118f * sg}, W3 = {0.38268343236f, -0.92387953251f * sg},
;                 W4 = {0.f, -1.f * sg}, W6 = {-0.70710678118f, -0.70710678118f * sg}, W9 = {-0.92387953251f, 0.38268343236f * sg};
;     x[5] = cmul(x[5], W1); x[9] = cmul(x[9], W2); x[13] = cmul(x[13], W3);
;     x[6] = cmul(x[6], W2); x[10] = cmul(x[10], W4); x[14] = cmul(x[14], W6);
;     x[7] = cmul(x[7], W3); x[11] = cmul(x[11], W6); x[15] = cmul(x[15], W9);
; #pragma unroll
;     for (int c = 0; c < 4; ++c) r4<INV>(x[4 * c], x[4 * c + 1], x[4 * c + 2], x[4 * c + 3]);
; }
; template <bool INV> __device__ __forceinline__ void bfly16(f32x2 (&x)[16], const LAS f32x2* TH, const LAS f32x2* TL, int tw) {
;     f32x2 W = tw32k(TH, TL, tw); if (INV) W.y = -W.y;
;     if (INV) { f32x2 p = W;
; #pragma unroll
;         for (int q = 1; q < 16; ++q) { x[q] = cmul(x[q], p); if (q < 15) p = cmul(p, W); } }
;     dft16<INV>(x);
;     if (!INV) { f32x2 p = W;
; #pragma unroll
;         for (int r = 1; r < 16; ++r) { x[4 * (r & 3) + (r >> 2)] = cmul(x[4 * (r & 3) + (r >> 2)], p); if (r < 15) p = cmul(p, W); } }
; }
; template <bool INV> __device__ __forceinline__ void bfly16_tab(f32x2 (&x)[16], const LAS f32x2* T, int tstride, int j) {
;     if (INV) {
; #pragma unroll
;         for (int q = 1; q < 16; ++q) { f32x2 p = T[q * tstride + j]; p.y = -p.y; x[q] = cmul(x[q], p); } }
;     dft16<INV>(x);
;     if (!INV) {
; #pragma unroll
;         for (int r = 1; r < 16; ++r) { const f32x2 p = T[r * tstride + j]; x[4 * (r & 3) + (r >> 2)] = cmul(x[4 * (r & 3) + (r >> 2)], p); } }
; }
; template <bool INV> __device__ __forceinline__ void pass16_s64(LAS f32x2* X, const LAS f32x2* TH, int base, int j) {
;     f32x2 x[16];
; #pragma unroll
;     for (int q = 0; q < 16; ++q) x[q] = X[base + q * 68];
;     bfly16_tab<INV>(x, TH - 2048, 64, j);
; #pragma unroll
;     for (int c = 0; c < 4; ++c)
; #pragma unroll
;         for (int d = 0; d < 4; ++d) X[base + (c + 4 * d) * 68] = x[4 * c + d];
; }
.LBB0_946:
	v_add_u32_e32 v37, s0, v140
	v_lshrrev_b32_e32 v138, 6, v37
	v_mad_u32_u24 v176, v138, s77, v142
	ds_read_b64 v[0:1], v176 offset:0
	ds_read_b64 v[2:3], v176 offset:4352
	ds_read_b64 v[4:5], v176 offset:544
	ds_read_b64 v[6:7], v176 offset:4896
	ds_read_b64 v[8:9], v176 offset:1088
	ds_read_b64 v[10:11], v176 offset:5440
	ds_read_b64 v[12:13], v176 offset:1632
	ds_read_b64 v[14:15], v176 offset:5984
	ds_read_b64 v[16:17], v176 offset:2176
	ds_read_b64 v[18:19], v176 offset:6528
	ds_read_b64 v[20:21], v176 offset:2720
	ds_read_b64 v[22:23], v176 offset:7072
	ds_read_b64 v[24:25], v176 offset:3264
	ds_read_b64 v[26:27], v176 offset:7616
	ds_read_b64 v[28:29], v176 offset:3808
	ds_read_b64 v[30:31], v176 offset:8160
	s_cmp_eq_u32 s0, 0
	s_movk_i32 s0, 0x200
	s_mov_b64 s[8:9], 0
	s_waitcnt lgkmcnt(14)
	v_pk_add_f32 v[32:33], v[0:1], v[2:3]
	s_waitcnt lgkmcnt(12)
	v_pk_add_f32 v[34:35], v[4:5], v[6:7]
	s_waitcnt lgkmcnt(10)
	v_pk_add_f32 v[38:39], v[8:9], v[10:11]
	s_waitcnt lgkmcnt(8)
	v_pk_add_f32 v[40:41], v[12:13], v[14:15]
	v_pk_add_f32 v[0:1], v[0:1], v[2:3] neg_lo:[0,1] neg_hi:[0,1]
	v_pk_add_f32 v[6:7], v[4:5], v[6:7] neg_lo:[0,1] neg_hi:[0,1]
	v_pk_add_f32 v[8:9], v[8:9], v[10:11] neg_lo:[0,1] neg_hi:[0,1]
	v_pk_add_f32 v[14:15], v[12:13], v[14:15] neg_lo:[0,1] neg_hi:[0,1]
	s_waitcnt lgkmcnt(6)
	v_pk_add_f32 v[12:13], v[16:17], v[18:19]
	s_waitcnt lgkmcnt(4)
	v_pk_add_f32 v[10:11], v[20:21], v[22:23]
	s_waitcnt lgkmcnt(2)
	v_pk_add_f32 v[4:5], v[24:25], v[26:27]
	s_waitcnt lgkmcnt(0)
	v_pk_add_f32 v[2:3], v[28:29], v[30:31]
	v_pk_add_f32 v[18:19], v[16:17], v[18:19] neg_lo:[0,1] neg_hi:[0,1]
	v_pk_add_f32 v[22:23], v[20:21], v[22:23] neg_lo:[0,1] neg_hi:[0,1]
	v_pk_add_f32 v[24:25], v[24:25], v[26:27] neg_lo:[0,1] neg_hi:[0,1]
	v_pk_add_f32 v[28:29], v[28:29], v[30:31] neg_lo:[0,1] neg_hi:[0,1]
	v_pk_add_f32 v[30:31], v[32:33], v[12:13]
	v_pk_add_f32 v[26:27], v[34:35], v[10:11]
	v_pk_add_f32 v[20:21], v[38:39], v[4:5]
	v_pk_add_f32 v[16:17], v[40:41], v[2:3]
	v_pk_add_f32 v[32:33], v[32:33], v[12:13] neg_lo:[0,1] neg_hi:[0,1]
	v_pk_add_f32 v[10:11], v[34:35], v[10:11] neg_lo:[0,1] neg_hi:[0,1]
	v_pk_add_f32 v[38:39], v[38:39], v[4:5] neg_lo:[0,1] neg_hi:[0,1]
	v_pk_add_f32 v[40:41], v[40:41], v[2:3] neg_lo:[0,1] neg_hi:[0,1]
	v_pk_add_f32 v[2:3], v[0:1], v[18:19] op_sel:[0,1] op_sel_hi:[1,0] neg_hi:[0,1]
	v_pk_add_f32 v[4:5], v[6:7], v[22:23] op_sel:[0,1] op_sel_hi:[1,0] neg_hi:[0,1]
	v_pk_add_f32 v[34:35], v[8:9], v[24:25] op_sel:[0,1] op_sel_hi:[1,0] neg_hi:[0,1]
	v_pk_add_f32 v[12:13], v[14:15], v[28:29] op_sel:[0,1] op_sel_hi:[1,0] neg_hi:[0,1]
	v_pk_add_f32 v[0:1], v[0:1], v[18:19] op_sel:[0,1] op_sel_hi:[1,0] neg_lo:[0,1]
	v_pk_add_f32 v[22:23], v[6:7], v[22:23] op_sel:[0,1] op_sel_hi:[1,0] neg_lo:[0,1]
	v_pk_add_f32 v[24:25], v[8:9], v[24:25] op_sel:[0,1] op_sel_hi:[1,0] neg_lo:[0,1]
	v_pk_add_f32 v[14:15], v[14:15], v[28:29] op_sel:[0,1] op_sel_hi:[1,0] neg_lo:[0,1]
	v_pk_add_f32 v[28:29], v[30:31], v[20:21]
	v_pk_mul_f32 v[8:9], v[4:5], s[70:71] op_sel_hi:[1,0]
	v_pk_mul_f32 v[6:7], v[10:11], s[72:73] op_sel_hi:[1,0]
	v_pk_mul_f32 v[18:19], v[22:23], s[64:65] op_sel_hi:[1,0]
	v_pk_add_f32 v[30:31], v[30:31], v[20:21] neg_lo:[0,1] neg_hi:[0,1]
	v_pk_fma_f32 v[4:5], v[4:5], s[44:45], v[8:9] op_sel:[0,0,1] op_sel_hi:[1,0,0] neg_lo:[0,0,1]
	v_pk_fma_f32 v[10:11], v[10:11], s[76:77], v[6:7] op_sel:[0,0,1] op_sel_hi:[1,0,0] neg_lo:[0,0,1]
	v_pk_fma_f32 v[18:19], v[22:23], s[82:83], v[18:19] op_sel:[0,0,1] op_sel_hi:[1,0,0] neg_lo:[0,0,1]
	v_pk_add_f32 v[22:23], v[26:27], v[16:17]
	v_pk_fma_f32 v[6:7], v[34:35], s[72:73], v[2:3] op_sel:[0,0,1] op_sel_hi:[1,0,0] neg_hi:[0,0,1]
	v_pk_add_f32 v[8:9], v[32:33], v[38:39] op_sel:[0,1] op_sel_hi:[1,0] neg_hi:[0,1]
	v_pk_fma_f32 v[20:21], v[24:25], s[72:73], v[0:1] op_sel:[0,0,1] op_sel_hi:[1,0,0] neg_hi:[0,0,1]
	v_pk_add_f32 v[26:27], v[26:27], v[16:17] neg_lo:[0,1] neg_hi:[0,1]
	v_pk_fma_f32 v[6:7], v[34:35], s[76:77], v[6:7] op_sel:[0,0,1] op_sel_hi:[1,0,0] neg_lo:[0,0,1]
	v_pk_add_f32 v[32:33], v[32:33], v[38:39] op_sel:[0,1] op_sel_hi:[1,0] neg_lo:[0,1]
	v_pk_fma_f32 v[24:25], v[24:25], s[72:73], v[20:21] op_sel:[0,0,1] op_sel_hi:[1,0,0] neg_lo:[0,0,1]
	v_pk_add_f32 v[20:21], v[28:29], v[22:23]
	v_pk_fma_f32 v[2:3], v[2:3], s[100:101], v[6:7] op_sel_hi:[1,0,1] neg_lo:[0,0,1] neg_hi:[0,0,1]
	v_pk_fma_f32 v[38:39], v[40:41], s[72:73], v[10:11] op_sel:[0,0,1] op_sel_hi:[1,0,0] neg_hi:[0,0,1]
	v_pk_fma_f32 v[0:1], v[0:1], s[100:101], v[24:25] op_sel_hi:[1,0,1] neg_lo:[0,0,1] neg_hi:[0,0,1]
	v_pk_add_f32 v[22:23], v[28:29], v[22:23] neg_lo:[0,1] neg_hi:[0,1]
	v_pk_fma_f32 v[28:29], v[12:13], s[64:65], v[4:5] op_sel:[0,0,1] op_sel_hi:[1,0,0] neg_hi:[0,0,1]
	v_pk_fma_f32 v[40:41], v[40:41], s[72:73], v[38:39] op_sel:[0,0,1] op_sel_hi:[1,0,0] neg_lo:[0,0,1]
	v_pk_fma_f32 v[38:39], v[14:15], s[82:83], v[18:19] op_sel:[0,0,1] op_sel_hi:[1,0,0] neg_hi:[0,0,1]
	v_pk_add_f32 v[34:35], v[30:31], v[26:27] op_sel:[0,1] op_sel_hi:[1,0] neg_hi:[0,1]
	v_pk_fma_f32 v[12:13], v[12:13], s[82:83], v[28:29] op_sel:[0,0,1] op_sel_hi:[1,0,0] neg_lo:[0,0,1]
; #define LAS __attribute__((address_space(3)))
; __device__ __forceinline__ f32x2 cmul(f32x2 a, f32x2 b) { return (f32x2){a.x * b.x - a.y * b.y, a.x * b.y + a.y * b.x}; }
; template <bool INV> __device__ __forceinline__ void bfly16_tab(f32x2 (&x)[16], const LAS f32x2* T, int tstride, int j) {
;     if (INV) {
; #pragma unroll
;         for (int q = 1; q < 16; ++q) { f32x2 p = T[q * tstride + j]; p.y = -p.y; x[q] = cmul(x[q], p); } }
;     dft16<INV>(x);
;     if (!INV) {
; #pragma unroll
;         for (int r = 1; r < 16; ++r) { const f32x2 p = T[r * tstride + j]; x[4 * (r & 3) + (r >> 2)] = cmul(x[4 * (r & 3) + (r >> 2)], p); } }
; }
; template <bool INV> __device__ __forceinline__ void pass16_s64(LAS f32x2* X, const LAS f32x2* TH, int base, int j) {
;     f32x2 x[16];
; #pragma unroll
;     for (int q = 0; q < 16; ++q) x[q] = X[base + q * 68];
;     bfly16_tab<INV>(x, TH - 2048, 64, j);
; #pragma unroll
;     for (int c = 0; c < 4; ++c)
; #pragma unroll
;         for (int d = 0; d < 4; ++d) X[base + (c + 4 * d) * 68] = x[4 * c + d];
; }
; template <bool INV> __device__ __forceinline__ void pass16(LAS f32x2* X, const LAS f32x2* TH, const LAS f32x2* TL, int base, int stride, int tw) {
;     f32x2 x[16];
; #pragma unroll
;     for (int q = 0; q < 16; ++q) x[q] = X[base + q * stride];
;     bfly16<INV>(x, TH, TL, tw);
; #pragma unroll
;     for (int c = 0; c < 4; ++c)
; #pragma unroll
;         for (int d = 0; d < 4; ++d) X[base + (c + 4 * d) * stride] = x[4 * c + d];
; }
; template <bool INV> __device__ __forceinline__ void pass16_s4(LAS f32x2* X, const LAS f32x2* TH, const LAS f32x2* TL, int tid) {
; #pragma unroll 1
;     for (int s = 0; s < 2; ++s) {
;         const int b = tid + NTHR * s, blk = b >> 2, jj = b & 3;
;         LAS f32x2* P = X + blk * 68 + jj;
;         f32x2 x[16];
; #pragma unroll
;         for (int q = 0; q < 16; ++q) x[q] = P[4 * q];
;         bfly16_tab<INV>(x, TH - 1024, 4, jj);
; #pragma unroll
;         for (int c = 0; c < 4; ++c)
; #pragma unroll
;             for (int d = 0; d < 4; ++d) P[4 * (c + 4 * d)] = x[4 * c + d];
;     }
; }
	v_pk_fma_f32 v[10:11], v[10:11], s[100:101], v[40:41] op_sel_hi:[1,0,1] neg_lo:[0,0,1] neg_hi:[0,0,1]
	v_pk_fma_f32 v[38:39], v[14:15], s[64:65], v[38:39] op_sel:[0,0,1] op_sel_hi:[1,0,0] neg_lo:[0,0,1]
	v_pk_add_f32 v[30:31], v[30:31], v[26:27] op_sel:[0,1] op_sel_hi:[1,0] neg_lo:[0,1]
	v_pk_fma_f32 v[4:5], v[4:5], s[100:101], v[12:13] op_sel_hi:[1,0,1] neg_lo:[0,0,1] neg_hi:[0,0,1]
	v_pk_add_f32 v[26:27], v[8:9], v[40:41]
	v_pk_fma_f32 v[18:19], v[18:19], s[100:101], v[38:39] op_sel_hi:[1,0,1] neg_lo:[0,0,1] neg_hi:[0,0,1]
	v_pk_add_f32 v[14:15], v[6:7], v[12:13]
	v_pk_add_f32 v[8:9], v[8:9], v[40:41] neg_lo:[0,1] neg_hi:[0,1]
	v_pk_add_f32 v[40:41], v[24:25], v[38:39]
	v_pk_add_f32 v[12:13], v[6:7], v[12:13] neg_lo:[0,1] neg_hi:[0,1]
	v_pk_add_f32 v[6:7], v[32:33], v[10:11] op_sel:[0,1] op_sel_hi:[1,0] neg_hi:[0,1]
	v_pk_add_f32 v[38:39], v[24:25], v[38:39] neg_lo:[0,1] neg_hi:[0,1]
	v_pk_add_f32 v[24:25], v[2:3], v[4:5] op_sel:[0,1] op_sel_hi:[1,0] neg_hi:[0,1]
	v_pk_add_f32 v[10:11], v[32:33], v[10:11] op_sel:[0,1] op_sel_hi:[1,0] neg_lo:[0,1]
	v_pk_add_f32 v[32:33], v[0:1], v[18:19] op_sel:[0,1] op_sel_hi:[1,0] neg_hi:[0,1]
	v_pk_add_f32 v[4:5], v[2:3], v[4:5] op_sel:[0,1] op_sel_hi:[1,0] neg_lo:[0,1]
	v_pk_add_f32 v[18:19], v[0:1], v[18:19] op_sel:[0,1] op_sel_hi:[1,0] neg_lo:[0,1]
	v_pk_mul_f32 v[0:1], v[14:15], v[208:209] op_sel:[0,1] op_sel_hi:[1,1]
	v_pk_mul_f32 v[2:3], v[26:27], v[210:211] op_sel:[0,1] op_sel_hi:[1,1]
	v_pk_fma_f32 v[14:15], v[14:15], v[208:209], v[0:1] op_sel:[0,0,1] op_sel_hi:[1,0,0] neg_lo:[0,0,1]
	v_pk_mul_f32 v[0:1], v[40:41], v[204:205] op_sel:[0,1] op_sel_hi:[1,1]
	v_pk_fma_f32 v[2:3], v[26:27], v[210:211], v[2:3] op_sel:[0,0,1] op_sel_hi:[1,0,0] neg_lo:[0,0,1]
	v_pk_mul_f32 v[26:27], v[34:35], v[206:207] op_sel:[0,1] op_sel_hi:[1,1]
	v_pk_fma_f32 v[40:41], v[40:41], v[204:205], v[0:1] op_sel:[0,0,1] op_sel_hi:[1,0,0] neg_lo:[0,0,1]
	v_pk_mul_f32 v[0:1], v[24:25], v[200:201] op_sel:[0,1] op_sel_hi:[1,1]
	v_pk_fma_f32 v[34:35], v[34:35], v[206:207], v[26:27] op_sel:[0,0,1] op_sel_hi:[1,0,0] neg_lo:[0,0,1]
	v_pk_mul_f32 v[26:27], v[6:7], v[202:203] op_sel:[0,1] op_sel_hi:[1,1]
	v_pk_fma_f32 v[0:1], v[24:25], v[200:201], v[0:1] op_sel:[0,0,1] op_sel_hi:[1,0,0] neg_lo:[0,0,1]
	v_pk_mul_f32 v[24:25], v[32:33], v[196:197] op_sel:[0,1] op_sel_hi:[1,1]
	v_pk_fma_f32 v[6:7], v[6:7], v[202:203], v[26:27] op_sel:[0,0,1] op_sel_hi:[1,0,0] neg_lo:[0,0,1]
	v_pk_mul_f32 v[26:27], v[22:23], v[198:199] op_sel:[0,1] op_sel_hi:[1,1]
	v_pk_fma_f32 v[24:25], v[32:33], v[196:197], v[24:25] op_sel:[0,0,1] op_sel_hi:[1,0,0] neg_lo:[0,0,1]
	v_pk_mul_f32 v[32:33], v[12:13], v[192:193] op_sel:[0,1] op_sel_hi:[1,1]
	v_pk_fma_f32 v[26:27], v[22:23], v[198:199], v[26:27] op_sel:[0,0,1] op_sel_hi:[1,0,0] neg_lo:[0,0,1]
	v_pk_mul_f32 v[22:23], v[8:9], v[194:195] op_sel:[0,1] op_sel_hi:[1,1]
	v_pk_fma_f32 v[12:13], v[12:13], v[192:193], v[32:33] op_sel:[0,0,1] op_sel_hi:[1,0,0] neg_lo:[0,0,1]
	v_pk_mul_f32 v[32:33], v[38:39], v[188:189] op_sel:[0,1] op_sel_hi:[1,1]
	v_pk_fma_f32 v[22:23], v[8:9], v[194:195], v[22:23] op_sel:[0,0,1] op_sel_hi:[1,0,0] neg_lo:[0,0,1]
	v_pk_mul_f32 v[8:9], v[30:31], v[190:191] op_sel:[0,1] op_sel_hi:[1,1]
	v_pk_fma_f32 v[32:33], v[38:39], v[188:189], v[32:33] op_sel:[0,0,1] op_sel_hi:[1,0,0] neg_lo:[0,0,1]
	v_pk_mul_f32 v[38:39], v[4:5], v[184:185] op_sel:[0,1] op_sel_hi:[1,1]
	v_pk_fma_f32 v[8:9], v[30:31], v[190:191], v[8:9] op_sel:[0,0,1] op_sel_hi:[1,0,0] neg_lo:[0,0,1]
	v_pk_mul_f32 v[30:31], v[10:11], v[186:187] op_sel:[0,1] op_sel_hi:[1,1]
	v_pk_fma_f32 v[38:39], v[4:5], v[184:185], v[38:39] op_sel:[0,0,1] op_sel_hi:[1,0,0] neg_lo:[0,0,1]
	v_pk_mul_f32 v[4:5], v[18:19], v[232:233] op_sel:[0,1] op_sel_hi:[1,1]
	v_pk_fma_f32 v[30:31], v[10:11], v[186:187], v[30:31] op_sel:[0,0,1] op_sel_hi:[1,0,0] neg_lo:[0,0,1]
	v_pk_fma_f32 v[18:19], v[18:19], v[232:233], v[4:5] op_sel:[0,0,1] op_sel_hi:[1,0,0] neg_lo:[0,0,1]
	ds_write_b64 v176, v[20:21] offset:0
	ds_write_b64 v176, v[14:15] offset:544
	ds_write_b64 v176, v[2:3] offset:1088
	ds_write_b64 v176, v[40:41] offset:1632
	ds_write_b64 v176, v[34:35] offset:2176
	ds_write_b64 v176, v[0:1] offset:2720
	ds_write_b64 v176, v[6:7] offset:3264
	ds_write_b64 v176, v[24:25] offset:3808
	ds_write_b64 v176, v[26:27] offset:4352
	ds_write_b64 v176, v[12:13] offset:4896
	ds_write_b64 v176, v[22:23] offset:5440
	ds_write_b64 v176, v[32:33] offset:5984
	ds_write_b64 v176, v[8:9] offset:6528
	ds_write_b64 v176, v[38:39] offset:7072
	ds_write_b64 v176, v[30:31] offset:7616
	ds_write_b64 v176, v[18:19] offset:8160
	s_cbranch_scc1 .LBB0_946
	s_waitcnt lgkmcnt(0)
	s_barrier
	s_mov_b32 s0, 0
	s_mov_b64 s[8:9], -1
	ds_read2_b64 v[232:235], v141 offset0:4 offset1:8
	ds_read2_b64 v[208:211], v141 offset0:12 offset1:16
	ds_read2_b64 v[204:207], v141 offset0:20 offset1:24
	ds_read2_b64 v[200:203], v141 offset0:28 offset1:32
	ds_read2_b64 v[196:199], v141 offset0:36 offset1:40
	ds_read2_b64 v[192:195], v141 offset0:44 offset1:48
	ds_read2_b64 v[188:191], v141 offset0:52 offset1:56
	ds_read_b64 v[186:187], v141 offset:480
